# layer-1 XN written to a region the chunk states do not overwrite (d_out tail + unused CTX ws region); duplicate layer-1 norm in P6 removed; P1 layer-1 norm hand-pipelined
# speedup vs baseline: 1.0732x; 1.0103x over previous
.LBB0_234:
	s_mov_b64 s[0:1], s[78:79]
	s_load_dwordx2 s[12:13], s[0:1], 0x100
	s_mov_b64 s[0:1], s[78:79]
	s_load_dwordx2 s[0:1], s[0:1], 0x100
	s_mul_i32 s60, s80, 0x3020000
	s_waitcnt lgkmcnt(0)
	v_writelane_b32 v253, s0, 42
	s_nop 1
	v_writelane_b32 v253, s1, 43
	s_mov_b64 s[0:1], s[78:79]
	s_load_dwordx2 s[14:15], s[0:1], 0x100
	s_mov_b64 s[0:1], s[78:79]
	s_load_dwordx2 s[10:11], s[0:1], 0x98
	s_mov_b64 s[0:1], s[78:79]
	s_load_dwordx2 s[0:1], s[0:1], 0xa0
	s_waitcnt lgkmcnt(0)
	v_writelane_b32 v253, s0, 44
	s_nop 1
	v_writelane_b32 v253, s1, 45
	s_mov_b64 s[0:1], s[78:79]
	s_load_dwordx2 s[6:7], s[0:1], 0xa8
	s_mov_b64 s[0:1], s[78:79]
	s_load_dwordx2 s[8:9], s[0:1], 0xb0
	s_mov_b64 s[0:1], s[78:79]
	s_load_dwordx2 s[0:1], s[0:1], 0xb8
	s_waitcnt lgkmcnt(0)
	v_writelane_b32 v253, s0, 46
	s_nop 1
	v_writelane_b32 v253, s1, 47
	s_mov_b64 s[0:1], -1
	v_readlane_b32 s4, v253, 38
	v_readlane_b32 s5, v253, 39
	s_andn2_b64 vcc, exec, s[4:5]
	s_nop 0
	v_cndmask_b32_e64 v0, 0, 1, s[4:5]
	v_cmp_ne_u32_e64 s[18:19], 1, v0
	s_mul_i32 s4, s80, 0xc6000
	s_nop 0
	v_writelane_b32 v253, s18, 48
	s_nop 1
	v_writelane_b32 v253, s19, 49
	v_writelane_b32 v253, s4, 50
	s_cbranch_vccnz .LBB0_377
	s_mov_b64 s[0:1], s[78:79]
	s_mov_b64 s[18:19], s[78:79]
	s_mov_b64 s[20:21], s[78:79]
	s_mov_b64 s[4:5], s[78:79]
	v_mov_b32_e32 v0, v224
	v_readlane_b32 s44, v253, 18
	v_readfirstlane_b32 s22, v0
	s_ashr_i32 s22, s22, 6
	s_add_i32 s36, s22, s70
	s_cmp_gt_i32 s36, 0x11fff
	v_readlane_b32 s45, v253, 19
	s_mov_b32 s46, 0x3a800000
	s_cbranch_scc1 .LBB0_238
	s_waitcnt lgkmcnt(0)
	s_load_dwordx2 s[0:1], s[78:79], 0x100
	s_load_dwordx2 s[20:21], s[78:79], 0x30
	s_load_dwordx2 s[4:5], s[78:79], 0xf8
	v_readfirstlane_b32 s36, v224
	v_and_b32_e32 v51, 63, v224
	v_lshlrev_b32_e32 v148, 5, v51
	v_lshlrev_b32_e32 v51, 4, v51
	v_add_u32_e32 v149, 0x1000, v51
	v_mov_b32_e32 v50, 0x3a800000
	s_lshr_b32 s36, s36, 6
	s_add_i32 s36, s36, s70
	s_lshr_b32 s35, s36, 6
	s_and_b32 s36, s36, 63
	s_mul_i32 s37, s35, 0x900
	s_lshl_b32 s31, s36, 5
	s_add_i32 s31, s31, s37
	s_addk_i32 s31, 0x100
	s_lshl_b32 s34, s36, 2
	s_add_i32 s34, s34, s37
	s_lshl_b32 s36, s80, 12
	s_mul_i32 s37, s80, 0xc6000
	s_waitcnt lgkmcnt(0)
	s_add_u32 s20, s20, s36
	s_addc_u32 s21, s21, 0
	s_sub_u32 s18, s0, 0xa4c000
	s_subb_u32 s19, s1, 0
	s_add_u32 s22, s0, 0x63c8000
	s_addc_u32 s23, s1, 0
	s_add_u32 s22, s22, s37
	s_addc_u32 s23, s23, 0
	global_load_dwordx4 v[32:35], v148, s[20:21]
	global_load_dwordx4 v[36:39], v148, s[20:21] offset:16
	global_load_dwordx4 v[40:43], v148, s[20:21] offset:2048
	global_load_dwordx4 v[44:47], v148, s[20:21] offset:2064
	s_add_u32 s0, s22, 0xc0000
	s_addc_u32 s1, s23, 0
	s_add_u32 s20, s0, 0x1000
	s_addc_u32 s21, s1, 0
	global_load_dwordx4 v[100:103], v148, s[0:1]
	global_load_dwordx4 v[104:107], v148, s[0:1] offset:16
	global_load_dwordx4 v[108:111], v148, s[0:1] offset:2048
	global_load_dwordx4 v[112:115], v148, s[0:1] offset:2064
	global_load_dwordx4 v[84:87], v148, s[20:21]
	global_load_dwordx4 v[88:91], v148, s[20:21] offset:16
	global_load_dwordx4 v[92:95], v148, s[20:21] offset:2048
	global_load_dwordx4 v[96:99], v148, s[20:21] offset:2064
	s_lshl_b32 s36, s34, 11
	s_add_u32 s24, s4, s36
	s_addc_u32 s25, s5, 0
	s_cmp_lt_u32 s36, 0x7000000
	s_cselect_b32 s26, s24, s18
	s_cselect_b32 s27, s25, s19
	s_cselect_b32 s37, 0x9000000, s36
	s_add_u32 s26, s26, s37
	s_addc_u32 s27, s27, 0
	global_load_dwordx4 v[0:3], v51, s[24:25]
	global_load_dwordx4 v[4:7], v51, s[24:25] offset:1024
	global_load_dwordx4 v[8:11], v51, s[24:25] offset:2048
	global_load_dwordx4 v[12:15], v51, s[24:25] offset:3072
	global_load_dwordx4 v[16:19], v149, s[24:25]
	global_load_dwordx4 v[20:23], v149, s[24:25] offset:1024
	global_load_dwordx4 v[24:27], v149, s[24:25] offset:2048
	global_load_dwordx4 v[28:31], v149, s[24:25] offset:3072
	s_waitcnt vmcnt(0)
	v_pk_add_f32 v[84:85], v[84:85], 1.0 op_sel_hi:[1,0]
	v_pk_add_f32 v[86:87], v[86:87], 1.0 op_sel_hi:[1,0]
	v_pk_add_f32 v[88:89], v[88:89], 1.0 op_sel_hi:[1,0]
	v_pk_add_f32 v[90:91], v[90:91], 1.0 op_sel_hi:[1,0]
	v_pk_add_f32 v[92:93], v[92:93], 1.0 op_sel_hi:[1,0]
	v_pk_add_f32 v[94:95], v[94:95], 1.0 op_sel_hi:[1,0]
	v_pk_add_f32 v[96:97], v[96:97], 1.0 op_sel_hi:[1,0]
	v_pk_add_f32 v[98:99], v[98:99], 1.0 op_sel_hi:[1,0]
	v_lshlrev_b32_e32 v116, 16, v0
	v_and_b32_e32 v117, 0xffff0000, v0
	v_lshlrev_b32_e32 v118, 16, v1
	v_and_b32_e32 v119, 0xffff0000, v1
	v_lshlrev_b32_e32 v120, 16, v2
	v_and_b32_e32 v121, 0xffff0000, v2
	v_lshlrev_b32_e32 v122, 16, v3
	v_and_b32_e32 v123, 0xffff0000, v3
	v_lshlrev_b32_e32 v124, 16, v4
	v_and_b32_e32 v125, 0xffff0000, v4
	v_lshlrev_b32_e32 v126, 16, v5
	v_and_b32_e32 v127, 0xffff0000, v5
	v_lshlrev_b32_e32 v128, 16, v6
	v_and_b32_e32 v129, 0xffff0000, v6
	v_lshlrev_b32_e32 v130, 16, v7
	v_and_b32_e32 v131, 0xffff0000, v7
	v_pk_mul_f32 v[132:133], v[116:117], v[116:117]
	v_pk_fma_f32 v[132:133], v[118:119], v[118:119], v[132:133]
	v_pk_fma_f32 v[132:133], v[120:121], v[120:121], v[132:133]
	v_pk_fma_f32 v[132:133], v[122:123], v[122:123], v[132:133]
	v_pk_fma_f32 v[132:133], v[124:125], v[124:125], v[132:133]
	v_pk_fma_f32 v[132:133], v[126:127], v[126:127], v[132:133]
	v_pk_fma_f32 v[132:133], v[128:129], v[128:129], v[132:133]
	v_pk_fma_f32 v[132:133], v[130:131], v[130:131], v[132:133]
	v_lshlrev_b32_e32 v116, 16, v8
	v_and_b32_e32 v117, 0xffff0000, v8
	v_lshlrev_b32_e32 v118, 16, v9
	v_and_b32_e32 v119, 0xffff0000, v9
	v_lshlrev_b32_e32 v120, 16, v10
	v_and_b32_e32 v121, 0xffff0000, v10
	v_lshlrev_b32_e32 v122, 16, v11
	v_and_b32_e32 v123, 0xffff0000, v11
	v_lshlrev_b32_e32 v124, 16, v12
	v_and_b32_e32 v125, 0xffff0000, v12
	v_lshlrev_b32_e32 v126, 16, v13
	v_and_b32_e32 v127, 0xffff0000, v13
	v_lshlrev_b32_e32 v128, 16, v14
	v_and_b32_e32 v129, 0xffff0000, v14
	v_lshlrev_b32_e32 v130, 16, v15
	v_and_b32_e32 v131, 0xffff0000, v15
	v_pk_mul_f32 v[134:135], v[116:117], v[116:117]
	v_pk_fma_f32 v[134:135], v[118:119], v[118:119], v[134:135]
	v_pk_fma_f32 v[134:135], v[120:121], v[120:121], v[134:135]
	v_pk_fma_f32 v[134:135], v[122:123], v[122:123], v[134:135]
	v_pk_fma_f32 v[134:135], v[124:125], v[124:125], v[134:135]
	v_pk_fma_f32 v[134:135], v[126:127], v[126:127], v[134:135]
	v_pk_fma_f32 v[134:135], v[128:129], v[128:129], v[134:135]
	v_pk_fma_f32 v[134:135], v[130:131], v[130:131], v[134:135]
	v_lshlrev_b32_e32 v116, 16, v16
	v_and_b32_e32 v117, 0xffff0000, v16
	v_lshlrev_b32_e32 v118, 16, v17
	v_and_b32_e32 v119, 0xffff0000, v17
	v_lshlrev_b32_e32 v120, 16, v18
	v_and_b32_e32 v121, 0xffff0000, v18
	v_lshlrev_b32_e32 v122, 16, v19
	v_and_b32_e32 v123, 0xffff0000, v19
	v_lshlrev_b32_e32 v124, 16, v20
	v_and_b32_e32 v125, 0xffff0000, v20
	v_lshlrev_b32_e32 v126, 16, v21
	v_and_b32_e32 v127, 0xffff0000, v21
	v_lshlrev_b32_e32 v128, 16, v22
	v_and_b32_e32 v129, 0xffff0000, v22
	v_lshlrev_b32_e32 v130, 16, v23
	v_and_b32_e32 v131, 0xffff0000, v23
	v_pk_mul_f32 v[136:137], v[116:117], v[116:117]
	v_pk_fma_f32 v[136:137], v[118:119], v[118:119], v[136:137]
	v_pk_fma_f32 v[136:137], v[120:121], v[120:121], v[136:137]
	v_pk_fma_f32 v[136:137], v[122:123], v[122:123], v[136:137]
	v_pk_fma_f32 v[136:137], v[124:125], v[124:125], v[136:137]
	v_pk_fma_f32 v[136:137], v[126:127], v[126:127], v[136:137]
	v_pk_fma_f32 v[136:137], v[128:129], v[128:129], v[136:137]
	v_pk_fma_f32 v[136:137], v[130:131], v[130:131], v[136:137]
	v_lshlrev_b32_e32 v116, 16, v24
	v_and_b32_e32 v117, 0xffff0000, v24
	v_lshlrev_b32_e32 v118, 16, v25
	v_and_b32_e32 v119, 0xffff0000, v25
	v_lshlrev_b32_e32 v120, 16, v26
	v_and_b32_e32 v121, 0xffff0000, v26
	v_lshlrev_b32_e32 v122, 16, v27
	v_and_b32_e32 v123, 0xffff0000, v27
	v_lshlrev_b32_e32 v124, 16, v28
	v_and_b32_e32 v125, 0xffff0000, v28
	v_lshlrev_b32_e32 v126, 16, v29
	v_and_b32_e32 v127, 0xffff0000, v29
	v_lshlrev_b32_e32 v128, 16, v30
	v_and_b32_e32 v129, 0xffff0000, v30
	v_lshlrev_b32_e32 v130, 16, v31
	v_and_b32_e32 v131, 0xffff0000, v31
	v_pk_mul_f32 v[138:139], v[116:117], v[116:117]
	v_pk_fma_f32 v[138:139], v[118:119], v[118:119], v[138:139]
	v_pk_fma_f32 v[138:139], v[120:121], v[120:121], v[138:139]
	v_pk_fma_f32 v[138:139], v[122:123], v[122:123], v[138:139]
	v_pk_fma_f32 v[138:139], v[124:125], v[124:125], v[138:139]
	v_pk_fma_f32 v[138:139], v[126:127], v[126:127], v[138:139]
	v_pk_fma_f32 v[138:139], v[128:129], v[128:129], v[138:139]
	v_pk_fma_f32 v[138:139], v[130:131], v[130:131], v[138:139]
	v_add_f32_e32 v132, v132, v133
	v_add_f32_e32 v134, v134, v135
	v_add_f32_e32 v136, v136, v137
	v_add_f32_e32 v138, v138, v139
	s_nop 1
	v_add_f32_dpp v132, v132, v132 row_shr:1 row_mask:0xf bank_mask:0xf bound_ctrl:1
	v_add_f32_dpp v134, v134, v134 row_shr:1 row_mask:0xf bank_mask:0xf bound_ctrl:1
	v_add_f32_dpp v136, v136, v136 row_shr:1 row_mask:0xf bank_mask:0xf bound_ctrl:1
	v_add_f32_dpp v138, v138, v138 row_shr:1 row_mask:0xf bank_mask:0xf bound_ctrl:1
	v_add_f32_dpp v132, v132, v132 row_shr:2 row_mask:0xf bank_mask:0xf bound_ctrl:1
	v_add_f32_dpp v134, v134, v134 row_shr:2 row_mask:0xf bank_mask:0xf bound_ctrl:1
	v_add_f32_dpp v136, v136, v136 row_shr:2 row_mask:0xf bank_mask:0xf bound_ctrl:1
	v_add_f32_dpp v138, v138, v138 row_shr:2 row_mask:0xf bank_mask:0xf bound_ctrl:1
	v_add_f32_dpp v132, v132, v132 row_shr:4 row_mask:0xf bank_mask:0xf bound_ctrl:1
	v_add_f32_dpp v134, v134, v134 row_shr:4 row_mask:0xf bank_mask:0xf bound_ctrl:1
	v_add_f32_dpp v136, v136, v136 row_shr:4 row_mask:0xf bank_mask:0xf bound_ctrl:1
	v_add_f32_dpp v138, v138, v138 row_shr:4 row_mask:0xf bank_mask:0xf bound_ctrl:1
	v_add_f32_dpp v132, v132, v132 row_shr:8 row_mask:0xf bank_mask:0xf bound_ctrl:1
	v_add_f32_dpp v134, v134, v134 row_shr:8 row_mask:0xf bank_mask:0xf bound_ctrl:1
	v_add_f32_dpp v136, v136, v136 row_shr:8 row_mask:0xf bank_mask:0xf bound_ctrl:1
	v_add_f32_dpp v138, v138, v138 row_shr:8 row_mask:0xf bank_mask:0xf bound_ctrl:1
	v_add_f32_dpp v132, v132, v132 row_bcast:15 row_mask:0xa bank_mask:0xf
	v_add_f32_dpp v134, v134, v134 row_bcast:15 row_mask:0xa bank_mask:0xf
	v_add_f32_dpp v136, v136, v136 row_bcast:15 row_mask:0xa bank_mask:0xf
	v_add_f32_dpp v138, v138, v138 row_bcast:15 row_mask:0xa bank_mask:0xf
	v_add_f32_dpp v132, v132, v132 row_bcast:31 row_mask:0xc bank_mask:0xf
	v_add_f32_dpp v134, v134, v134 row_bcast:31 row_mask:0xc bank_mask:0xf
	v_add_f32_dpp v136, v136, v136 row_bcast:31 row_mask:0xc bank_mask:0xf
	v_add_f32_dpp v138, v138, v138 row_bcast:31 row_mask:0xc bank_mask:0xf
	s_nop 1
	v_readlane_b32 s32, v132, 63
	v_readlane_b32 s28, v134, 63
	v_readlane_b32 s29, v136, 63
	v_readlane_b32 s30, v138, 63
	s_nop 1
	v_mov_b32_e32 v140, s32
	v_mov_b32_e32 v142, s28
	v_mov_b32_e32 v144, s29
	v_mov_b32_e32 v146, s30
	v_fmaak_f32 v140, v140, v50, 0x358637bd
	v_fmaak_f32 v142, v142, v50, 0x358637bd
	v_fmaak_f32 v144, v144, v50, 0x358637bd
	v_fmaak_f32 v146, v146, v50, 0x358637bd
	v_rsq_f32_e32 v140, v140
	v_rsq_f32_e32 v142, v142
	v_rsq_f32_e32 v144, v144
	v_rsq_f32_e32 v146, v146
	s_nop 0
	v_lshlrev_b32_e32 v116, 16, v0
	v_and_b32_e32 v117, 0xffff0000, v0
	v_lshlrev_b32_e32 v118, 16, v1
	v_and_b32_e32 v119, 0xffff0000, v1
	v_lshlrev_b32_e32 v120, 16, v2
	v_and_b32_e32 v121, 0xffff0000, v2
	v_lshlrev_b32_e32 v122, 16, v3
	v_and_b32_e32 v123, 0xffff0000, v3
	v_lshlrev_b32_e32 v124, 16, v4
	v_and_b32_e32 v125, 0xffff0000, v4
	v_lshlrev_b32_e32 v126, 16, v5
	v_and_b32_e32 v127, 0xffff0000, v5
	v_lshlrev_b32_e32 v128, 16, v6
	v_and_b32_e32 v129, 0xffff0000, v6
	v_lshlrev_b32_e32 v130, 16, v7
	v_and_b32_e32 v131, 0xffff0000, v7
	v_pk_mul_f32 v[116:117], v[140:141], v[116:117] op_sel_hi:[0,1]
	v_pk_mul_f32 v[118:119], v[140:141], v[118:119] op_sel_hi:[0,1]
	v_pk_mul_f32 v[120:121], v[140:141], v[120:121] op_sel_hi:[0,1]
	v_pk_mul_f32 v[122:123], v[140:141], v[122:123] op_sel_hi:[0,1]
	v_pk_mul_f32 v[124:125], v[140:141], v[124:125] op_sel_hi:[0,1]
	v_pk_mul_f32 v[126:127], v[140:141], v[126:127] op_sel_hi:[0,1]
	v_pk_mul_f32 v[128:129], v[140:141], v[128:129] op_sel_hi:[0,1]
	v_pk_mul_f32 v[130:131], v[140:141], v[130:131] op_sel_hi:[0,1]
	v_pk_mul_f32 v[116:117], v[116:117], v[32:33]
	v_pk_mul_f32 v[118:119], v[118:119], v[34:35]
	v_pk_mul_f32 v[120:121], v[120:121], v[36:37]
	v_pk_mul_f32 v[122:123], v[122:123], v[38:39]
	v_pk_mul_f32 v[124:125], v[124:125], v[40:41]
	v_pk_mul_f32 v[126:127], v[126:127], v[42:43]
	v_pk_mul_f32 v[128:129], v[128:129], v[44:45]
	v_pk_mul_f32 v[130:131], v[130:131], v[46:47]
	v_pk_fma_f32 v[116:117], v[116:117], v[84:85], v[100:101]
	v_pk_fma_f32 v[118:119], v[118:119], v[86:87], v[102:103]
	v_pk_fma_f32 v[120:121], v[120:121], v[88:89], v[104:105]
	v_pk_fma_f32 v[122:123], v[122:123], v[90:91], v[106:107]
	v_pk_fma_f32 v[124:125], v[124:125], v[92:93], v[108:109]
	v_pk_fma_f32 v[126:127], v[126:127], v[94:95], v[110:111]
	v_pk_fma_f32 v[128:129], v[128:129], v[96:97], v[112:113]
	v_pk_fma_f32 v[130:131], v[130:131], v[98:99], v[114:115]
	v_cvt_pk_bf16_f32 v164, v116, v117
	v_cvt_pk_bf16_f32 v165, v118, v119
	v_cvt_pk_bf16_f32 v166, v120, v121
	v_cvt_pk_bf16_f32 v167, v122, v123
	v_cvt_pk_bf16_f32 v168, v124, v125
	v_cvt_pk_bf16_f32 v169, v126, v127
	v_cvt_pk_bf16_f32 v170, v128, v129
	v_cvt_pk_bf16_f32 v171, v130, v131
	global_store_dwordx4 v51, v[164:167], s[26:27]
	global_store_dwordx4 v51, v[168:171], s[26:27] offset:1024
	v_lshlrev_b32_e32 v116, 16, v8
	v_and_b32_e32 v117, 0xffff0000, v8
	v_lshlrev_b32_e32 v118, 16, v9
	v_and_b32_e32 v119, 0xffff0000, v9
	v_lshlrev_b32_e32 v120, 16, v10
	v_and_b32_e32 v121, 0xffff0000, v10
	v_lshlrev_b32_e32 v122, 16, v11
	v_and_b32_e32 v123, 0xffff0000, v11
	v_lshlrev_b32_e32 v124, 16, v12
	v_and_b32_e32 v125, 0xffff0000, v12
	v_lshlrev_b32_e32 v126, 16, v13
	v_and_b32_e32 v127, 0xffff0000, v13
	v_lshlrev_b32_e32 v128, 16, v14
	v_and_b32_e32 v129, 0xffff0000, v14
	v_lshlrev_b32_e32 v130, 16, v15
	v_and_b32_e32 v131, 0xffff0000, v15
	v_pk_mul_f32 v[116:117], v[142:143], v[116:117] op_sel_hi:[0,1]
	v_pk_mul_f32 v[118:119], v[142:143], v[118:119] op_sel_hi:[0,1]
	v_pk_mul_f32 v[120:121], v[142:143], v[120:121] op_sel_hi:[0,1]
	v_pk_mul_f32 v[122:123], v[142:143], v[122:123] op_sel_hi:[0,1]
	v_pk_mul_f32 v[124:125], v[142:143], v[124:125] op_sel_hi:[0,1]
	v_pk_mul_f32 v[126:127], v[142:143], v[126:127] op_sel_hi:[0,1]
	v_pk_mul_f32 v[128:129], v[142:143], v[128:129] op_sel_hi:[0,1]
	v_pk_mul_f32 v[130:131], v[142:143], v[130:131] op_sel_hi:[0,1]
	v_pk_mul_f32 v[116:117], v[116:117], v[32:33]
	v_pk_mul_f32 v[118:119], v[118:119], v[34:35]
	v_pk_mul_f32 v[120:121], v[120:121], v[36:37]
	v_pk_mul_f32 v[122:123], v[122:123], v[38:39]
	v_pk_mul_f32 v[124:125], v[124:125], v[40:41]
	v_pk_mul_f32 v[126:127], v[126:127], v[42:43]
	v_pk_mul_f32 v[128:129], v[128:129], v[44:45]
	v_pk_mul_f32 v[130:131], v[130:131], v[46:47]
	v_pk_fma_f32 v[116:117], v[116:117], v[84:85], v[100:101]
	v_pk_fma_f32 v[118:119], v[118:119], v[86:87], v[102:103]
	v_pk_fma_f32 v[120:121], v[120:121], v[88:89], v[104:105]
	v_pk_fma_f32 v[122:123], v[122:123], v[90:91], v[106:107]
	v_pk_fma_f32 v[124:125], v[124:125], v[92:93], v[108:109]
	v_pk_fma_f32 v[126:127], v[126:127], v[94:95], v[110:111]
	v_pk_fma_f32 v[128:129], v[128:129], v[96:97], v[112:113]
	v_pk_fma_f32 v[130:131], v[130:131], v[98:99], v[114:115]
	v_cvt_pk_bf16_f32 v172, v116, v117
	v_cvt_pk_bf16_f32 v173, v118, v119
	v_cvt_pk_bf16_f32 v174, v120, v121
	v_cvt_pk_bf16_f32 v175, v122, v123
	v_cvt_pk_bf16_f32 v176, v124, v125
	v_cvt_pk_bf16_f32 v177, v126, v127
	v_cvt_pk_bf16_f32 v178, v128, v129
	v_cvt_pk_bf16_f32 v179, v130, v131
	global_store_dwordx4 v51, v[172:175], s[26:27] offset:2048
	global_store_dwordx4 v51, v[176:179], s[26:27] offset:3072
	v_lshlrev_b32_e32 v116, 16, v16
	v_and_b32_e32 v117, 0xffff0000, v16
	v_lshlrev_b32_e32 v118, 16, v17
	v_and_b32_e32 v119, 0xffff0000, v17
	v_lshlrev_b32_e32 v120, 16, v18
	v_and_b32_e32 v121, 0xffff0000, v18
	v_lshlrev_b32_e32 v122, 16, v19
	v_and_b32_e32 v123, 0xffff0000, v19
	v_lshlrev_b32_e32 v124, 16, v20
	v_and_b32_e32 v125, 0xffff0000, v20
	v_lshlrev_b32_e32 v126, 16, v21
	v_and_b32_e32 v127, 0xffff0000, v21
	v_lshlrev_b32_e32 v128, 16, v22
	v_and_b32_e32 v129, 0xffff0000, v22
	v_lshlrev_b32_e32 v130, 16, v23
	v_and_b32_e32 v131, 0xffff0000, v23
	v_pk_mul_f32 v[116:117], v[144:145], v[116:117] op_sel_hi:[0,1]
	v_pk_mul_f32 v[118:119], v[144:145], v[118:119] op_sel_hi:[0,1]
	v_pk_mul_f32 v[120:121], v[144:145], v[120:121] op_sel_hi:[0,1]
	v_pk_mul_f32 v[122:123], v[144:145], v[122:123] op_sel_hi:[0,1]
	v_pk_mul_f32 v[124:125], v[144:145], v[124:125] op_sel_hi:[0,1]
	v_pk_mul_f32 v[126:127], v[144:145], v[126:127] op_sel_hi:[0,1]
	v_pk_mul_f32 v[128:129], v[144:145], v[128:129] op_sel_hi:[0,1]
	v_pk_mul_f32 v[130:131], v[144:145], v[130:131] op_sel_hi:[0,1]
	v_pk_mul_f32 v[116:117], v[116:117], v[32:33]
	v_pk_mul_f32 v[118:119], v[118:119], v[34:35]
	v_pk_mul_f32 v[120:121], v[120:121], v[36:37]
	v_pk_mul_f32 v[122:123], v[122:123], v[38:39]
	v_pk_mul_f32 v[124:125], v[124:125], v[40:41]
	v_pk_mul_f32 v[126:127], v[126:127], v[42:43]
	v_pk_mul_f32 v[128:129], v[128:129], v[44:45]
	v_pk_mul_f32 v[130:131], v[130:131], v[46:47]
	v_pk_fma_f32 v[116:117], v[116:117], v[84:85], v[100:101]
	v_pk_fma_f32 v[118:119], v[118:119], v[86:87], v[102:103]
	v_pk_fma_f32 v[120:121], v[120:121], v[88:89], v[104:105]
	v_pk_fma_f32 v[122:123], v[122:123], v[90:91], v[106:107]
	v_pk_fma_f32 v[124:125], v[124:125], v[92:93], v[108:109]
	v_pk_fma_f32 v[126:127], v[126:127], v[94:95], v[110:111]
	v_pk_fma_f32 v[128:129], v[128:129], v[96:97], v[112:113]
	v_pk_fma_f32 v[130:131], v[130:131], v[98:99], v[114:115]
	v_cvt_pk_bf16_f32 v164, v116, v117
	v_cvt_pk_bf16_f32 v165, v118, v119
	v_cvt_pk_bf16_f32 v166, v120, v121
	v_cvt_pk_bf16_f32 v167, v122, v123
	v_cvt_pk_bf16_f32 v168, v124, v125
	v_cvt_pk_bf16_f32 v169, v126, v127
	v_cvt_pk_bf16_f32 v170, v128, v129
	v_cvt_pk_bf16_f32 v171, v130, v131
	global_store_dwordx4 v149, v[164:167], s[26:27]
	global_store_dwordx4 v149, v[168:171], s[26:27] offset:1024
	v_lshlrev_b32_e32 v116, 16, v24
	v_and_b32_e32 v117, 0xffff0000, v24
	v_lshlrev_b32_e32 v118, 16, v25
	v_and_b32_e32 v119, 0xffff0000, v25
	v_lshlrev_b32_e32 v120, 16, v26
	v_and_b32_e32 v121, 0xffff0000, v26
	v_lshlrev_b32_e32 v122, 16, v27
	v_and_b32_e32 v123, 0xffff0000, v27
	v_lshlrev_b32_e32 v124, 16, v28
	v_and_b32_e32 v125, 0xffff0000, v28
	v_lshlrev_b32_e32 v126, 16, v29
	v_and_b32_e32 v127, 0xffff0000, v29
	v_lshlrev_b32_e32 v128, 16, v30
	v_and_b32_e32 v129, 0xffff0000, v30
	v_lshlrev_b32_e32 v130, 16, v31
	v_and_b32_e32 v131, 0xffff0000, v31
	v_pk_mul_f32 v[116:117], v[146:147], v[116:117] op_sel_hi:[0,1]
	v_pk_mul_f32 v[118:119], v[146:147], v[118:119] op_sel_hi:[0,1]
	v_pk_mul_f32 v[120:121], v[146:147], v[120:121] op_sel_hi:[0,1]
	v_pk_mul_f32 v[122:123], v[146:147], v[122:123] op_sel_hi:[0,1]
	v_pk_mul_f32 v[124:125], v[146:147], v[124:125] op_sel_hi:[0,1]
	v_pk_mul_f32 v[126:127], v[146:147], v[126:127] op_sel_hi:[0,1]
	v_pk_mul_f32 v[128:129], v[146:147], v[128:129] op_sel_hi:[0,1]
	v_pk_mul_f32 v[130:131], v[146:147], v[130:131] op_sel_hi:[0,1]
	v_pk_mul_f32 v[116:117], v[116:117], v[32:33]
	v_pk_mul_f32 v[118:119], v[118:119], v[34:35]
	v_pk_mul_f32 v[120:121], v[120:121], v[36:37]
	v_pk_mul_f32 v[122:123], v[122:123], v[38:39]
	v_pk_mul_f32 v[124:125], v[124:125], v[40:41]
	v_pk_mul_f32 v[126:127], v[126:127], v[42:43]
	v_pk_mul_f32 v[128:129], v[128:129], v[44:45]
	v_pk_mul_f32 v[130:131], v[130:131], v[46:47]
	v_pk_fma_f32 v[116:117], v[116:117], v[84:85], v[100:101]
	v_pk_fma_f32 v[118:119], v[118:119], v[86:87], v[102:103]
	v_pk_fma_f32 v[120:121], v[120:121], v[88:89], v[104:105]
	v_pk_fma_f32 v[122:123], v[122:123], v[90:91], v[106:107]
	v_pk_fma_f32 v[124:125], v[124:125], v[92:93], v[108:109]
	v_pk_fma_f32 v[126:127], v[126:127], v[94:95], v[110:111]
	v_pk_fma_f32 v[128:129], v[128:129], v[96:97], v[112:113]
	v_pk_fma_f32 v[130:131], v[130:131], v[98:99], v[114:115]
	v_cvt_pk_bf16_f32 v172, v116, v117
	v_cvt_pk_bf16_f32 v173, v118, v119
	v_cvt_pk_bf16_f32 v174, v120, v121
	v_cvt_pk_bf16_f32 v175, v122, v123
	v_cvt_pk_bf16_f32 v176, v124, v125
	v_cvt_pk_bf16_f32 v177, v126, v127
	v_cvt_pk_bf16_f32 v178, v128, v129
	v_cvt_pk_bf16_f32 v179, v130, v131
	global_store_dwordx4 v149, v[172:175], s[26:27] offset:2048
	global_store_dwordx4 v149, v[176:179], s[26:27] offset:3072
	s_mul_i32 s36, s35, 0x6000
	s_add_u32 s0, s22, s36
	s_addc_u32 s1, s23, 0
	s_add_u32 s20, s0, 0x1000
	s_addc_u32 s21, s1, 0
	global_load_dwordx4 v[100:103], v148, s[0:1]
	global_load_dwordx4 v[104:107], v148, s[0:1] offset:16
	global_load_dwordx4 v[108:111], v148, s[0:1] offset:2048
	global_load_dwordx4 v[112:115], v148, s[0:1] offset:2064
	global_load_dwordx4 v[84:87], v148, s[20:21]
	global_load_dwordx4 v[88:91], v148, s[20:21] offset:16
	global_load_dwordx4 v[92:95], v148, s[20:21] offset:2048
	global_load_dwordx4 v[96:99], v148, s[20:21] offset:2064
	s_lshl_b32 s36, s31, 11
	s_add_u32 s24, s4, s36
	s_addc_u32 s25, s5, 0
	s_cmp_lt_u32 s36, 0x7000000
	s_cselect_b32 s26, s24, s18
	s_cselect_b32 s27, s25, s19
	s_cselect_b32 s37, 0x9000000, s36
	s_add_u32 s26, s26, s37
	s_addc_u32 s27, s27, 0
	global_load_dwordx4 v[52:55], v51, s[24:25]
	global_load_dwordx4 v[56:59], v51, s[24:25] offset:1024
	global_load_dwordx4 v[60:63], v51, s[24:25] offset:2048
	global_load_dwordx4 v[64:67], v51, s[24:25] offset:3072
	global_load_dwordx4 v[68:71], v149, s[24:25]
	global_load_dwordx4 v[72:75], v149, s[24:25] offset:1024
	global_load_dwordx4 v[76:79], v149, s[24:25] offset:2048
	global_load_dwordx4 v[80:83], v149, s[24:25] offset:3072
	s_waitcnt vmcnt(0)
	v_pk_add_f32 v[84:85], v[84:85], 1.0 op_sel_hi:[1,0]
	v_pk_add_f32 v[86:87], v[86:87], 1.0 op_sel_hi:[1,0]
	v_pk_add_f32 v[88:89], v[88:89], 1.0 op_sel_hi:[1,0]
	v_pk_add_f32 v[90:91], v[90:91], 1.0 op_sel_hi:[1,0]
	v_pk_add_f32 v[92:93], v[92:93], 1.0 op_sel_hi:[1,0]
	v_pk_add_f32 v[94:95], v[94:95], 1.0 op_sel_hi:[1,0]
	v_pk_add_f32 v[96:97], v[96:97], 1.0 op_sel_hi:[1,0]
	v_pk_add_f32 v[98:99], v[98:99], 1.0 op_sel_hi:[1,0]
	s_add_u32 s24, s24, 0x2000
	s_addc_u32 s25, s25, 0
	global_load_dwordx4 v[0:3], v51, s[24:25]
	global_load_dwordx4 v[4:7], v51, s[24:25] offset:1024
	global_load_dwordx4 v[8:11], v51, s[24:25] offset:2048
	global_load_dwordx4 v[12:15], v51, s[24:25] offset:3072
	global_load_dwordx4 v[16:19], v149, s[24:25]
	global_load_dwordx4 v[20:23], v149, s[24:25] offset:1024
	global_load_dwordx4 v[24:27], v149, s[24:25] offset:2048
	global_load_dwordx4 v[28:31], v149, s[24:25] offset:3072
	v_lshlrev_b32_e32 v116, 16, v52
	v_and_b32_e32 v117, 0xffff0000, v52
	v_lshlrev_b32_e32 v118, 16, v53
	v_and_b32_e32 v119, 0xffff0000, v53
	v_lshlrev_b32_e32 v120, 16, v54
	v_and_b32_e32 v121, 0xffff0000, v54
	v_lshlrev_b32_e32 v122, 16, v55
	v_and_b32_e32 v123, 0xffff0000, v55
	v_lshlrev_b32_e32 v124, 16, v56
	v_and_b32_e32 v125, 0xffff0000, v56
	v_lshlrev_b32_e32 v126, 16, v57
	v_and_b32_e32 v127, 0xffff0000, v57
	v_lshlrev_b32_e32 v128, 16, v58
	v_and_b32_e32 v129, 0xffff0000, v58
	v_lshlrev_b32_e32 v130, 16, v59
	v_and_b32_e32 v131, 0xffff0000, v59
	v_pk_mul_f32 v[132:133], v[116:117], v[116:117]
	v_pk_fma_f32 v[132:133], v[118:119], v[118:119], v[132:133]
	v_pk_fma_f32 v[132:133], v[120:121], v[120:121], v[132:133]
	v_pk_fma_f32 v[132:133], v[122:123], v[122:123], v[132:133]
	v_pk_fma_f32 v[132:133], v[124:125], v[124:125], v[132:133]
	v_pk_fma_f32 v[132:133], v[126:127], v[126:127], v[132:133]
	v_pk_fma_f32 v[132:133], v[128:129], v[128:129], v[132:133]
	v_pk_fma_f32 v[132:133], v[130:131], v[130:131], v[132:133]
	v_lshlrev_b32_e32 v116, 16, v60
	v_and_b32_e32 v117, 0xffff0000, v60
	v_lshlrev_b32_e32 v118, 16, v61
	v_and_b32_e32 v119, 0xffff0000, v61
	v_lshlrev_b32_e32 v120, 16, v62
	v_and_b32_e32 v121, 0xffff0000, v62
	v_lshlrev_b32_e32 v122, 16, v63
	v_and_b32_e32 v123, 0xffff0000, v63
	v_lshlrev_b32_e32 v124, 16, v64
	v_and_b32_e32 v125, 0xffff0000, v64
	v_lshlrev_b32_e32 v126, 16, v65
	v_and_b32_e32 v127, 0xffff0000, v65
	v_lshlrev_b32_e32 v128, 16, v66
	v_and_b32_e32 v129, 0xffff0000, v66
	v_lshlrev_b32_e32 v130, 16, v67
	v_and_b32_e32 v131, 0xffff0000, v67
	v_pk_mul_f32 v[134:135], v[116:117], v[116:117]
	v_pk_fma_f32 v[134:135], v[118:119], v[118:119], v[134:135]
	v_pk_fma_f32 v[134:135], v[120:121], v[120:121], v[134:135]
	v_pk_fma_f32 v[134:135], v[122:123], v[122:123], v[134:135]
	v_pk_fma_f32 v[134:135], v[124:125], v[124:125], v[134:135]
	v_pk_fma_f32 v[134:135], v[126:127], v[126:127], v[134:135]
	v_pk_fma_f32 v[134:135], v[128:129], v[128:129], v[134:135]
	v_pk_fma_f32 v[134:135], v[130:131], v[130:131], v[134:135]
	v_lshlrev_b32_e32 v116, 16, v68
	v_and_b32_e32 v117, 0xffff0000, v68
	v_lshlrev_b32_e32 v118, 16, v69
	v_and_b32_e32 v119, 0xffff0000, v69
	v_lshlrev_b32_e32 v120, 16, v70
	v_and_b32_e32 v121, 0xffff0000, v70
	v_lshlrev_b32_e32 v122, 16, v71
	v_and_b32_e32 v123, 0xffff0000, v71
	v_lshlrev_b32_e32 v124, 16, v72
	v_and_b32_e32 v125, 0xffff0000, v72
	v_lshlrev_b32_e32 v126, 16, v73
	v_and_b32_e32 v127, 0xffff0000, v73
	v_lshlrev_b32_e32 v128, 16, v74
	v_and_b32_e32 v129, 0xffff0000, v74
	v_lshlrev_b32_e32 v130, 16, v75
	v_and_b32_e32 v131, 0xffff0000, v75
	v_pk_mul_f32 v[136:137], v[116:117], v[116:117]
	v_pk_fma_f32 v[136:137], v[118:119], v[118:119], v[136:137]
	v_pk_fma_f32 v[136:137], v[120:121], v[120:121], v[136:137]
	v_pk_fma_f32 v[136:137], v[122:123], v[122:123], v[136:137]
	v_pk_fma_f32 v[136:137], v[124:125], v[124:125], v[136:137]
	v_pk_fma_f32 v[136:137], v[126:127], v[126:127], v[136:137]
	v_pk_fma_f32 v[136:137], v[128:129], v[128:129], v[136:137]
	v_pk_fma_f32 v[136:137], v[130:131], v[130:131], v[136:137]
	v_lshlrev_b32_e32 v116, 16, v76
	v_and_b32_e32 v117, 0xffff0000, v76
	v_lshlrev_b32_e32 v118, 16, v77
	v_and_b32_e32 v119, 0xffff0000, v77
	v_lshlrev_b32_e32 v120, 16, v78
	v_and_b32_e32 v121, 0xffff0000, v78
	v_lshlrev_b32_e32 v122, 16, v79
	v_and_b32_e32 v123, 0xffff0000, v79
	v_lshlrev_b32_e32 v124, 16, v80
	v_and_b32_e32 v125, 0xffff0000, v80
	v_lshlrev_b32_e32 v126, 16, v81
	v_and_b32_e32 v127, 0xffff0000, v81
	v_lshlrev_b32_e32 v128, 16, v82
	v_and_b32_e32 v129, 0xffff0000, v82
	v_lshlrev_b32_e32 v130, 16, v83
	v_and_b32_e32 v131, 0xffff0000, v83
	v_pk_mul_f32 v[138:139], v[116:117], v[116:117]
	v_pk_fma_f32 v[138:139], v[118:119], v[118:119], v[138:139]
	v_pk_fma_f32 v[138:139], v[120:121], v[120:121], v[138:139]
	v_pk_fma_f32 v[138:139], v[122:123], v[122:123], v[138:139]
	v_pk_fma_f32 v[138:139], v[124:125], v[124:125], v[138:139]
	v_pk_fma_f32 v[138:139], v[126:127], v[126:127], v[138:139]
	v_pk_fma_f32 v[138:139], v[128:129], v[128:129], v[138:139]
	v_pk_fma_f32 v[138:139], v[130:131], v[130:131], v[138:139]
	v_add_f32_e32 v132, v132, v133
	v_add_f32_e32 v134, v134, v135
	v_add_f32_e32 v136, v136, v137
	v_add_f32_e32 v138, v138, v139
	s_nop 1
	v_add_f32_dpp v132, v132, v132 row_shr:1 row_mask:0xf bank_mask:0xf bound_ctrl:1
	v_add_f32_dpp v134, v134, v134 row_shr:1 row_mask:0xf bank_mask:0xf bound_ctrl:1
	v_add_f32_dpp v136, v136, v136 row_shr:1 row_mask:0xf bank_mask:0xf bound_ctrl:1
	v_add_f32_dpp v138, v138, v138 row_shr:1 row_mask:0xf bank_mask:0xf bound_ctrl:1
	v_add_f32_dpp v132, v132, v132 row_shr:2 row_mask:0xf bank_mask:0xf bound_ctrl:1
	v_add_f32_dpp v134, v134, v134 row_shr:2 row_mask:0xf bank_mask:0xf bound_ctrl:1
	v_add_f32_dpp v136, v136, v136 row_shr:2 row_mask:0xf bank_mask:0xf bound_ctrl:1
	v_add_f32_dpp v138, v138, v138 row_shr:2 row_mask:0xf bank_mask:0xf bound_ctrl:1
	v_add_f32_dpp v132, v132, v132 row_shr:4 row_mask:0xf bank_mask:0xf bound_ctrl:1
	v_add_f32_dpp v134, v134, v134 row_shr:4 row_mask:0xf bank_mask:0xf bound_ctrl:1
	v_add_f32_dpp v136, v136, v136 row_shr:4 row_mask:0xf bank_mask:0xf bound_ctrl:1
	v_add_f32_dpp v138, v138, v138 row_shr:4 row_mask:0xf bank_mask:0xf bound_ctrl:1
	v_add_f32_dpp v132, v132, v132 row_shr:8 row_mask:0xf bank_mask:0xf bound_ctrl:1
	v_add_f32_dpp v134, v134, v134 row_shr:8 row_mask:0xf bank_mask:0xf bound_ctrl:1
	v_add_f32_dpp v136, v136, v136 row_shr:8 row_mask:0xf bank_mask:0xf bound_ctrl:1
	v_add_f32_dpp v138, v138, v138 row_shr:8 row_mask:0xf bank_mask:0xf bound_ctrl:1
	v_add_f32_dpp v132, v132, v132 row_bcast:15 row_mask:0xa bank_mask:0xf
	v_add_f32_dpp v134, v134, v134 row_bcast:15 row_mask:0xa bank_mask:0xf
	v_add_f32_dpp v136, v136, v136 row_bcast:15 row_mask:0xa bank_mask:0xf
	v_add_f32_dpp v138, v138, v138 row_bcast:15 row_mask:0xa bank_mask:0xf
	v_add_f32_dpp v132, v132, v132 row_bcast:31 row_mask:0xc bank_mask:0xf
	v_add_f32_dpp v134, v134, v134 row_bcast:31 row_mask:0xc bank_mask:0xf
	v_add_f32_dpp v136, v136, v136 row_bcast:31 row_mask:0xc bank_mask:0xf
	v_add_f32_dpp v138, v138, v138 row_bcast:31 row_mask:0xc bank_mask:0xf
	s_nop 1
	v_readlane_b32 s32, v132, 63
	v_readlane_b32 s28, v134, 63
	v_readlane_b32 s29, v136, 63
	v_readlane_b32 s30, v138, 63
	s_nop 1
	v_mov_b32_e32 v140, s32
	v_mov_b32_e32 v142, s28
	v_mov_b32_e32 v144, s29
	v_mov_b32_e32 v146, s30
	v_fmaak_f32 v140, v140, v50, 0x358637bd
	v_fmaak_f32 v142, v142, v50, 0x358637bd
	v_fmaak_f32 v144, v144, v50, 0x358637bd
	v_fmaak_f32 v146, v146, v50, 0x358637bd
	v_rsq_f32_e32 v140, v140
	v_rsq_f32_e32 v142, v142
	v_rsq_f32_e32 v144, v144
	v_rsq_f32_e32 v146, v146
	s_nop 0
	v_lshlrev_b32_e32 v116, 16, v52
	v_and_b32_e32 v117, 0xffff0000, v52
	v_lshlrev_b32_e32 v118, 16, v53
	v_and_b32_e32 v119, 0xffff0000, v53
	v_lshlrev_b32_e32 v120, 16, v54
	v_and_b32_e32 v121, 0xffff0000, v54
	v_lshlrev_b32_e32 v122, 16, v55
	v_and_b32_e32 v123, 0xffff0000, v55
	v_lshlrev_b32_e32 v124, 16, v56
	v_and_b32_e32 v125, 0xffff0000, v56
	v_lshlrev_b32_e32 v126, 16, v57
	v_and_b32_e32 v127, 0xffff0000, v57
	v_lshlrev_b32_e32 v128, 16, v58
	v_and_b32_e32 v129, 0xffff0000, v58
	v_lshlrev_b32_e32 v130, 16, v59
	v_and_b32_e32 v131, 0xffff0000, v59
	v_pk_mul_f32 v[116:117], v[140:141], v[116:117] op_sel_hi:[0,1]
	v_pk_mul_f32 v[118:119], v[140:141], v[118:119] op_sel_hi:[0,1]
	v_pk_mul_f32 v[120:121], v[140:141], v[120:121] op_sel_hi:[0,1]
	v_pk_mul_f32 v[122:123], v[140:141], v[122:123] op_sel_hi:[0,1]
	v_pk_mul_f32 v[124:125], v[140:141], v[124:125] op_sel_hi:[0,1]
	v_pk_mul_f32 v[126:127], v[140:141], v[126:127] op_sel_hi:[0,1]
	v_pk_mul_f32 v[128:129], v[140:141], v[128:129] op_sel_hi:[0,1]
	v_pk_mul_f32 v[130:131], v[140:141], v[130:131] op_sel_hi:[0,1]
	v_pk_mul_f32 v[116:117], v[116:117], v[32:33]
	v_pk_mul_f32 v[118:119], v[118:119], v[34:35]
	v_pk_mul_f32 v[120:121], v[120:121], v[36:37]
	v_pk_mul_f32 v[122:123], v[122:123], v[38:39]
	v_pk_mul_f32 v[124:125], v[124:125], v[40:41]
	v_pk_mul_f32 v[126:127], v[126:127], v[42:43]
	v_pk_mul_f32 v[128:129], v[128:129], v[44:45]
	v_pk_mul_f32 v[130:131], v[130:131], v[46:47]
	v_pk_fma_f32 v[116:117], v[116:117], v[84:85], v[100:101]
	v_pk_fma_f32 v[118:119], v[118:119], v[86:87], v[102:103]
	v_pk_fma_f32 v[120:121], v[120:121], v[88:89], v[104:105]
	v_pk_fma_f32 v[122:123], v[122:123], v[90:91], v[106:107]
	v_pk_fma_f32 v[124:125], v[124:125], v[92:93], v[108:109]
	v_pk_fma_f32 v[126:127], v[126:127], v[94:95], v[110:111]
	v_pk_fma_f32 v[128:129], v[128:129], v[96:97], v[112:113]
	v_pk_fma_f32 v[130:131], v[130:131], v[98:99], v[114:115]
	v_cvt_pk_bf16_f32 v164, v116, v117
	v_cvt_pk_bf16_f32 v165, v118, v119
	v_cvt_pk_bf16_f32 v166, v120, v121
	v_cvt_pk_bf16_f32 v167, v122, v123
	v_cvt_pk_bf16_f32 v168, v124, v125
	v_cvt_pk_bf16_f32 v169, v126, v127
	v_cvt_pk_bf16_f32 v170, v128, v129
	v_cvt_pk_bf16_f32 v171, v130, v131
	global_store_dwordx4 v51, v[164:167], s[26:27]
	global_store_dwordx4 v51, v[168:171], s[26:27] offset:1024
	v_lshlrev_b32_e32 v116, 16, v60
	v_and_b32_e32 v117, 0xffff0000, v60
	v_lshlrev_b32_e32 v118, 16, v61
	v_and_b32_e32 v119, 0xffff0000, v61
	v_lshlrev_b32_e32 v120, 16, v62
	v_and_b32_e32 v121, 0xffff0000, v62
	v_lshlrev_b32_e32 v122, 16, v63
	v_and_b32_e32 v123, 0xffff0000, v63
	v_lshlrev_b32_e32 v124, 16, v64
	v_and_b32_e32 v125, 0xffff0000, v64
	v_lshlrev_b32_e32 v126, 16, v65
	v_and_b32_e32 v127, 0xffff0000, v65
	v_lshlrev_b32_e32 v128, 16, v66
	v_and_b32_e32 v129, 0xffff0000, v66
	v_lshlrev_b32_e32 v130, 16, v67
	v_and_b32_e32 v131, 0xffff0000, v67
	v_pk_mul_f32 v[116:117], v[142:143], v[116:117] op_sel_hi:[0,1]
	v_pk_mul_f32 v[118:119], v[142:143], v[118:119] op_sel_hi:[0,1]
	v_pk_mul_f32 v[120:121], v[142:143], v[120:121] op_sel_hi:[0,1]
	v_pk_mul_f32 v[122:123], v[142:143], v[122:123] op_sel_hi:[0,1]
	v_pk_mul_f32 v[124:125], v[142:143], v[124:125] op_sel_hi:[0,1]
	v_pk_mul_f32 v[126:127], v[142:143], v[126:127] op_sel_hi:[0,1]
	v_pk_mul_f32 v[128:129], v[142:143], v[128:129] op_sel_hi:[0,1]
	v_pk_mul_f32 v[130:131], v[142:143], v[130:131] op_sel_hi:[0,1]
	v_pk_mul_f32 v[116:117], v[116:117], v[32:33]
	v_pk_mul_f32 v[118:119], v[118:119], v[34:35]
	v_pk_mul_f32 v[120:121], v[120:121], v[36:37]
	v_pk_mul_f32 v[122:123], v[122:123], v[38:39]
	v_pk_mul_f32 v[124:125], v[124:125], v[40:41]
	v_pk_mul_f32 v[126:127], v[126:127], v[42:43]
	v_pk_mul_f32 v[128:129], v[128:129], v[44:45]
	v_pk_mul_f32 v[130:131], v[130:131], v[46:47]
	v_pk_fma_f32 v[116:117], v[116:117], v[84:85], v[100:101]
	v_pk_fma_f32 v[118:119], v[118:119], v[86:87], v[102:103]
	v_pk_fma_f32 v[120:121], v[120:121], v[88:89], v[104:105]
	v_pk_fma_f32 v[122:123], v[122:123], v[90:91], v[106:107]
	v_pk_fma_f32 v[124:125], v[124:125], v[92:93], v[108:109]
	v_pk_fma_f32 v[126:127], v[126:127], v[94:95], v[110:111]
	v_pk_fma_f32 v[128:129], v[128:129], v[96:97], v[112:113]
	v_pk_fma_f32 v[130:131], v[130:131], v[98:99], v[114:115]
	v_cvt_pk_bf16_f32 v172, v116, v117
	v_cvt_pk_bf16_f32 v173, v118, v119
	v_cvt_pk_bf16_f32 v174, v120, v121
	v_cvt_pk_bf16_f32 v175, v122, v123
	v_cvt_pk_bf16_f32 v176, v124, v125
	v_cvt_pk_bf16_f32 v177, v126, v127
	v_cvt_pk_bf16_f32 v178, v128, v129
	v_cvt_pk_bf16_f32 v179, v130, v131
	global_store_dwordx4 v51, v[172:175], s[26:27] offset:2048
	global_store_dwordx4 v51, v[176:179], s[26:27] offset:3072
	v_lshlrev_b32_e32 v116, 16, v68
	v_and_b32_e32 v117, 0xffff0000, v68
	v_lshlrev_b32_e32 v118, 16, v69
	v_and_b32_e32 v119, 0xffff0000, v69
	v_lshlrev_b32_e32 v120, 16, v70
	v_and_b32_e32 v121, 0xffff0000, v70
	v_lshlrev_b32_e32 v122, 16, v71
	v_and_b32_e32 v123, 0xffff0000, v71
	v_lshlrev_b32_e32 v124, 16, v72
	v_and_b32_e32 v125, 0xffff0000, v72
	v_lshlrev_b32_e32 v126, 16, v73
	v_and_b32_e32 v127, 0xffff0000, v73
	v_lshlrev_b32_e32 v128, 16, v74
	v_and_b32_e32 v129, 0xffff0000, v74
	v_lshlrev_b32_e32 v130, 16, v75
	v_and_b32_e32 v131, 0xffff0000, v75
	v_pk_mul_f32 v[116:117], v[144:145], v[116:117] op_sel_hi:[0,1]
	v_pk_mul_f32 v[118:119], v[144:145], v[118:119] op_sel_hi:[0,1]
	v_pk_mul_f32 v[120:121], v[144:145], v[120:121] op_sel_hi:[0,1]
	v_pk_mul_f32 v[122:123], v[144:145], v[122:123] op_sel_hi:[0,1]
	v_pk_mul_f32 v[124:125], v[144:145], v[124:125] op_sel_hi:[0,1]
	v_pk_mul_f32 v[126:127], v[144:145], v[126:127] op_sel_hi:[0,1]
	v_pk_mul_f32 v[128:129], v[144:145], v[128:129] op_sel_hi:[0,1]
	v_pk_mul_f32 v[130:131], v[144:145], v[130:131] op_sel_hi:[0,1]
	v_pk_mul_f32 v[116:117], v[116:117], v[32:33]
	v_pk_mul_f32 v[118:119], v[118:119], v[34:35]
	v_pk_mul_f32 v[120:121], v[120:121], v[36:37]
	v_pk_mul_f32 v[122:123], v[122:123], v[38:39]
	v_pk_mul_f32 v[124:125], v[124:125], v[40:41]
	v_pk_mul_f32 v[126:127], v[126:127], v[42:43]
	v_pk_mul_f32 v[128:129], v[128:129], v[44:45]
	v_pk_mul_f32 v[130:131], v[130:131], v[46:47]
	v_pk_fma_f32 v[116:117], v[116:117], v[84:85], v[100:101]
	v_pk_fma_f32 v[118:119], v[118:119], v[86:87], v[102:103]
	v_pk_fma_f32 v[120:121], v[120:121], v[88:89], v[104:105]
	v_pk_fma_f32 v[122:123], v[122:123], v[90:91], v[106:107]
	v_pk_fma_f32 v[124:125], v[124:125], v[92:93], v[108:109]
	v_pk_fma_f32 v[126:127], v[126:127], v[94:95], v[110:111]
	v_pk_fma_f32 v[128:129], v[128:129], v[96:97], v[112:113]
	v_pk_fma_f32 v[130:131], v[130:131], v[98:99], v[114:115]
	v_cvt_pk_bf16_f32 v164, v116, v117
	v_cvt_pk_bf16_f32 v165, v118, v119
	v_cvt_pk_bf16_f32 v166, v120, v121
	v_cvt_pk_bf16_f32 v167, v122, v123
	v_cvt_pk_bf16_f32 v168, v124, v125
	v_cvt_pk_bf16_f32 v169, v126, v127
	v_cvt_pk_bf16_f32 v170, v128, v129
	v_cvt_pk_bf16_f32 v171, v130, v131
	global_store_dwordx4 v149, v[164:167], s[26:27]
	global_store_dwordx4 v149, v[168:171], s[26:27] offset:1024
	v_lshlrev_b32_e32 v116, 16, v76
	v_and_b32_e32 v117, 0xffff0000, v76
	v_lshlrev_b32_e32 v118, 16, v77
	v_and_b32_e32 v119, 0xffff0000, v77
	v_lshlrev_b32_e32 v120, 16, v78
	v_and_b32_e32 v121, 0xffff0000, v78
	v_lshlrev_b32_e32 v122, 16, v79
	v_and_b32_e32 v123, 0xffff0000, v79
	v_lshlrev_b32_e32 v124, 16, v80
	v_and_b32_e32 v125, 0xffff0000, v80
	v_lshlrev_b32_e32 v126, 16, v81
	v_and_b32_e32 v127, 0xffff0000, v81
	v_lshlrev_b32_e32 v128, 16, v82
	v_and_b32_e32 v129, 0xffff0000, v82
	v_lshlrev_b32_e32 v130, 16, v83
	v_and_b32_e32 v131, 0xffff0000, v83
	v_pk_mul_f32 v[116:117], v[146:147], v[116:117] op_sel_hi:[0,1]
	v_pk_mul_f32 v[118:119], v[146:147], v[118:119] op_sel_hi:[0,1]
	v_pk_mul_f32 v[120:121], v[146:147], v[120:121] op_sel_hi:[0,1]
	v_pk_mul_f32 v[122:123], v[146:147], v[122:123] op_sel_hi:[0,1]
	v_pk_mul_f32 v[124:125], v[146:147], v[124:125] op_sel_hi:[0,1]
	v_pk_mul_f32 v[126:127], v[146:147], v[126:127] op_sel_hi:[0,1]
	v_pk_mul_f32 v[128:129], v[146:147], v[128:129] op_sel_hi:[0,1]
	v_pk_mul_f32 v[130:131], v[146:147], v[130:131] op_sel_hi:[0,1]
	v_pk_mul_f32 v[116:117], v[116:117], v[32:33]
	v_pk_mul_f32 v[118:119], v[118:119], v[34:35]
	v_pk_mul_f32 v[120:121], v[120:121], v[36:37]
	v_pk_mul_f32 v[122:123], v[122:123], v[38:39]
	v_pk_mul_f32 v[124:125], v[124:125], v[40:41]
	v_pk_mul_f32 v[126:127], v[126:127], v[42:43]
	v_pk_mul_f32 v[128:129], v[128:129], v[44:45]
	v_pk_mul_f32 v[130:131], v[130:131], v[46:47]
	v_pk_fma_f32 v[116:117], v[116:117], v[84:85], v[100:101]
	v_pk_fma_f32 v[118:119], v[118:119], v[86:87], v[102:103]
	v_pk_fma_f32 v[120:121], v[120:121], v[88:89], v[104:105]
	v_pk_fma_f32 v[122:123], v[122:123], v[90:91], v[106:107]
	v_pk_fma_f32 v[124:125], v[124:125], v[92:93], v[108:109]
	v_pk_fma_f32 v[126:127], v[126:127], v[94:95], v[110:111]
	v_pk_fma_f32 v[128:129], v[128:129], v[96:97], v[112:113]
	v_pk_fma_f32 v[130:131], v[130:131], v[98:99], v[114:115]
	v_cvt_pk_bf16_f32 v172, v116, v117
	v_cvt_pk_bf16_f32 v173, v118, v119
	v_cvt_pk_bf16_f32 v174, v120, v121
	v_cvt_pk_bf16_f32 v175, v122, v123
	v_cvt_pk_bf16_f32 v176, v124, v125
	v_cvt_pk_bf16_f32 v177, v126, v127
	v_cvt_pk_bf16_f32 v178, v128, v129
	v_cvt_pk_bf16_f32 v179, v130, v131
	global_store_dwordx4 v149, v[172:175], s[26:27] offset:2048
	global_store_dwordx4 v149, v[176:179], s[26:27] offset:3072
	s_add_u32 s26, s26, 0x2000
	s_addc_u32 s27, s27, 0
	s_add_u32 s24, s24, 0x2000
	s_addc_u32 s25, s25, 0
	global_load_dwordx4 v[52:55], v51, s[24:25]
	global_load_dwordx4 v[56:59], v51, s[24:25] offset:1024
	global_load_dwordx4 v[60:63], v51, s[24:25] offset:2048
	global_load_dwordx4 v[64:67], v51, s[24:25] offset:3072
	global_load_dwordx4 v[68:71], v149, s[24:25]
	global_load_dwordx4 v[72:75], v149, s[24:25] offset:1024
	global_load_dwordx4 v[76:79], v149, s[24:25] offset:2048
	global_load_dwordx4 v[80:83], v149, s[24:25] offset:3072
	s_waitcnt vmcnt(16)
	v_lshlrev_b32_e32 v116, 16, v0
	v_and_b32_e32 v117, 0xffff0000, v0
	v_lshlrev_b32_e32 v118, 16, v1
	v_and_b32_e32 v119, 0xffff0000, v1
	v_lshlrev_b32_e32 v120, 16, v2
	v_and_b32_e32 v121, 0xffff0000, v2
	v_lshlrev_b32_e32 v122, 16, v3
	v_and_b32_e32 v123, 0xffff0000, v3
	v_lshlrev_b32_e32 v124, 16, v4
	v_and_b32_e32 v125, 0xffff0000, v4
	v_lshlrev_b32_e32 v126, 16, v5
	v_and_b32_e32 v127, 0xffff0000, v5
	v_lshlrev_b32_e32 v128, 16, v6
	v_and_b32_e32 v129, 0xffff0000, v6
	v_lshlrev_b32_e32 v130, 16, v7
	v_and_b32_e32 v131, 0xffff0000, v7
	v_pk_mul_f32 v[132:133], v[116:117], v[116:117]
	v_pk_fma_f32 v[132:133], v[118:119], v[118:119], v[132:133]
	v_pk_fma_f32 v[132:133], v[120:121], v[120:121], v[132:133]
	v_pk_fma_f32 v[132:133], v[122:123], v[122:123], v[132:133]
	v_pk_fma_f32 v[132:133], v[124:125], v[124:125], v[132:133]
	v_pk_fma_f32 v[132:133], v[126:127], v[126:127], v[132:133]
	v_pk_fma_f32 v[132:133], v[128:129], v[128:129], v[132:133]
	v_pk_fma_f32 v[132:133], v[130:131], v[130:131], v[132:133]
	v_lshlrev_b32_e32 v116, 16, v8
	v_and_b32_e32 v117, 0xffff0000, v8
	v_lshlrev_b32_e32 v118, 16, v9
	v_and_b32_e32 v119, 0xffff0000, v9
	v_lshlrev_b32_e32 v120, 16, v10
	v_and_b32_e32 v121, 0xffff0000, v10
	v_lshlrev_b32_e32 v122, 16, v11
	v_and_b32_e32 v123, 0xffff0000, v11
	v_lshlrev_b32_e32 v124, 16, v12
	v_and_b32_e32 v125, 0xffff0000, v12
	v_lshlrev_b32_e32 v126, 16, v13
	v_and_b32_e32 v127, 0xffff0000, v13
	v_lshlrev_b32_e32 v128, 16, v14
	v_and_b32_e32 v129, 0xffff0000, v14
	v_lshlrev_b32_e32 v130, 16, v15
	v_and_b32_e32 v131, 0xffff0000, v15
	v_pk_mul_f32 v[134:135], v[116:117], v[116:117]
	v_pk_fma_f32 v[134:135], v[118:119], v[118:119], v[134:135]
	v_pk_fma_f32 v[134:135], v[120:121], v[120:121], v[134:135]
	v_pk_fma_f32 v[134:135], v[122:123], v[122:123], v[134:135]
	v_pk_fma_f32 v[134:135], v[124:125], v[124:125], v[134:135]
	v_pk_fma_f32 v[134:135], v[126:127], v[126:127], v[134:135]
	v_pk_fma_f32 v[134:135], v[128:129], v[128:129], v[134:135]
	v_pk_fma_f32 v[134:135], v[130:131], v[130:131], v[134:135]
	v_lshlrev_b32_e32 v116, 16, v16
	v_and_b32_e32 v117, 0xffff0000, v16
	v_lshlrev_b32_e32 v118, 16, v17
	v_and_b32_e32 v119, 0xffff0000, v17
	v_lshlrev_b32_e32 v120, 16, v18
	v_and_b32_e32 v121, 0xffff0000, v18
	v_lshlrev_b32_e32 v122, 16, v19
	v_and_b32_e32 v123, 0xffff0000, v19
	v_lshlrev_b32_e32 v124, 16, v20
	v_and_b32_e32 v125, 0xffff0000, v20
	v_lshlrev_b32_e32 v126, 16, v21
	v_and_b32_e32 v127, 0xffff0000, v21
	v_lshlrev_b32_e32 v128, 16, v22
	v_and_b32_e32 v129, 0xffff0000, v22
	v_lshlrev_b32_e32 v130, 16, v23
	v_and_b32_e32 v131, 0xffff0000, v23
	v_pk_mul_f32 v[136:137], v[116:117], v[116:117]
	v_pk_fma_f32 v[136:137], v[118:119], v[118:119], v[136:137]
	v_pk_fma_f32 v[136:137], v[120:121], v[120:121], v[136:137]
	v_pk_fma_f32 v[136:137], v[122:123], v[122:123], v[136:137]
	v_pk_fma_f32 v[136:137], v[124:125], v[124:125], v[136:137]
	v_pk_fma_f32 v[136:137], v[126:127], v[126:127], v[136:137]
	v_pk_fma_f32 v[136:137], v[128:129], v[128:129], v[136:137]
	v_pk_fma_f32 v[136:137], v[130:131], v[130:131], v[136:137]
	v_lshlrev_b32_e32 v116, 16, v24
	v_and_b32_e32 v117, 0xffff0000, v24
	v_lshlrev_b32_e32 v118, 16, v25
	v_and_b32_e32 v119, 0xffff0000, v25
	v_lshlrev_b32_e32 v120, 16, v26
	v_and_b32_e32 v121, 0xffff0000, v26
	v_lshlrev_b32_e32 v122, 16, v27
	v_and_b32_e32 v123, 0xffff0000, v27
	v_lshlrev_b32_e32 v124, 16, v28
	v_and_b32_e32 v125, 0xffff0000, v28
	v_lshlrev_b32_e32 v126, 16, v29
	v_and_b32_e32 v127, 0xffff0000, v29
	v_lshlrev_b32_e32 v128, 16, v30
	v_and_b32_e32 v129, 0xffff0000, v30
	v_lshlrev_b32_e32 v130, 16, v31
	v_and_b32_e32 v131, 0xffff0000, v31
	v_pk_mul_f32 v[138:139], v[116:117], v[116:117]
	v_pk_fma_f32 v[138:139], v[118:119], v[118:119], v[138:139]
	v_pk_fma_f32 v[138:139], v[120:121], v[120:121], v[138:139]
	v_pk_fma_f32 v[138:139], v[122:123], v[122:123], v[138:139]
	v_pk_fma_f32 v[138:139], v[124:125], v[124:125], v[138:139]
	v_pk_fma_f32 v[138:139], v[126:127], v[126:127], v[138:139]
	v_pk_fma_f32 v[138:139], v[128:129], v[128:129], v[138:139]
	v_pk_fma_f32 v[138:139], v[130:131], v[130:131], v[138:139]
	v_add_f32_e32 v132, v132, v133
	v_add_f32_e32 v134, v134, v135
	v_add_f32_e32 v136, v136, v137
	v_add_f32_e32 v138, v138, v139
	s_nop 1
	v_add_f32_dpp v132, v132, v132 row_shr:1 row_mask:0xf bank_mask:0xf bound_ctrl:1
	v_add_f32_dpp v134, v134, v134 row_shr:1 row_mask:0xf bank_mask:0xf bound_ctrl:1
	v_add_f32_dpp v136, v136, v136 row_shr:1 row_mask:0xf bank_mask:0xf bound_ctrl:1
	v_add_f32_dpp v138, v138, v138 row_shr:1 row_mask:0xf bank_mask:0xf bound_ctrl:1
	v_add_f32_dpp v132, v132, v132 row_shr:2 row_mask:0xf bank_mask:0xf bound_ctrl:1
	v_add_f32_dpp v134, v134, v134 row_shr:2 row_mask:0xf bank_mask:0xf bound_ctrl:1
	v_add_f32_dpp v136, v136, v136 row_shr:2 row_mask:0xf bank_mask:0xf bound_ctrl:1
	v_add_f32_dpp v138, v138, v138 row_shr:2 row_mask:0xf bank_mask:0xf bound_ctrl:1
	v_add_f32_dpp v132, v132, v132 row_shr:4 row_mask:0xf bank_mask:0xf bound_ctrl:1
	v_add_f32_dpp v134, v134, v134 row_shr:4 row_mask:0xf bank_mask:0xf bound_ctrl:1
	v_add_f32_dpp v136, v136, v136 row_shr:4 row_mask:0xf bank_mask:0xf bound_ctrl:1
	v_add_f32_dpp v138, v138, v138 row_shr:4 row_mask:0xf bank_mask:0xf bound_ctrl:1
	v_add_f32_dpp v132, v132, v132 row_shr:8 row_mask:0xf bank_mask:0xf bound_ctrl:1
	v_add_f32_dpp v134, v134, v134 row_shr:8 row_mask:0xf bank_mask:0xf bound_ctrl:1
	v_add_f32_dpp v136, v136, v136 row_shr:8 row_mask:0xf bank_mask:0xf bound_ctrl:1
	v_add_f32_dpp v138, v138, v138 row_shr:8 row_mask:0xf bank_mask:0xf bound_ctrl:1
	v_add_f32_dpp v132, v132, v132 row_bcast:15 row_mask:0xa bank_mask:0xf
	v_add_f32_dpp v134, v134, v134 row_bcast:15 row_mask:0xa bank_mask:0xf
	v_add_f32_dpp v136, v136, v136 row_bcast:15 row_mask:0xa bank_mask:0xf
	v_add_f32_dpp v138, v138, v138 row_bcast:15 row_mask:0xa bank_mask:0xf
	v_add_f32_dpp v132, v132, v132 row_bcast:31 row_mask:0xc bank_mask:0xf
	v_add_f32_dpp v134, v134, v134 row_bcast:31 row_mask:0xc bank_mask:0xf
	v_add_f32_dpp v136, v136, v136 row_bcast:31 row_mask:0xc bank_mask:0xf
	v_add_f32_dpp v138, v138, v138 row_bcast:31 row_mask:0xc bank_mask:0xf
	s_nop 1
	v_readlane_b32 s32, v132, 63
	v_readlane_b32 s28, v134, 63
	v_readlane_b32 s29, v136, 63
	v_readlane_b32 s30, v138, 63
	s_nop 1
	v_mov_b32_e32 v140, s32
	v_mov_b32_e32 v142, s28
	v_mov_b32_e32 v144, s29
	v_mov_b32_e32 v146, s30
	v_fmaak_f32 v140, v140, v50, 0x358637bd
	v_fmaak_f32 v142, v142, v50, 0x358637bd
	v_fmaak_f32 v144, v144, v50, 0x358637bd
	v_fmaak_f32 v146, v146, v50, 0x358637bd
	v_rsq_f32_e32 v140, v140
	v_rsq_f32_e32 v142, v142
	v_rsq_f32_e32 v144, v144
	v_rsq_f32_e32 v146, v146
	s_nop 0
	v_lshlrev_b32_e32 v116, 16, v0
	v_and_b32_e32 v117, 0xffff0000, v0
	v_lshlrev_b32_e32 v118, 16, v1
	v_and_b32_e32 v119, 0xffff0000, v1
	v_lshlrev_b32_e32 v120, 16, v2
	v_and_b32_e32 v121, 0xffff0000, v2
	v_lshlrev_b32_e32 v122, 16, v3
	v_and_b32_e32 v123, 0xffff0000, v3
	v_lshlrev_b32_e32 v124, 16, v4
	v_and_b32_e32 v125, 0xffff0000, v4
	v_lshlrev_b32_e32 v126, 16, v5
	v_and_b32_e32 v127, 0xffff0000, v5
	v_lshlrev_b32_e32 v128, 16, v6
	v_and_b32_e32 v129, 0xffff0000, v6
	v_lshlrev_b32_e32 v130, 16, v7
	v_and_b32_e32 v131, 0xffff0000, v7
	v_pk_mul_f32 v[116:117], v[140:141], v[116:117] op_sel_hi:[0,1]
	v_pk_mul_f32 v[118:119], v[140:141], v[118:119] op_sel_hi:[0,1]
	v_pk_mul_f32 v[120:121], v[140:141], v[120:121] op_sel_hi:[0,1]
	v_pk_mul_f32 v[122:123], v[140:141], v[122:123] op_sel_hi:[0,1]
	v_pk_mul_f32 v[124:125], v[140:141], v[124:125] op_sel_hi:[0,1]
	v_pk_mul_f32 v[126:127], v[140:141], v[126:127] op_sel_hi:[0,1]
	v_pk_mul_f32 v[128:129], v[140:141], v[128:129] op_sel_hi:[0,1]
	v_pk_mul_f32 v[130:131], v[140:141], v[130:131] op_sel_hi:[0,1]
	v_pk_mul_f32 v[116:117], v[116:117], v[32:33]
	v_pk_mul_f32 v[118:119], v[118:119], v[34:35]
	v_pk_mul_f32 v[120:121], v[120:121], v[36:37]
	v_pk_mul_f32 v[122:123], v[122:123], v[38:39]
	v_pk_mul_f32 v[124:125], v[124:125], v[40:41]
	v_pk_mul_f32 v[126:127], v[126:127], v[42:43]
	v_pk_mul_f32 v[128:129], v[128:129], v[44:45]
	v_pk_mul_f32 v[130:131], v[130:131], v[46:47]
	v_pk_fma_f32 v[116:117], v[116:117], v[84:85], v[100:101]
	v_pk_fma_f32 v[118:119], v[118:119], v[86:87], v[102:103]
	v_pk_fma_f32 v[120:121], v[120:121], v[88:89], v[104:105]
	v_pk_fma_f32 v[122:123], v[122:123], v[90:91], v[106:107]
	v_pk_fma_f32 v[124:125], v[124:125], v[92:93], v[108:109]
	v_pk_fma_f32 v[126:127], v[126:127], v[94:95], v[110:111]
	v_pk_fma_f32 v[128:129], v[128:129], v[96:97], v[112:113]
	v_pk_fma_f32 v[130:131], v[130:131], v[98:99], v[114:115]
	v_cvt_pk_bf16_f32 v172, v116, v117
	v_cvt_pk_bf16_f32 v173, v118, v119
	v_cvt_pk_bf16_f32 v174, v120, v121
	v_cvt_pk_bf16_f32 v175, v122, v123
	v_cvt_pk_bf16_f32 v176, v124, v125
	v_cvt_pk_bf16_f32 v177, v126, v127
	v_cvt_pk_bf16_f32 v178, v128, v129
	v_cvt_pk_bf16_f32 v179, v130, v131
	global_store_dwordx4 v51, v[172:175], s[26:27]
	global_store_dwordx4 v51, v[176:179], s[26:27] offset:1024
	v_lshlrev_b32_e32 v116, 16, v8
	v_and_b32_e32 v117, 0xffff0000, v8
	v_lshlrev_b32_e32 v118, 16, v9
	v_and_b32_e32 v119, 0xffff0000, v9
	v_lshlrev_b32_e32 v120, 16, v10
	v_and_b32_e32 v121, 0xffff0000, v10
	v_lshlrev_b32_e32 v122, 16, v11
	v_and_b32_e32 v123, 0xffff0000, v11
	v_lshlrev_b32_e32 v124, 16, v12
	v_and_b32_e32 v125, 0xffff0000, v12
	v_lshlrev_b32_e32 v126, 16, v13
	v_and_b32_e32 v127, 0xffff0000, v13
	v_lshlrev_b32_e32 v128, 16, v14
	v_and_b32_e32 v129, 0xffff0000, v14
	v_lshlrev_b32_e32 v130, 16, v15
	v_and_b32_e32 v131, 0xffff0000, v15
	v_pk_mul_f32 v[116:117], v[142:143], v[116:117] op_sel_hi:[0,1]
	v_pk_mul_f32 v[118:119], v[142:143], v[118:119] op_sel_hi:[0,1]
	v_pk_mul_f32 v[120:121], v[142:143], v[120:121] op_sel_hi:[0,1]
	v_pk_mul_f32 v[122:123], v[142:143], v[122:123] op_sel_hi:[0,1]
	v_pk_mul_f32 v[124:125], v[142:143], v[124:125] op_sel_hi:[0,1]
	v_pk_mul_f32 v[126:127], v[142:143], v[126:127] op_sel_hi:[0,1]
	v_pk_mul_f32 v[128:129], v[142:143], v[128:129] op_sel_hi:[0,1]
	v_pk_mul_f32 v[130:131], v[142:143], v[130:131] op_sel_hi:[0,1]
	v_pk_mul_f32 v[116:117], v[116:117], v[32:33]
	v_pk_mul_f32 v[118:119], v[118:119], v[34:35]
	v_pk_mul_f32 v[120:121], v[120:121], v[36:37]
	v_pk_mul_f32 v[122:123], v[122:123], v[38:39]
	v_pk_mul_f32 v[124:125], v[124:125], v[40:41]
	v_pk_mul_f32 v[126:127], v[126:127], v[42:43]
	v_pk_mul_f32 v[128:129], v[128:129], v[44:45]
	v_pk_mul_f32 v[130:131], v[130:131], v[46:47]
	v_pk_fma_f32 v[116:117], v[116:117], v[84:85], v[100:101]
	v_pk_fma_f32 v[118:119], v[118:119], v[86:87], v[102:103]
	v_pk_fma_f32 v[120:121], v[120:121], v[88:89], v[104:105]
	v_pk_fma_f32 v[122:123], v[122:123], v[90:91], v[106:107]
	v_pk_fma_f32 v[124:125], v[124:125], v[92:93], v[108:109]
	v_pk_fma_f32 v[126:127], v[126:127], v[94:95], v[110:111]
	v_pk_fma_f32 v[128:129], v[128:129], v[96:97], v[112:113]
	v_pk_fma_f32 v[130:131], v[130:131], v[98:99], v[114:115]
	v_cvt_pk_bf16_f32 v164, v116, v117
	v_cvt_pk_bf16_f32 v165, v118, v119
	v_cvt_pk_bf16_f32 v166, v120, v121
	v_cvt_pk_bf16_f32 v167, v122, v123
	v_cvt_pk_bf16_f32 v168, v124, v125
	v_cvt_pk_bf16_f32 v169, v126, v127
	v_cvt_pk_bf16_f32 v170, v128, v129
	v_cvt_pk_bf16_f32 v171, v130, v131
	global_store_dwordx4 v51, v[164:167], s[26:27] offset:2048
	global_store_dwordx4 v51, v[168:171], s[26:27] offset:3072
	v_lshlrev_b32_e32 v116, 16, v16
	v_and_b32_e32 v117, 0xffff0000, v16
	v_lshlrev_b32_e32 v118, 16, v17
	v_and_b32_e32 v119, 0xffff0000, v17
	v_lshlrev_b32_e32 v120, 16, v18
	v_and_b32_e32 v121, 0xffff0000, v18
	v_lshlrev_b32_e32 v122, 16, v19
	v_and_b32_e32 v123, 0xffff0000, v19
	v_lshlrev_b32_e32 v124, 16, v20
	v_and_b32_e32 v125, 0xffff0000, v20
	v_lshlrev_b32_e32 v126, 16, v21
	v_and_b32_e32 v127, 0xffff0000, v21
	v_lshlrev_b32_e32 v128, 16, v22
	v_and_b32_e32 v129, 0xffff0000, v22
	v_lshlrev_b32_e32 v130, 16, v23
	v_and_b32_e32 v131, 0xffff0000, v23
	v_pk_mul_f32 v[116:117], v[144:145], v[116:117] op_sel_hi:[0,1]
	v_pk_mul_f32 v[118:119], v[144:145], v[118:119] op_sel_hi:[0,1]
	v_pk_mul_f32 v[120:121], v[144:145], v[120:121] op_sel_hi:[0,1]
	v_pk_mul_f32 v[122:123], v[144:145], v[122:123] op_sel_hi:[0,1]
	v_pk_mul_f32 v[124:125], v[144:145], v[124:125] op_sel_hi:[0,1]
	v_pk_mul_f32 v[126:127], v[144:145], v[126:127] op_sel_hi:[0,1]
	v_pk_mul_f32 v[128:129], v[144:145], v[128:129] op_sel_hi:[0,1]
	v_pk_mul_f32 v[130:131], v[144:145], v[130:131] op_sel_hi:[0,1]
	v_pk_mul_f32 v[116:117], v[116:117], v[32:33]
	v_pk_mul_f32 v[118:119], v[118:119], v[34:35]
	v_pk_mul_f32 v[120:121], v[120:121], v[36:37]
	v_pk_mul_f32 v[122:123], v[122:123], v[38:39]
	v_pk_mul_f32 v[124:125], v[124:125], v[40:41]
	v_pk_mul_f32 v[126:127], v[126:127], v[42:43]
	v_pk_mul_f32 v[128:129], v[128:129], v[44:45]
	v_pk_mul_f32 v[130:131], v[130:131], v[46:47]
	v_pk_fma_f32 v[116:117], v[116:117], v[84:85], v[100:101]
	v_pk_fma_f32 v[118:119], v[118:119], v[86:87], v[102:103]
	v_pk_fma_f32 v[120:121], v[120:121], v[88:89], v[104:105]
	v_pk_fma_f32 v[122:123], v[122:123], v[90:91], v[106:107]
	v_pk_fma_f32 v[124:125], v[124:125], v[92:93], v[108:109]
	v_pk_fma_f32 v[126:127], v[126:127], v[94:95], v[110:111]
	v_pk_fma_f32 v[128:129], v[128:129], v[96:97], v[112:113]
	v_pk_fma_f32 v[130:131], v[130:131], v[98:99], v[114:115]
	v_cvt_pk_bf16_f32 v172, v116, v117
	v_cvt_pk_bf16_f32 v173, v118, v119
	v_cvt_pk_bf16_f32 v174, v120, v121
	v_cvt_pk_bf16_f32 v175, v122, v123
	v_cvt_pk_bf16_f32 v176, v124, v125
	v_cvt_pk_bf16_f32 v177, v126, v127
	v_cvt_pk_bf16_f32 v178, v128, v129
	v_cvt_pk_bf16_f32 v179, v130, v131
	global_store_dwordx4 v149, v[172:175], s[26:27]
	global_store_dwordx4 v149, v[176:179], s[26:27] offset:1024
	v_lshlrev_b32_e32 v116, 16, v24
	v_and_b32_e32 v117, 0xffff0000, v24
	v_lshlrev_b32_e32 v118, 16, v25
	v_and_b32_e32 v119, 0xffff0000, v25
	v_lshlrev_b32_e32 v120, 16, v26
	v_and_b32_e32 v121, 0xffff0000, v26
	v_lshlrev_b32_e32 v122, 16, v27
	v_and_b32_e32 v123, 0xffff0000, v27
	v_lshlrev_b32_e32 v124, 16, v28
	v_and_b32_e32 v125, 0xffff0000, v28
	v_lshlrev_b32_e32 v126, 16, v29
	v_and_b32_e32 v127, 0xffff0000, v29
	v_lshlrev_b32_e32 v128, 16, v30
	v_and_b32_e32 v129, 0xffff0000, v30
	v_lshlrev_b32_e32 v130, 16, v31
	v_and_b32_e32 v131, 0xffff0000, v31
	v_pk_mul_f32 v[116:117], v[146:147], v[116:117] op_sel_hi:[0,1]
	v_pk_mul_f32 v[118:119], v[146:147], v[118:119] op_sel_hi:[0,1]
	v_pk_mul_f32 v[120:121], v[146:147], v[120:121] op_sel_hi:[0,1]
	v_pk_mul_f32 v[122:123], v[146:147], v[122:123] op_sel_hi:[0,1]
	v_pk_mul_f32 v[124:125], v[146:147], v[124:125] op_sel_hi:[0,1]
	v_pk_mul_f32 v[126:127], v[146:147], v[126:127] op_sel_hi:[0,1]
	v_pk_mul_f32 v[128:129], v[146:147], v[128:129] op_sel_hi:[0,1]
	v_pk_mul_f32 v[130:131], v[146:147], v[130:131] op_sel_hi:[0,1]
	v_pk_mul_f32 v[116:117], v[116:117], v[32:33]
	v_pk_mul_f32 v[118:119], v[118:119], v[34:35]
	v_pk_mul_f32 v[120:121], v[120:121], v[36:37]
	v_pk_mul_f32 v[122:123], v[122:123], v[38:39]
	v_pk_mul_f32 v[124:125], v[124:125], v[40:41]
	v_pk_mul_f32 v[126:127], v[126:127], v[42:43]
	v_pk_mul_f32 v[128:129], v[128:129], v[44:45]
	v_pk_mul_f32 v[130:131], v[130:131], v[46:47]
	v_pk_fma_f32 v[116:117], v[116:117], v[84:85], v[100:101]
	v_pk_fma_f32 v[118:119], v[118:119], v[86:87], v[102:103]
	v_pk_fma_f32 v[120:121], v[120:121], v[88:89], v[104:105]
	v_pk_fma_f32 v[122:123], v[122:123], v[90:91], v[106:107]
	v_pk_fma_f32 v[124:125], v[124:125], v[92:93], v[108:109]
	v_pk_fma_f32 v[126:127], v[126:127], v[94:95], v[110:111]
	v_pk_fma_f32 v[128:129], v[128:129], v[96:97], v[112:113]
	v_pk_fma_f32 v[130:131], v[130:131], v[98:99], v[114:115]
	v_cvt_pk_bf16_f32 v164, v116, v117
	v_cvt_pk_bf16_f32 v165, v118, v119
	v_cvt_pk_bf16_f32 v166, v120, v121
	v_cvt_pk_bf16_f32 v167, v122, v123
	v_cvt_pk_bf16_f32 v168, v124, v125
	v_cvt_pk_bf16_f32 v169, v126, v127
	v_cvt_pk_bf16_f32 v170, v128, v129
	v_cvt_pk_bf16_f32 v171, v130, v131
	global_store_dwordx4 v149, v[164:167], s[26:27] offset:2048
	global_store_dwordx4 v149, v[168:171], s[26:27] offset:3072
	s_add_u32 s26, s26, 0x2000
	s_addc_u32 s27, s27, 0
	s_add_u32 s24, s24, 0x2000
	s_addc_u32 s25, s25, 0
	global_load_dwordx4 v[0:3], v51, s[24:25]
	global_load_dwordx4 v[4:7], v51, s[24:25] offset:1024
	global_load_dwordx4 v[8:11], v51, s[24:25] offset:2048
	global_load_dwordx4 v[12:15], v51, s[24:25] offset:3072
	global_load_dwordx4 v[16:19], v149, s[24:25]
	global_load_dwordx4 v[20:23], v149, s[24:25] offset:1024
	global_load_dwordx4 v[24:27], v149, s[24:25] offset:2048
	global_load_dwordx4 v[28:31], v149, s[24:25] offset:3072
	s_waitcnt vmcnt(16)
	v_lshlrev_b32_e32 v116, 16, v52
	v_and_b32_e32 v117, 0xffff0000, v52
	v_lshlrev_b32_e32 v118, 16, v53
	v_and_b32_e32 v119, 0xffff0000, v53
	v_lshlrev_b32_e32 v120, 16, v54
	v_and_b32_e32 v121, 0xffff0000, v54
	v_lshlrev_b32_e32 v122, 16, v55
	v_and_b32_e32 v123, 0xffff0000, v55
	v_lshlrev_b32_e32 v124, 16, v56
	v_and_b32_e32 v125, 0xffff0000, v56
	v_lshlrev_b32_e32 v126, 16, v57
	v_and_b32_e32 v127, 0xffff0000, v57
	v_lshlrev_b32_e32 v128, 16, v58
	v_and_b32_e32 v129, 0xffff0000, v58
	v_lshlrev_b32_e32 v130, 16, v59
	v_and_b32_e32 v131, 0xffff0000, v59
	v_pk_mul_f32 v[132:133], v[116:117], v[116:117]
	v_pk_fma_f32 v[132:133], v[118:119], v[118:119], v[132:133]
	v_pk_fma_f32 v[132:133], v[120:121], v[120:121], v[132:133]
	v_pk_fma_f32 v[132:133], v[122:123], v[122:123], v[132:133]
	v_pk_fma_f32 v[132:133], v[124:125], v[124:125], v[132:133]
	v_pk_fma_f32 v[132:133], v[126:127], v[126:127], v[132:133]
	v_pk_fma_f32 v[132:133], v[128:129], v[128:129], v[132:133]
	v_pk_fma_f32 v[132:133], v[130:131], v[130:131], v[132:133]
	v_lshlrev_b32_e32 v116, 16, v60
	v_and_b32_e32 v117, 0xffff0000, v60
	v_lshlrev_b32_e32 v118, 16, v61
	v_and_b32_e32 v119, 0xffff0000, v61
	v_lshlrev_b32_e32 v120, 16, v62
	v_and_b32_e32 v121, 0xffff0000, v62
	v_lshlrev_b32_e32 v122, 16, v63
	v_and_b32_e32 v123, 0xffff0000, v63
	v_lshlrev_b32_e32 v124, 16, v64
	v_and_b32_e32 v125, 0xffff0000, v64
	v_lshlrev_b32_e32 v126, 16, v65
	v_and_b32_e32 v127, 0xffff0000, v65
	v_lshlrev_b32_e32 v128, 16, v66
	v_and_b32_e32 v129, 0xffff0000, v66
	v_lshlrev_b32_e32 v130, 16, v67
	v_and_b32_e32 v131, 0xffff0000, v67
	v_pk_mul_f32 v[134:135], v[116:117], v[116:117]
	v_pk_fma_f32 v[134:135], v[118:119], v[118:119], v[134:135]
	v_pk_fma_f32 v[134:135], v[120:121], v[120:121], v[134:135]
	v_pk_fma_f32 v[134:135], v[122:123], v[122:123], v[134:135]
	v_pk_fma_f32 v[134:135], v[124:125], v[124:125], v[134:135]
	v_pk_fma_f32 v[134:135], v[126:127], v[126:127], v[134:135]
	v_pk_fma_f32 v[134:135], v[128:129], v[128:129], v[134:135]
	v_pk_fma_f32 v[134:135], v[130:131], v[130:131], v[134:135]
	v_lshlrev_b32_e32 v116, 16, v68
	v_and_b32_e32 v117, 0xffff0000, v68
	v_lshlrev_b32_e32 v118, 16, v69
	v_and_b32_e32 v119, 0xffff0000, v69
	v_lshlrev_b32_e32 v120, 16, v70
	v_and_b32_e32 v121, 0xffff0000, v70
	v_lshlrev_b32_e32 v122, 16, v71
	v_and_b32_e32 v123, 0xffff0000, v71
	v_lshlrev_b32_e32 v124, 16, v72
	v_and_b32_e32 v125, 0xffff0000, v72
	v_lshlrev_b32_e32 v126, 16, v73
	v_and_b32_e32 v127, 0xffff0000, v73
	v_lshlrev_b32_e32 v128, 16, v74
	v_and_b32_e32 v129, 0xffff0000, v74
	v_lshlrev_b32_e32 v130, 16, v75
	v_and_b32_e32 v131, 0xffff0000, v75
	v_pk_mul_f32 v[136:137], v[116:117], v[116:117]
	v_pk_fma_f32 v[136:137], v[118:119], v[118:119], v[136:137]
	v_pk_fma_f32 v[136:137], v[120:121], v[120:121], v[136:137]
	v_pk_fma_f32 v[136:137], v[122:123], v[122:123], v[136:137]
	v_pk_fma_f32 v[136:137], v[124:125], v[124:125], v[136:137]
	v_pk_fma_f32 v[136:137], v[126:127], v[126:127], v[136:137]
	v_pk_fma_f32 v[136:137], v[128:129], v[128:129], v[136:137]
	v_pk_fma_f32 v[136:137], v[130:131], v[130:131], v[136:137]
	v_lshlrev_b32_e32 v116, 16, v76
	v_and_b32_e32 v117, 0xffff0000, v76
	v_lshlrev_b32_e32 v118, 16, v77
	v_and_b32_e32 v119, 0xffff0000, v77
	v_lshlrev_b32_e32 v120, 16, v78
	v_and_b32_e32 v121, 0xffff0000, v78
	v_lshlrev_b32_e32 v122, 16, v79
	v_and_b32_e32 v123, 0xffff0000, v79
	v_lshlrev_b32_e32 v124, 16, v80
	v_and_b32_e32 v125, 0xffff0000, v80
	v_lshlrev_b32_e32 v126, 16, v81
	v_and_b32_e32 v127, 0xffff0000, v81
	v_lshlrev_b32_e32 v128, 16, v82
	v_and_b32_e32 v129, 0xffff0000, v82
	v_lshlrev_b32_e32 v130, 16, v83
	v_and_b32_e32 v131, 0xffff0000, v83
	v_pk_mul_f32 v[138:139], v[116:117], v[116:117]
	v_pk_fma_f32 v[138:139], v[118:119], v[118:119], v[138:139]
	v_pk_fma_f32 v[138:139], v[120:121], v[120:121], v[138:139]
	v_pk_fma_f32 v[138:139], v[122:123], v[122:123], v[138:139]
	v_pk_fma_f32 v[138:139], v[124:125], v[124:125], v[138:139]
	v_pk_fma_f32 v[138:139], v[126:127], v[126:127], v[138:139]
	v_pk_fma_f32 v[138:139], v[128:129], v[128:129], v[138:139]
	v_pk_fma_f32 v[138:139], v[130:131], v[130:131], v[138:139]
	v_add_f32_e32 v132, v132, v133
	v_add_f32_e32 v134, v134, v135
	v_add_f32_e32 v136, v136, v137
	v_add_f32_e32 v138, v138, v139
	s_nop 1
	v_add_f32_dpp v132, v132, v132 row_shr:1 row_mask:0xf bank_mask:0xf bound_ctrl:1
	v_add_f32_dpp v134, v134, v134 row_shr:1 row_mask:0xf bank_mask:0xf bound_ctrl:1
	v_add_f32_dpp v136, v136, v136 row_shr:1 row_mask:0xf bank_mask:0xf bound_ctrl:1
	v_add_f32_dpp v138, v138, v138 row_shr:1 row_mask:0xf bank_mask:0xf bound_ctrl:1
	v_add_f32_dpp v132, v132, v132 row_shr:2 row_mask:0xf bank_mask:0xf bound_ctrl:1
	v_add_f32_dpp v134, v134, v134 row_shr:2 row_mask:0xf bank_mask:0xf bound_ctrl:1
	v_add_f32_dpp v136, v136, v136 row_shr:2 row_mask:0xf bank_mask:0xf bound_ctrl:1
	v_add_f32_dpp v138, v138, v138 row_shr:2 row_mask:0xf bank_mask:0xf bound_ctrl:1
	v_add_f32_dpp v132, v132, v132 row_shr:4 row_mask:0xf bank_mask:0xf bound_ctrl:1
	v_add_f32_dpp v134, v134, v134 row_shr:4 row_mask:0xf bank_mask:0xf bound_ctrl:1
	v_add_f32_dpp v136, v136, v136 row_shr:4 row_mask:0xf bank_mask:0xf bound_ctrl:1
	v_add_f32_dpp v138, v138, v138 row_shr:4 row_mask:0xf bank_mask:0xf bound_ctrl:1
	v_add_f32_dpp v132, v132, v132 row_shr:8 row_mask:0xf bank_mask:0xf bound_ctrl:1
	v_add_f32_dpp v134, v134, v134 row_shr:8 row_mask:0xf bank_mask:0xf bound_ctrl:1
	v_add_f32_dpp v136, v136, v136 row_shr:8 row_mask:0xf bank_mask:0xf bound_ctrl:1
	v_add_f32_dpp v138, v138, v138 row_shr:8 row_mask:0xf bank_mask:0xf bound_ctrl:1
	v_add_f32_dpp v132, v132, v132 row_bcast:15 row_mask:0xa bank_mask:0xf
	v_add_f32_dpp v134, v134, v134 row_bcast:15 row_mask:0xa bank_mask:0xf
	v_add_f32_dpp v136, v136, v136 row_bcast:15 row_mask:0xa bank_mask:0xf
	v_add_f32_dpp v138, v138, v138 row_bcast:15 row_mask:0xa bank_mask:0xf
	v_add_f32_dpp v132, v132, v132 row_bcast:31 row_mask:0xc bank_mask:0xf
	v_add_f32_dpp v134, v134, v134 row_bcast:31 row_mask:0xc bank_mask:0xf
	v_add_f32_dpp v136, v136, v136 row_bcast:31 row_mask:0xc bank_mask:0xf
	v_add_f32_dpp v138, v138, v138 row_bcast:31 row_mask:0xc bank_mask:0xf
	s_nop 1
	v_readlane_b32 s32, v132, 63
	v_readlane_b32 s28, v134, 63
	v_readlane_b32 s29, v136, 63
	v_readlane_b32 s30, v138, 63
	s_nop 1
	v_mov_b32_e32 v140, s32
	v_mov_b32_e32 v142, s28
	v_mov_b32_e32 v144, s29
	v_mov_b32_e32 v146, s30
	v_fmaak_f32 v140, v140, v50, 0x358637bd
	v_fmaak_f32 v142, v142, v50, 0x358637bd
	v_fmaak_f32 v144, v144, v50, 0x358637bd
	v_fmaak_f32 v146, v146, v50, 0x358637bd
	v_rsq_f32_e32 v140, v140
	v_rsq_f32_e32 v142, v142
	v_rsq_f32_e32 v144, v144
	v_rsq_f32_e32 v146, v146
	s_nop 0
	v_lshlrev_b32_e32 v116, 16, v52
	v_and_b32_e32 v117, 0xffff0000, v52
	v_lshlrev_b32_e32 v118, 16, v53
	v_and_b32_e32 v119, 0xffff0000, v53
	v_lshlrev_b32_e32 v120, 16, v54
	v_and_b32_e32 v121, 0xffff0000, v54
	v_lshlrev_b32_e32 v122, 16, v55
	v_and_b32_e32 v123, 0xffff0000, v55
	v_lshlrev_b32_e32 v124, 16, v56
	v_and_b32_e32 v125, 0xffff0000, v56
	v_lshlrev_b32_e32 v126, 16, v57
	v_and_b32_e32 v127, 0xffff0000, v57
	v_lshlrev_b32_e32 v128, 16, v58
	v_and_b32_e32 v129, 0xffff0000, v58
	v_lshlrev_b32_e32 v130, 16, v59
	v_and_b32_e32 v131, 0xffff0000, v59
	v_pk_mul_f32 v[116:117], v[140:141], v[116:117] op_sel_hi:[0,1]
	v_pk_mul_f32 v[118:119], v[140:141], v[118:119] op_sel_hi:[0,1]
	v_pk_mul_f32 v[120:121], v[140:141], v[120:121] op_sel_hi:[0,1]
	v_pk_mul_f32 v[122:123], v[140:141], v[122:123] op_sel_hi:[0,1]
	v_pk_mul_f32 v[124:125], v[140:141], v[124:125] op_sel_hi:[0,1]
	v_pk_mul_f32 v[126:127], v[140:141], v[126:127] op_sel_hi:[0,1]
	v_pk_mul_f32 v[128:129], v[140:141], v[128:129] op_sel_hi:[0,1]
	v_pk_mul_f32 v[130:131], v[140:141], v[130:131] op_sel_hi:[0,1]
	v_pk_mul_f32 v[116:117], v[116:117], v[32:33]
	v_pk_mul_f32 v[118:119], v[118:119], v[34:35]
	v_pk_mul_f32 v[120:121], v[120:121], v[36:37]
	v_pk_mul_f32 v[122:123], v[122:123], v[38:39]
	v_pk_mul_f32 v[124:125], v[124:125], v[40:41]
	v_pk_mul_f32 v[126:127], v[126:127], v[42:43]
	v_pk_mul_f32 v[128:129], v[128:129], v[44:45]
	v_pk_mul_f32 v[130:131], v[130:131], v[46:47]
	v_pk_fma_f32 v[116:117], v[116:117], v[84:85], v[100:101]
	v_pk_fma_f32 v[118:119], v[118:119], v[86:87], v[102:103]
	v_pk_fma_f32 v[120:121], v[120:121], v[88:89], v[104:105]
	v_pk_fma_f32 v[122:123], v[122:123], v[90:91], v[106:107]
	v_pk_fma_f32 v[124:125], v[124:125], v[92:93], v[108:109]
	v_pk_fma_f32 v[126:127], v[126:127], v[94:95], v[110:111]
	v_pk_fma_f32 v[128:129], v[128:129], v[96:97], v[112:113]
	v_pk_fma_f32 v[130:131], v[130:131], v[98:99], v[114:115]
	v_cvt_pk_bf16_f32 v164, v116, v117
	v_cvt_pk_bf16_f32 v165, v118, v119
	v_cvt_pk_bf16_f32 v166, v120, v121
	v_cvt_pk_bf16_f32 v167, v122, v123
	v_cvt_pk_bf16_f32 v168, v124, v125
	v_cvt_pk_bf16_f32 v169, v126, v127
	v_cvt_pk_bf16_f32 v170, v128, v129
	v_cvt_pk_bf16_f32 v171, v130, v131
	global_store_dwordx4 v51, v[164:167], s[26:27]
	global_store_dwordx4 v51, v[168:171], s[26:27] offset:1024
	v_lshlrev_b32_e32 v116, 16, v60
	v_and_b32_e32 v117, 0xffff0000, v60
	v_lshlrev_b32_e32 v118, 16, v61
	v_and_b32_e32 v119, 0xffff0000, v61
	v_lshlrev_b32_e32 v120, 16, v62
	v_and_b32_e32 v121, 0xffff0000, v62
	v_lshlrev_b32_e32 v122, 16, v63
	v_and_b32_e32 v123, 0xffff0000, v63
	v_lshlrev_b32_e32 v124, 16, v64
	v_and_b32_e32 v125, 0xffff0000, v64
	v_lshlrev_b32_e32 v126, 16, v65
	v_and_b32_e32 v127, 0xffff0000, v65
	v_lshlrev_b32_e32 v128, 16, v66
	v_and_b32_e32 v129, 0xffff0000, v66
	v_lshlrev_b32_e32 v130, 16, v67
	v_and_b32_e32 v131, 0xffff0000, v67
	v_pk_mul_f32 v[116:117], v[142:143], v[116:117] op_sel_hi:[0,1]
	v_pk_mul_f32 v[118:119], v[142:143], v[118:119] op_sel_hi:[0,1]
	v_pk_mul_f32 v[120:121], v[142:143], v[120:121] op_sel_hi:[0,1]
	v_pk_mul_f32 v[122:123], v[142:143], v[122:123] op_sel_hi:[0,1]
	v_pk_mul_f32 v[124:125], v[142:143], v[124:125] op_sel_hi:[0,1]
	v_pk_mul_f32 v[126:127], v[142:143], v[126:127] op_sel_hi:[0,1]
	v_pk_mul_f32 v[128:129], v[142:143], v[128:129] op_sel_hi:[0,1]
	v_pk_mul_f32 v[130:131], v[142:143], v[130:131] op_sel_hi:[0,1]
	v_pk_mul_f32 v[116:117], v[116:117], v[32:33]
	v_pk_mul_f32 v[118:119], v[118:119], v[34:35]
	v_pk_mul_f32 v[120:121], v[120:121], v[36:37]
	v_pk_mul_f32 v[122:123], v[122:123], v[38:39]
	v_pk_mul_f32 v[124:125], v[124:125], v[40:41]
	v_pk_mul_f32 v[126:127], v[126:127], v[42:43]
	v_pk_mul_f32 v[128:129], v[128:129], v[44:45]
	v_pk_mul_f32 v[130:131], v[130:131], v[46:47]
	v_pk_fma_f32 v[116:117], v[116:117], v[84:85], v[100:101]
	v_pk_fma_f32 v[118:119], v[118:119], v[86:87], v[102:103]
	v_pk_fma_f32 v[120:121], v[120:121], v[88:89], v[104:105]
	v_pk_fma_f32 v[122:123], v[122:123], v[90:91], v[106:107]
	v_pk_fma_f32 v[124:125], v[124:125], v[92:93], v[108:109]
	v_pk_fma_f32 v[126:127], v[126:127], v[94:95], v[110:111]
	v_pk_fma_f32 v[128:129], v[128:129], v[96:97], v[112:113]
	v_pk_fma_f32 v[130:131], v[130:131], v[98:99], v[114:115]
	v_cvt_pk_bf16_f32 v172, v116, v117
	v_cvt_pk_bf16_f32 v173, v118, v119
	v_cvt_pk_bf16_f32 v174, v120, v121
	v_cvt_pk_bf16_f32 v175, v122, v123
	v_cvt_pk_bf16_f32 v176, v124, v125
	v_cvt_pk_bf16_f32 v177, v126, v127
	v_cvt_pk_bf16_f32 v178, v128, v129
	v_cvt_pk_bf16_f32 v179, v130, v131
	global_store_dwordx4 v51, v[172:175], s[26:27] offset:2048
	global_store_dwordx4 v51, v[176:179], s[26:27] offset:3072
	v_lshlrev_b32_e32 v116, 16, v68
	v_and_b32_e32 v117, 0xffff0000, v68
	v_lshlrev_b32_e32 v118, 16, v69
	v_and_b32_e32 v119, 0xffff0000, v69
	v_lshlrev_b32_e32 v120, 16, v70
	v_and_b32_e32 v121, 0xffff0000, v70
	v_lshlrev_b32_e32 v122, 16, v71
	v_and_b32_e32 v123, 0xffff0000, v71
	v_lshlrev_b32_e32 v124, 16, v72
	v_and_b32_e32 v125, 0xffff0000, v72
	v_lshlrev_b32_e32 v126, 16, v73
	v_and_b32_e32 v127, 0xffff0000, v73
	v_lshlrev_b32_e32 v128, 16, v74
	v_and_b32_e32 v129, 0xffff0000, v74
	v_lshlrev_b32_e32 v130, 16, v75
	v_and_b32_e32 v131, 0xffff0000, v75
	v_pk_mul_f32 v[116:117], v[144:145], v[116:117] op_sel_hi:[0,1]
	v_pk_mul_f32 v[118:119], v[144:145], v[118:119] op_sel_hi:[0,1]
	v_pk_mul_f32 v[120:121], v[144:145], v[120:121] op_sel_hi:[0,1]
	v_pk_mul_f32 v[122:123], v[144:145], v[122:123] op_sel_hi:[0,1]
	v_pk_mul_f32 v[124:125], v[144:145], v[124:125] op_sel_hi:[0,1]
	v_pk_mul_f32 v[126:127], v[144:145], v[126:127] op_sel_hi:[0,1]
	v_pk_mul_f32 v[128:129], v[144:145], v[128:129] op_sel_hi:[0,1]
	v_pk_mul_f32 v[130:131], v[144:145], v[130:131] op_sel_hi:[0,1]
	v_pk_mul_f32 v[116:117], v[116:117], v[32:33]
	v_pk_mul_f32 v[118:119], v[118:119], v[34:35]
	v_pk_mul_f32 v[120:121], v[120:121], v[36:37]
	v_pk_mul_f32 v[122:123], v[122:123], v[38:39]
	v_pk_mul_f32 v[124:125], v[124:125], v[40:41]
	v_pk_mul_f32 v[126:127], v[126:127], v[42:43]
	v_pk_mul_f32 v[128:129], v[128:129], v[44:45]
	v_pk_mul_f32 v[130:131], v[130:131], v[46:47]
	v_pk_fma_f32 v[116:117], v[116:117], v[84:85], v[100:101]
	v_pk_fma_f32 v[118:119], v[118:119], v[86:87], v[102:103]
	v_pk_fma_f32 v[120:121], v[120:121], v[88:89], v[104:105]
	v_pk_fma_f32 v[122:123], v[122:123], v[90:91], v[106:107]
	v_pk_fma_f32 v[124:125], v[124:125], v[92:93], v[108:109]
	v_pk_fma_f32 v[126:127], v[126:127], v[94:95], v[110:111]
	v_pk_fma_f32 v[128:129], v[128:129], v[96:97], v[112:113]
	v_pk_fma_f32 v[130:131], v[130:131], v[98:99], v[114:115]
	v_cvt_pk_bf16_f32 v164, v116, v117
	v_cvt_pk_bf16_f32 v165, v118, v119
	v_cvt_pk_bf16_f32 v166, v120, v121
	v_cvt_pk_bf16_f32 v167, v122, v123
	v_cvt_pk_bf16_f32 v168, v124, v125
	v_cvt_pk_bf16_f32 v169, v126, v127
	v_cvt_pk_bf16_f32 v170, v128, v129
	v_cvt_pk_bf16_f32 v171, v130, v131
	global_store_dwordx4 v149, v[164:167], s[26:27]
	global_store_dwordx4 v149, v[168:171], s[26:27] offset:1024
	v_lshlrev_b32_e32 v116, 16, v76
	v_and_b32_e32 v117, 0xffff0000, v76
	v_lshlrev_b32_e32 v118, 16, v77
	v_and_b32_e32 v119, 0xffff0000, v77
	v_lshlrev_b32_e32 v120, 16, v78
	v_and_b32_e32 v121, 0xffff0000, v78
	v_lshlrev_b32_e32 v122, 16, v79
	v_and_b32_e32 v123, 0xffff0000, v79
	v_lshlrev_b32_e32 v124, 16, v80
	v_and_b32_e32 v125, 0xffff0000, v80
	v_lshlrev_b32_e32 v126, 16, v81
	v_and_b32_e32 v127, 0xffff0000, v81
	v_lshlrev_b32_e32 v128, 16, v82
	v_and_b32_e32 v129, 0xffff0000, v82
	v_lshlrev_b32_e32 v130, 16, v83
	v_and_b32_e32 v131, 0xffff0000, v83
	v_pk_mul_f32 v[116:117], v[146:147], v[116:117] op_sel_hi:[0,1]
	v_pk_mul_f32 v[118:119], v[146:147], v[118:119] op_sel_hi:[0,1]
	v_pk_mul_f32 v[120:121], v[146:147], v[120:121] op_sel_hi:[0,1]
	v_pk_mul_f32 v[122:123], v[146:147], v[122:123] op_sel_hi:[0,1]
	v_pk_mul_f32 v[124:125], v[146:147], v[124:125] op_sel_hi:[0,1]
	v_pk_mul_f32 v[126:127], v[146:147], v[126:127] op_sel_hi:[0,1]
	v_pk_mul_f32 v[128:129], v[146:147], v[128:129] op_sel_hi:[0,1]
	v_pk_mul_f32 v[130:131], v[146:147], v[130:131] op_sel_hi:[0,1]
	v_pk_mul_f32 v[116:117], v[116:117], v[32:33]
	v_pk_mul_f32 v[118:119], v[118:119], v[34:35]
	v_pk_mul_f32 v[120:121], v[120:121], v[36:37]
	v_pk_mul_f32 v[122:123], v[122:123], v[38:39]
	v_pk_mul_f32 v[124:125], v[124:125], v[40:41]
	v_pk_mul_f32 v[126:127], v[126:127], v[42:43]
	v_pk_mul_f32 v[128:129], v[128:129], v[44:45]
	v_pk_mul_f32 v[130:131], v[130:131], v[46:47]
	v_pk_fma_f32 v[116:117], v[116:117], v[84:85], v[100:101]
	v_pk_fma_f32 v[118:119], v[118:119], v[86:87], v[102:103]
	v_pk_fma_f32 v[120:121], v[120:121], v[88:89], v[104:105]
	v_pk_fma_f32 v[122:123], v[122:123], v[90:91], v[106:107]
	v_pk_fma_f32 v[124:125], v[124:125], v[92:93], v[108:109]
	v_pk_fma_f32 v[126:127], v[126:127], v[94:95], v[110:111]
	v_pk_fma_f32 v[128:129], v[128:129], v[96:97], v[112:113]
	v_pk_fma_f32 v[130:131], v[130:131], v[98:99], v[114:115]
	v_cvt_pk_bf16_f32 v172, v116, v117
	v_cvt_pk_bf16_f32 v173, v118, v119
	v_cvt_pk_bf16_f32 v174, v120, v121
	v_cvt_pk_bf16_f32 v175, v122, v123
	v_cvt_pk_bf16_f32 v176, v124, v125
	v_cvt_pk_bf16_f32 v177, v126, v127
	v_cvt_pk_bf16_f32 v178, v128, v129
	v_cvt_pk_bf16_f32 v179, v130, v131
	global_store_dwordx4 v149, v[172:175], s[26:27] offset:2048
	global_store_dwordx4 v149, v[176:179], s[26:27] offset:3072
	s_add_u32 s26, s26, 0x2000
	s_addc_u32 s27, s27, 0
	s_add_u32 s24, s24, 0x2000
	s_addc_u32 s25, s25, 0
	global_load_dwordx4 v[52:55], v51, s[24:25]
	global_load_dwordx4 v[56:59], v51, s[24:25] offset:1024
	global_load_dwordx4 v[60:63], v51, s[24:25] offset:2048
	global_load_dwordx4 v[64:67], v51, s[24:25] offset:3072
	global_load_dwordx4 v[68:71], v149, s[24:25]
	global_load_dwordx4 v[72:75], v149, s[24:25] offset:1024
	global_load_dwordx4 v[76:79], v149, s[24:25] offset:2048
	global_load_dwordx4 v[80:83], v149, s[24:25] offset:3072
	s_waitcnt vmcnt(16)
	v_lshlrev_b32_e32 v116, 16, v0
	v_and_b32_e32 v117, 0xffff0000, v0
	v_lshlrev_b32_e32 v118, 16, v1
	v_and_b32_e32 v119, 0xffff0000, v1
	v_lshlrev_b32_e32 v120, 16, v2
	v_and_b32_e32 v121, 0xffff0000, v2
	v_lshlrev_b32_e32 v122, 16, v3
	v_and_b32_e32 v123, 0xffff0000, v3
	v_lshlrev_b32_e32 v124, 16, v4
	v_and_b32_e32 v125, 0xffff0000, v4
	v_lshlrev_b32_e32 v126, 16, v5
	v_and_b32_e32 v127, 0xffff0000, v5
	v_lshlrev_b32_e32 v128, 16, v6
	v_and_b32_e32 v129, 0xffff0000, v6
	v_lshlrev_b32_e32 v130, 16, v7
	v_and_b32_e32 v131, 0xffff0000, v7
	v_pk_mul_f32 v[132:133], v[116:117], v[116:117]
	v_pk_fma_f32 v[132:133], v[118:119], v[118:119], v[132:133]
	v_pk_fma_f32 v[132:133], v[120:121], v[120:121], v[132:133]
	v_pk_fma_f32 v[132:133], v[122:123], v[122:123], v[132:133]
	v_pk_fma_f32 v[132:133], v[124:125], v[124:125], v[132:133]
	v_pk_fma_f32 v[132:133], v[126:127], v[126:127], v[132:133]
	v_pk_fma_f32 v[132:133], v[128:129], v[128:129], v[132:133]
	v_pk_fma_f32 v[132:133], v[130:131], v[130:131], v[132:133]
	v_lshlrev_b32_e32 v116, 16, v8
	v_and_b32_e32 v117, 0xffff0000, v8
	v_lshlrev_b32_e32 v118, 16, v9
	v_and_b32_e32 v119, 0xffff0000, v9
	v_lshlrev_b32_e32 v120, 16, v10
	v_and_b32_e32 v121, 0xffff0000, v10
	v_lshlrev_b32_e32 v122, 16, v11
	v_and_b32_e32 v123, 0xffff0000, v11
	v_lshlrev_b32_e32 v124, 16, v12
	v_and_b32_e32 v125, 0xffff0000, v12
	v_lshlrev_b32_e32 v126, 16, v13
	v_and_b32_e32 v127, 0xffff0000, v13
	v_lshlrev_b32_e32 v128, 16, v14
	v_and_b32_e32 v129, 0xffff0000, v14
	v_lshlrev_b32_e32 v130, 16, v15
	v_and_b32_e32 v131, 0xffff0000, v15
	v_pk_mul_f32 v[134:135], v[116:117], v[116:117]
	v_pk_fma_f32 v[134:135], v[118:119], v[118:119], v[134:135]
	v_pk_fma_f32 v[134:135], v[120:121], v[120:121], v[134:135]
	v_pk_fma_f32 v[134:135], v[122:123], v[122:123], v[134:135]
	v_pk_fma_f32 v[134:135], v[124:125], v[124:125], v[134:135]
	v_pk_fma_f32 v[134:135], v[126:127], v[126:127], v[134:135]
	v_pk_fma_f32 v[134:135], v[128:129], v[128:129], v[134:135]
	v_pk_fma_f32 v[134:135], v[130:131], v[130:131], v[134:135]
	v_lshlrev_b32_e32 v116, 16, v16
	v_and_b32_e32 v117, 0xffff0000, v16
	v_lshlrev_b32_e32 v118, 16, v17
	v_and_b32_e32 v119, 0xffff0000, v17
	v_lshlrev_b32_e32 v120, 16, v18
	v_and_b32_e32 v121, 0xffff0000, v18
	v_lshlrev_b32_e32 v122, 16, v19
	v_and_b32_e32 v123, 0xffff0000, v19
	v_lshlrev_b32_e32 v124, 16, v20
	v_and_b32_e32 v125, 0xffff0000, v20
	v_lshlrev_b32_e32 v126, 16, v21
	v_and_b32_e32 v127, 0xffff0000, v21
	v_lshlrev_b32_e32 v128, 16, v22
	v_and_b32_e32 v129, 0xffff0000, v22
	v_lshlrev_b32_e32 v130, 16, v23
	v_and_b32_e32 v131, 0xffff0000, v23
	v_pk_mul_f32 v[136:137], v[116:117], v[116:117]
	v_pk_fma_f32 v[136:137], v[118:119], v[118:119], v[136:137]
	v_pk_fma_f32 v[136:137], v[120:121], v[120:121], v[136:137]
	v_pk_fma_f32 v[136:137], v[122:123], v[122:123], v[136:137]
	v_pk_fma_f32 v[136:137], v[124:125], v[124:125], v[136:137]
	v_pk_fma_f32 v[136:137], v[126:127], v[126:127], v[136:137]
	v_pk_fma_f32 v[136:137], v[128:129], v[128:129], v[136:137]
	v_pk_fma_f32 v[136:137], v[130:131], v[130:131], v[136:137]
	v_lshlrev_b32_e32 v116, 16, v24
	v_and_b32_e32 v117, 0xffff0000, v24
	v_lshlrev_b32_e32 v118, 16, v25
	v_and_b32_e32 v119, 0xffff0000, v25
	v_lshlrev_b32_e32 v120, 16, v26
	v_and_b32_e32 v121, 0xffff0000, v26
	v_lshlrev_b32_e32 v122, 16, v27
	v_and_b32_e32 v123, 0xffff0000, v27
	v_lshlrev_b32_e32 v124, 16, v28
	v_and_b32_e32 v125, 0xffff0000, v28
	v_lshlrev_b32_e32 v126, 16, v29
	v_and_b32_e32 v127, 0xffff0000, v29
	v_lshlrev_b32_e32 v128, 16, v30
	v_and_b32_e32 v129, 0xffff0000, v30
	v_lshlrev_b32_e32 v130, 16, v31
	v_and_b32_e32 v131, 0xffff0000, v31
	v_pk_mul_f32 v[138:139], v[116:117], v[116:117]
	v_pk_fma_f32 v[138:139], v[118:119], v[118:119], v[138:139]
	v_pk_fma_f32 v[138:139], v[120:121], v[120:121], v[138:139]
	v_pk_fma_f32 v[138:139], v[122:123], v[122:123], v[138:139]
	v_pk_fma_f32 v[138:139], v[124:125], v[124:125], v[138:139]
	v_pk_fma_f32 v[138:139], v[126:127], v[126:127], v[138:139]
	v_pk_fma_f32 v[138:139], v[128:129], v[128:129], v[138:139]
	v_pk_fma_f32 v[138:139], v[130:131], v[130:131], v[138:139]
	v_add_f32_e32 v132, v132, v133
	v_add_f32_e32 v134, v134, v135
	v_add_f32_e32 v136, v136, v137
	v_add_f32_e32 v138, v138, v139
	s_nop 1
	v_add_f32_dpp v132, v132, v132 row_shr:1 row_mask:0xf bank_mask:0xf bound_ctrl:1
	v_add_f32_dpp v134, v134, v134 row_shr:1 row_mask:0xf bank_mask:0xf bound_ctrl:1
	v_add_f32_dpp v136, v136, v136 row_shr:1 row_mask:0xf bank_mask:0xf bound_ctrl:1
	v_add_f32_dpp v138, v138, v138 row_shr:1 row_mask:0xf bank_mask:0xf bound_ctrl:1
	v_add_f32_dpp v132, v132, v132 row_shr:2 row_mask:0xf bank_mask:0xf bound_ctrl:1
	v_add_f32_dpp v134, v134, v134 row_shr:2 row_mask:0xf bank_mask:0xf bound_ctrl:1
	v_add_f32_dpp v136, v136, v136 row_shr:2 row_mask:0xf bank_mask:0xf bound_ctrl:1
	v_add_f32_dpp v138, v138, v138 row_shr:2 row_mask:0xf bank_mask:0xf bound_ctrl:1
	v_add_f32_dpp v132, v132, v132 row_shr:4 row_mask:0xf bank_mask:0xf bound_ctrl:1
	v_add_f32_dpp v134, v134, v134 row_shr:4 row_mask:0xf bank_mask:0xf bound_ctrl:1
	v_add_f32_dpp v136, v136, v136 row_shr:4 row_mask:0xf bank_mask:0xf bound_ctrl:1
	v_add_f32_dpp v138, v138, v138 row_shr:4 row_mask:0xf bank_mask:0xf bound_ctrl:1
	v_add_f32_dpp v132, v132, v132 row_shr:8 row_mask:0xf bank_mask:0xf bound_ctrl:1
	v_add_f32_dpp v134, v134, v134 row_shr:8 row_mask:0xf bank_mask:0xf bound_ctrl:1
	v_add_f32_dpp v136, v136, v136 row_shr:8 row_mask:0xf bank_mask:0xf bound_ctrl:1
	v_add_f32_dpp v138, v138, v138 row_shr:8 row_mask:0xf bank_mask:0xf bound_ctrl:1
	v_add_f32_dpp v132, v132, v132 row_bcast:15 row_mask:0xa bank_mask:0xf
	v_add_f32_dpp v134, v134, v134 row_bcast:15 row_mask:0xa bank_mask:0xf
	v_add_f32_dpp v136, v136, v136 row_bcast:15 row_mask:0xa bank_mask:0xf
	v_add_f32_dpp v138, v138, v138 row_bcast:15 row_mask:0xa bank_mask:0xf
	v_add_f32_dpp v132, v132, v132 row_bcast:31 row_mask:0xc bank_mask:0xf
	v_add_f32_dpp v134, v134, v134 row_bcast:31 row_mask:0xc bank_mask:0xf
	v_add_f32_dpp v136, v136, v136 row_bcast:31 row_mask:0xc bank_mask:0xf
	v_add_f32_dpp v138, v138, v138 row_bcast:31 row_mask:0xc bank_mask:0xf
	s_nop 1
	v_readlane_b32 s32, v132, 63
	v_readlane_b32 s28, v134, 63
	v_readlane_b32 s29, v136, 63
	v_readlane_b32 s30, v138, 63
	s_nop 1
	v_mov_b32_e32 v140, s32
	v_mov_b32_e32 v142, s28
	v_mov_b32_e32 v144, s29
	v_mov_b32_e32 v146, s30
	v_fmaak_f32 v140, v140, v50, 0x358637bd
	v_fmaak_f32 v142, v142, v50, 0x358637bd
	v_fmaak_f32 v144, v144, v50, 0x358637bd
	v_fmaak_f32 v146, v146, v50, 0x358637bd
	v_rsq_f32_e32 v140, v140
	v_rsq_f32_e32 v142, v142
	v_rsq_f32_e32 v144, v144
	v_rsq_f32_e32 v146, v146
	s_nop 0
	v_lshlrev_b32_e32 v116, 16, v0
	v_and_b32_e32 v117, 0xffff0000, v0
	v_lshlrev_b32_e32 v118, 16, v1
	v_and_b32_e32 v119, 0xffff0000, v1
	v_lshlrev_b32_e32 v120, 16, v2
	v_and_b32_e32 v121, 0xffff0000, v2
	v_lshlrev_b32_e32 v122, 16, v3
	v_and_b32_e32 v123, 0xffff0000, v3
	v_lshlrev_b32_e32 v124, 16, v4
	v_and_b32_e32 v125, 0xffff0000, v4
	v_lshlrev_b32_e32 v126, 16, v5
	v_and_b32_e32 v127, 0xffff0000, v5
	v_lshlrev_b32_e32 v128, 16, v6
	v_and_b32_e32 v129, 0xffff0000, v6
	v_lshlrev_b32_e32 v130, 16, v7
	v_and_b32_e32 v131, 0xffff0000, v7
	v_pk_mul_f32 v[116:117], v[140:141], v[116:117] op_sel_hi:[0,1]
	v_pk_mul_f32 v[118:119], v[140:141], v[118:119] op_sel_hi:[0,1]
	v_pk_mul_f32 v[120:121], v[140:141], v[120:121] op_sel_hi:[0,1]
	v_pk_mul_f32 v[122:123], v[140:141], v[122:123] op_sel_hi:[0,1]
	v_pk_mul_f32 v[124:125], v[140:141], v[124:125] op_sel_hi:[0,1]
	v_pk_mul_f32 v[126:127], v[140:141], v[126:127] op_sel_hi:[0,1]
	v_pk_mul_f32 v[128:129], v[140:141], v[128:129] op_sel_hi:[0,1]
	v_pk_mul_f32 v[130:131], v[140:141], v[130:131] op_sel_hi:[0,1]
	v_pk_mul_f32 v[116:117], v[116:117], v[32:33]
	v_pk_mul_f32 v[118:119], v[118:119], v[34:35]
	v_pk_mul_f32 v[120:121], v[120:121], v[36:37]
	v_pk_mul_f32 v[122:123], v[122:123], v[38:39]
	v_pk_mul_f32 v[124:125], v[124:125], v[40:41]
	v_pk_mul_f32 v[126:127], v[126:127], v[42:43]
	v_pk_mul_f32 v[128:129], v[128:129], v[44:45]
	v_pk_mul_f32 v[130:131], v[130:131], v[46:47]
	v_pk_fma_f32 v[116:117], v[116:117], v[84:85], v[100:101]
	v_pk_fma_f32 v[118:119], v[118:119], v[86:87], v[102:103]
	v_pk_fma_f32 v[120:121], v[120:121], v[88:89], v[104:105]
	v_pk_fma_f32 v[122:123], v[122:123], v[90:91], v[106:107]
	v_pk_fma_f32 v[124:125], v[124:125], v[92:93], v[108:109]
	v_pk_fma_f32 v[126:127], v[126:127], v[94:95], v[110:111]
	v_pk_fma_f32 v[128:129], v[128:129], v[96:97], v[112:113]
	v_pk_fma_f32 v[130:131], v[130:131], v[98:99], v[114:115]
	v_cvt_pk_bf16_f32 v172, v116, v117
	v_cvt_pk_bf16_f32 v173, v118, v119
	v_cvt_pk_bf16_f32 v174, v120, v121
	v_cvt_pk_bf16_f32 v175, v122, v123
	v_cvt_pk_bf16_f32 v176, v124, v125
	v_cvt_pk_bf16_f32 v177, v126, v127
	v_cvt_pk_bf16_f32 v178, v128, v129
	v_cvt_pk_bf16_f32 v179, v130, v131
	global_store_dwordx4 v51, v[172:175], s[26:27]
	global_store_dwordx4 v51, v[176:179], s[26:27] offset:1024
	v_lshlrev_b32_e32 v116, 16, v8
	v_and_b32_e32 v117, 0xffff0000, v8
	v_lshlrev_b32_e32 v118, 16, v9
	v_and_b32_e32 v119, 0xffff0000, v9
	v_lshlrev_b32_e32 v120, 16, v10
	v_and_b32_e32 v121, 0xffff0000, v10
	v_lshlrev_b32_e32 v122, 16, v11
	v_and_b32_e32 v123, 0xffff0000, v11
	v_lshlrev_b32_e32 v124, 16, v12
	v_and_b32_e32 v125, 0xffff0000, v12
	v_lshlrev_b32_e32 v126, 16, v13
	v_and_b32_e32 v127, 0xffff0000, v13
	v_lshlrev_b32_e32 v128, 16, v14
	v_and_b32_e32 v129, 0xffff0000, v14
	v_lshlrev_b32_e32 v130, 16, v15
	v_and_b32_e32 v131, 0xffff0000, v15
	v_pk_mul_f32 v[116:117], v[142:143], v[116:117] op_sel_hi:[0,1]
	v_pk_mul_f32 v[118:119], v[142:143], v[118:119] op_sel_hi:[0,1]
	v_pk_mul_f32 v[120:121], v[142:143], v[120:121] op_sel_hi:[0,1]
	v_pk_mul_f32 v[122:123], v[142:143], v[122:123] op_sel_hi:[0,1]
	v_pk_mul_f32 v[124:125], v[142:143], v[124:125] op_sel_hi:[0,1]
	v_pk_mul_f32 v[126:127], v[142:143], v[126:127] op_sel_hi:[0,1]
	v_pk_mul_f32 v[128:129], v[142:143], v[128:129] op_sel_hi:[0,1]
	v_pk_mul_f32 v[130:131], v[142:143], v[130:131] op_sel_hi:[0,1]
	v_pk_mul_f32 v[116:117], v[116:117], v[32:33]
	v_pk_mul_f32 v[118:119], v[118:119], v[34:35]
	v_pk_mul_f32 v[120:121], v[120:121], v[36:37]
	v_pk_mul_f32 v[122:123], v[122:123], v[38:39]
	v_pk_mul_f32 v[124:125], v[124:125], v[40:41]
	v_pk_mul_f32 v[126:127], v[126:127], v[42:43]
	v_pk_mul_f32 v[128:129], v[128:129], v[44:45]
	v_pk_mul_f32 v[130:131], v[130:131], v[46:47]
	v_pk_fma_f32 v[116:117], v[116:117], v[84:85], v[100:101]
	v_pk_fma_f32 v[118:119], v[118:119], v[86:87], v[102:103]
	v_pk_fma_f32 v[120:121], v[120:121], v[88:89], v[104:105]
	v_pk_fma_f32 v[122:123], v[122:123], v[90:91], v[106:107]
	v_pk_fma_f32 v[124:125], v[124:125], v[92:93], v[108:109]
	v_pk_fma_f32 v[126:127], v[126:127], v[94:95], v[110:111]
	v_pk_fma_f32 v[128:129], v[128:129], v[96:97], v[112:113]
	v_pk_fma_f32 v[130:131], v[130:131], v[98:99], v[114:115]
	v_cvt_pk_bf16_f32 v164, v116, v117
	v_cvt_pk_bf16_f32 v165, v118, v119
	v_cvt_pk_bf16_f32 v166, v120, v121
	v_cvt_pk_bf16_f32 v167, v122, v123
	v_cvt_pk_bf16_f32 v168, v124, v125
	v_cvt_pk_bf16_f32 v169, v126, v127
	v_cvt_pk_bf16_f32 v170, v128, v129
	v_cvt_pk_bf16_f32 v171, v130, v131
	global_store_dwordx4 v51, v[164:167], s[26:27] offset:2048
	global_store_dwordx4 v51, v[168:171], s[26:27] offset:3072
	v_lshlrev_b32_e32 v116, 16, v16
	v_and_b32_e32 v117, 0xffff0000, v16
	v_lshlrev_b32_e32 v118, 16, v17
	v_and_b32_e32 v119, 0xffff0000, v17
	v_lshlrev_b32_e32 v120, 16, v18
	v_and_b32_e32 v121, 0xffff0000, v18
	v_lshlrev_b32_e32 v122, 16, v19
	v_and_b32_e32 v123, 0xffff0000, v19
	v_lshlrev_b32_e32 v124, 16, v20
	v_and_b32_e32 v125, 0xffff0000, v20
	v_lshlrev_b32_e32 v126, 16, v21
	v_and_b32_e32 v127, 0xffff0000, v21
	v_lshlrev_b32_e32 v128, 16, v22
	v_and_b32_e32 v129, 0xffff0000, v22
	v_lshlrev_b32_e32 v130, 16, v23
	v_and_b32_e32 v131, 0xffff0000, v23
	v_pk_mul_f32 v[116:117], v[144:145], v[116:117] op_sel_hi:[0,1]
	v_pk_mul_f32 v[118:119], v[144:145], v[118:119] op_sel_hi:[0,1]
	v_pk_mul_f32 v[120:121], v[144:145], v[120:121] op_sel_hi:[0,1]
	v_pk_mul_f32 v[122:123], v[144:145], v[122:123] op_sel_hi:[0,1]
	v_pk_mul_f32 v[124:125], v[144:145], v[124:125] op_sel_hi:[0,1]
	v_pk_mul_f32 v[126:127], v[144:145], v[126:127] op_sel_hi:[0,1]
	v_pk_mul_f32 v[128:129], v[144:145], v[128:129] op_sel_hi:[0,1]
	v_pk_mul_f32 v[130:131], v[144:145], v[130:131] op_sel_hi:[0,1]
	v_pk_mul_f32 v[116:117], v[116:117], v[32:33]
	v_pk_mul_f32 v[118:119], v[118:119], v[34:35]
	v_pk_mul_f32 v[120:121], v[120:121], v[36:37]
	v_pk_mul_f32 v[122:123], v[122:123], v[38:39]
	v_pk_mul_f32 v[124:125], v[124:125], v[40:41]
	v_pk_mul_f32 v[126:127], v[126:127], v[42:43]
	v_pk_mul_f32 v[128:129], v[128:129], v[44:45]
	v_pk_mul_f32 v[130:131], v[130:131], v[46:47]
	v_pk_fma_f32 v[116:117], v[116:117], v[84:85], v[100:101]
	v_pk_fma_f32 v[118:119], v[118:119], v[86:87], v[102:103]
	v_pk_fma_f32 v[120:121], v[120:121], v[88:89], v[104:105]
	v_pk_fma_f32 v[122:123], v[122:123], v[90:91], v[106:107]
	v_pk_fma_f32 v[124:125], v[124:125], v[92:93], v[108:109]
	v_pk_fma_f32 v[126:127], v[126:127], v[94:95], v[110:111]
	v_pk_fma_f32 v[128:129], v[128:129], v[96:97], v[112:113]
	v_pk_fma_f32 v[130:131], v[130:131], v[98:99], v[114:115]
	v_cvt_pk_bf16_f32 v172, v116, v117
	v_cvt_pk_bf16_f32 v173, v118, v119
	v_cvt_pk_bf16_f32 v174, v120, v121
	v_cvt_pk_bf16_f32 v175, v122, v123
	v_cvt_pk_bf16_f32 v176, v124, v125
	v_cvt_pk_bf16_f32 v177, v126, v127
	v_cvt_pk_bf16_f32 v178, v128, v129
	v_cvt_pk_bf16_f32 v179, v130, v131
	global_store_dwordx4 v149, v[172:175], s[26:27]
	global_store_dwordx4 v149, v[176:179], s[26:27] offset:1024
	v_lshlrev_b32_e32 v116, 16, v24
	v_and_b32_e32 v117, 0xffff0000, v24
	v_lshlrev_b32_e32 v118, 16, v25
	v_and_b32_e32 v119, 0xffff0000, v25
	v_lshlrev_b32_e32 v120, 16, v26
	v_and_b32_e32 v121, 0xffff0000, v26
	v_lshlrev_b32_e32 v122, 16, v27
	v_and_b32_e32 v123, 0xffff0000, v27
	v_lshlrev_b32_e32 v124, 16, v28
	v_and_b32_e32 v125, 0xffff0000, v28
	v_lshlrev_b32_e32 v126, 16, v29
	v_and_b32_e32 v127, 0xffff0000, v29
	v_lshlrev_b32_e32 v128, 16, v30
	v_and_b32_e32 v129, 0xffff0000, v30
	v_lshlrev_b32_e32 v130, 16, v31
	v_and_b32_e32 v131, 0xffff0000, v31
	v_pk_mul_f32 v[116:117], v[146:147], v[116:117] op_sel_hi:[0,1]
	v_pk_mul_f32 v[118:119], v[146:147], v[118:119] op_sel_hi:[0,1]
	v_pk_mul_f32 v[120:121], v[146:147], v[120:121] op_sel_hi:[0,1]
	v_pk_mul_f32 v[122:123], v[146:147], v[122:123] op_sel_hi:[0,1]
	v_pk_mul_f32 v[124:125], v[146:147], v[124:125] op_sel_hi:[0,1]
	v_pk_mul_f32 v[126:127], v[146:147], v[126:127] op_sel_hi:[0,1]
	v_pk_mul_f32 v[128:129], v[146:147], v[128:129] op_sel_hi:[0,1]
	v_pk_mul_f32 v[130:131], v[146:147], v[130:131] op_sel_hi:[0,1]
	v_pk_mul_f32 v[116:117], v[116:117], v[32:33]
	v_pk_mul_f32 v[118:119], v[118:119], v[34:35]
	v_pk_mul_f32 v[120:121], v[120:121], v[36:37]
	v_pk_mul_f32 v[122:123], v[122:123], v[38:39]
	v_pk_mul_f32 v[124:125], v[124:125], v[40:41]
	v_pk_mul_f32 v[126:127], v[126:127], v[42:43]
	v_pk_mul_f32 v[128:129], v[128:129], v[44:45]
	v_pk_mul_f32 v[130:131], v[130:131], v[46:47]
	v_pk_fma_f32 v[116:117], v[116:117], v[84:85], v[100:101]
	v_pk_fma_f32 v[118:119], v[118:119], v[86:87], v[102:103]
	v_pk_fma_f32 v[120:121], v[120:121], v[88:89], v[104:105]
	v_pk_fma_f32 v[122:123], v[122:123], v[90:91], v[106:107]
	v_pk_fma_f32 v[124:125], v[124:125], v[92:93], v[108:109]
	v_pk_fma_f32 v[126:127], v[126:127], v[94:95], v[110:111]
	v_pk_fma_f32 v[128:129], v[128:129], v[96:97], v[112:113]
	v_pk_fma_f32 v[130:131], v[130:131], v[98:99], v[114:115]
	v_cvt_pk_bf16_f32 v164, v116, v117
	v_cvt_pk_bf16_f32 v165, v118, v119
	v_cvt_pk_bf16_f32 v166, v120, v121
	v_cvt_pk_bf16_f32 v167, v122, v123
	v_cvt_pk_bf16_f32 v168, v124, v125
	v_cvt_pk_bf16_f32 v169, v126, v127
	v_cvt_pk_bf16_f32 v170, v128, v129
	v_cvt_pk_bf16_f32 v171, v130, v131
	global_store_dwordx4 v149, v[164:167], s[26:27] offset:2048
	global_store_dwordx4 v149, v[168:171], s[26:27] offset:3072
	s_add_u32 s26, s26, 0x2000
	s_addc_u32 s27, s27, 0
	s_add_u32 s24, s24, 0x2000
	s_addc_u32 s25, s25, 0
	global_load_dwordx4 v[0:3], v51, s[24:25]
	global_load_dwordx4 v[4:7], v51, s[24:25] offset:1024
	global_load_dwordx4 v[8:11], v51, s[24:25] offset:2048
	global_load_dwordx4 v[12:15], v51, s[24:25] offset:3072
	global_load_dwordx4 v[16:19], v149, s[24:25]
	global_load_dwordx4 v[20:23], v149, s[24:25] offset:1024
	global_load_dwordx4 v[24:27], v149, s[24:25] offset:2048
	global_load_dwordx4 v[28:31], v149, s[24:25] offset:3072
	s_waitcnt vmcnt(16)
	v_lshlrev_b32_e32 v116, 16, v52
	v_and_b32_e32 v117, 0xffff0000, v52
	v_lshlrev_b32_e32 v118, 16, v53
	v_and_b32_e32 v119, 0xffff0000, v53
	v_lshlrev_b32_e32 v120, 16, v54
	v_and_b32_e32 v121, 0xffff0000, v54
	v_lshlrev_b32_e32 v122, 16, v55
	v_and_b32_e32 v123, 0xffff0000, v55
	v_lshlrev_b32_e32 v124, 16, v56
	v_and_b32_e32 v125, 0xffff0000, v56
	v_lshlrev_b32_e32 v126, 16, v57
	v_and_b32_e32 v127, 0xffff0000, v57
	v_lshlrev_b32_e32 v128, 16, v58
	v_and_b32_e32 v129, 0xffff0000, v58
	v_lshlrev_b32_e32 v130, 16, v59
	v_and_b32_e32 v131, 0xffff0000, v59
	v_pk_mul_f32 v[132:133], v[116:117], v[116:117]
	v_pk_fma_f32 v[132:133], v[118:119], v[118:119], v[132:133]
	v_pk_fma_f32 v[132:133], v[120:121], v[120:121], v[132:133]
	v_pk_fma_f32 v[132:133], v[122:123], v[122:123], v[132:133]
	v_pk_fma_f32 v[132:133], v[124:125], v[124:125], v[132:133]
	v_pk_fma_f32 v[132:133], v[126:127], v[126:127], v[132:133]
	v_pk_fma_f32 v[132:133], v[128:129], v[128:129], v[132:133]
	v_pk_fma_f32 v[132:133], v[130:131], v[130:131], v[132:133]
	v_lshlrev_b32_e32 v116, 16, v60
	v_and_b32_e32 v117, 0xffff0000, v60
	v_lshlrev_b32_e32 v118, 16, v61
	v_and_b32_e32 v119, 0xffff0000, v61
	v_lshlrev_b32_e32 v120, 16, v62
	v_and_b32_e32 v121, 0xffff0000, v62
	v_lshlrev_b32_e32 v122, 16, v63
	v_and_b32_e32 v123, 0xffff0000, v63
	v_lshlrev_b32_e32 v124, 16, v64
	v_and_b32_e32 v125, 0xffff0000, v64
	v_lshlrev_b32_e32 v126, 16, v65
	v_and_b32_e32 v127, 0xffff0000, v65
	v_lshlrev_b32_e32 v128, 16, v66
	v_and_b32_e32 v129, 0xffff0000, v66
	v_lshlrev_b32_e32 v130, 16, v67
	v_and_b32_e32 v131, 0xffff0000, v67
	v_pk_mul_f32 v[134:135], v[116:117], v[116:117]
	v_pk_fma_f32 v[134:135], v[118:119], v[118:119], v[134:135]
	v_pk_fma_f32 v[134:135], v[120:121], v[120:121], v[134:135]
	v_pk_fma_f32 v[134:135], v[122:123], v[122:123], v[134:135]
	v_pk_fma_f32 v[134:135], v[124:125], v[124:125], v[134:135]
	v_pk_fma_f32 v[134:135], v[126:127], v[126:127], v[134:135]
	v_pk_fma_f32 v[134:135], v[128:129], v[128:129], v[134:135]
	v_pk_fma_f32 v[134:135], v[130:131], v[130:131], v[134:135]
	v_lshlrev_b32_e32 v116, 16, v68
	v_and_b32_e32 v117, 0xffff0000, v68
	v_lshlrev_b32_e32 v118, 16, v69
	v_and_b32_e32 v119, 0xffff0000, v69
	v_lshlrev_b32_e32 v120, 16, v70
	v_and_b32_e32 v121, 0xffff0000, v70
	v_lshlrev_b32_e32 v122, 16, v71
	v_and_b32_e32 v123, 0xffff0000, v71
	v_lshlrev_b32_e32 v124, 16, v72
	v_and_b32_e32 v125, 0xffff0000, v72
	v_lshlrev_b32_e32 v126, 16, v73
	v_and_b32_e32 v127, 0xffff0000, v73
	v_lshlrev_b32_e32 v128, 16, v74
	v_and_b32_e32 v129, 0xffff0000, v74
	v_lshlrev_b32_e32 v130, 16, v75
	v_and_b32_e32 v131, 0xffff0000, v75
	v_pk_mul_f32 v[136:137], v[116:117], v[116:117]
	v_pk_fma_f32 v[136:137], v[118:119], v[118:119], v[136:137]
	v_pk_fma_f32 v[136:137], v[120:121], v[120:121], v[136:137]
	v_pk_fma_f32 v[136:137], v[122:123], v[122:123], v[136:137]
	v_pk_fma_f32 v[136:137], v[124:125], v[124:125], v[136:137]
	v_pk_fma_f32 v[136:137], v[126:127], v[126:127], v[136:137]
	v_pk_fma_f32 v[136:137], v[128:129], v[128:129], v[136:137]
	v_pk_fma_f32 v[136:137], v[130:131], v[130:131], v[136:137]
	v_lshlrev_b32_e32 v116, 16, v76
	v_and_b32_e32 v117, 0xffff0000, v76
	v_lshlrev_b32_e32 v118, 16, v77
	v_and_b32_e32 v119, 0xffff0000, v77
	v_lshlrev_b32_e32 v120, 16, v78
	v_and_b32_e32 v121, 0xffff0000, v78
	v_lshlrev_b32_e32 v122, 16, v79
	v_and_b32_e32 v123, 0xffff0000, v79
	v_lshlrev_b32_e32 v124, 16, v80
	v_and_b32_e32 v125, 0xffff0000, v80
	v_lshlrev_b32_e32 v126, 16, v81
	v_and_b32_e32 v127, 0xffff0000, v81
	v_lshlrev_b32_e32 v128, 16, v82
	v_and_b32_e32 v129, 0xffff0000, v82
	v_lshlrev_b32_e32 v130, 16, v83
	v_and_b32_e32 v131, 0xffff0000, v83
	v_pk_mul_f32 v[138:139], v[116:117], v[116:117]
	v_pk_fma_f32 v[138:139], v[118:119], v[118:119], v[138:139]
	v_pk_fma_f32 v[138:139], v[120:121], v[120:121], v[138:139]
	v_pk_fma_f32 v[138:139], v[122:123], v[122:123], v[138:139]
	v_pk_fma_f32 v[138:139], v[124:125], v[124:125], v[138:139]
	v_pk_fma_f32 v[138:139], v[126:127], v[126:127], v[138:139]
	v_pk_fma_f32 v[138:139], v[128:129], v[128:129], v[138:139]
	v_pk_fma_f32 v[138:139], v[130:131], v[130:131], v[138:139]
	v_add_f32_e32 v132, v132, v133
	v_add_f32_e32 v134, v134, v135
	v_add_f32_e32 v136, v136, v137
	v_add_f32_e32 v138, v138, v139
	s_nop 1
	v_add_f32_dpp v132, v132, v132 row_shr:1 row_mask:0xf bank_mask:0xf bound_ctrl:1
	v_add_f32_dpp v134, v134, v134 row_shr:1 row_mask:0xf bank_mask:0xf bound_ctrl:1
	v_add_f32_dpp v136, v136, v136 row_shr:1 row_mask:0xf bank_mask:0xf bound_ctrl:1
	v_add_f32_dpp v138, v138, v138 row_shr:1 row_mask:0xf bank_mask:0xf bound_ctrl:1
	v_add_f32_dpp v132, v132, v132 row_shr:2 row_mask:0xf bank_mask:0xf bound_ctrl:1
	v_add_f32_dpp v134, v134, v134 row_shr:2 row_mask:0xf bank_mask:0xf bound_ctrl:1
	v_add_f32_dpp v136, v136, v136 row_shr:2 row_mask:0xf bank_mask:0xf bound_ctrl:1
	v_add_f32_dpp v138, v138, v138 row_shr:2 row_mask:0xf bank_mask:0xf bound_ctrl:1
	v_add_f32_dpp v132, v132, v132 row_shr:4 row_mask:0xf bank_mask:0xf bound_ctrl:1
	v_add_f32_dpp v134, v134, v134 row_shr:4 row_mask:0xf bank_mask:0xf bound_ctrl:1
	v_add_f32_dpp v136, v136, v136 row_shr:4 row_mask:0xf bank_mask:0xf bound_ctrl:1
	v_add_f32_dpp v138, v138, v138 row_shr:4 row_mask:0xf bank_mask:0xf bound_ctrl:1
	v_add_f32_dpp v132, v132, v132 row_shr:8 row_mask:0xf bank_mask:0xf bound_ctrl:1
	v_add_f32_dpp v134, v134, v134 row_shr:8 row_mask:0xf bank_mask:0xf bound_ctrl:1
	v_add_f32_dpp v136, v136, v136 row_shr:8 row_mask:0xf bank_mask:0xf bound_ctrl:1
	v_add_f32_dpp v138, v138, v138 row_shr:8 row_mask:0xf bank_mask:0xf bound_ctrl:1
	v_add_f32_dpp v132, v132, v132 row_bcast:15 row_mask:0xa bank_mask:0xf
	v_add_f32_dpp v134, v134, v134 row_bcast:15 row_mask:0xa bank_mask:0xf
	v_add_f32_dpp v136, v136, v136 row_bcast:15 row_mask:0xa bank_mask:0xf
	v_add_f32_dpp v138, v138, v138 row_bcast:15 row_mask:0xa bank_mask:0xf
	v_add_f32_dpp v132, v132, v132 row_bcast:31 row_mask:0xc bank_mask:0xf
	v_add_f32_dpp v134, v134, v134 row_bcast:31 row_mask:0xc bank_mask:0xf
	v_add_f32_dpp v136, v136, v136 row_bcast:31 row_mask:0xc bank_mask:0xf
	v_add_f32_dpp v138, v138, v138 row_bcast:31 row_mask:0xc bank_mask:0xf
	s_nop 1
	v_readlane_b32 s32, v132, 63
	v_readlane_b32 s28, v134, 63
	v_readlane_b32 s29, v136, 63
	v_readlane_b32 s30, v138, 63
	s_nop 1
	v_mov_b32_e32 v140, s32
	v_mov_b32_e32 v142, s28
	v_mov_b32_e32 v144, s29
	v_mov_b32_e32 v146, s30
	v_fmaak_f32 v140, v140, v50, 0x358637bd
	v_fmaak_f32 v142, v142, v50, 0x358637bd
	v_fmaak_f32 v144, v144, v50, 0x358637bd
	v_fmaak_f32 v146, v146, v50, 0x358637bd
	v_rsq_f32_e32 v140, v140
	v_rsq_f32_e32 v142, v142
	v_rsq_f32_e32 v144, v144
	v_rsq_f32_e32 v146, v146
	s_nop 0
	v_lshlrev_b32_e32 v116, 16, v52
	v_and_b32_e32 v117, 0xffff0000, v52
	v_lshlrev_b32_e32 v118, 16, v53
	v_and_b32_e32 v119, 0xffff0000, v53
	v_lshlrev_b32_e32 v120, 16, v54
	v_and_b32_e32 v121, 0xffff0000, v54
	v_lshlrev_b32_e32 v122, 16, v55
	v_and_b32_e32 v123, 0xffff0000, v55
	v_lshlrev_b32_e32 v124, 16, v56
	v_and_b32_e32 v125, 0xffff0000, v56
	v_lshlrev_b32_e32 v126, 16, v57
	v_and_b32_e32 v127, 0xffff0000, v57
	v_lshlrev_b32_e32 v128, 16, v58
	v_and_b32_e32 v129, 0xffff0000, v58
	v_lshlrev_b32_e32 v130, 16, v59
	v_and_b32_e32 v131, 0xffff0000, v59
	v_pk_mul_f32 v[116:117], v[140:141], v[116:117] op_sel_hi:[0,1]
	v_pk_mul_f32 v[118:119], v[140:141], v[118:119] op_sel_hi:[0,1]
	v_pk_mul_f32 v[120:121], v[140:141], v[120:121] op_sel_hi:[0,1]
	v_pk_mul_f32 v[122:123], v[140:141], v[122:123] op_sel_hi:[0,1]
	v_pk_mul_f32 v[124:125], v[140:141], v[124:125] op_sel_hi:[0,1]
	v_pk_mul_f32 v[126:127], v[140:141], v[126:127] op_sel_hi:[0,1]
	v_pk_mul_f32 v[128:129], v[140:141], v[128:129] op_sel_hi:[0,1]
	v_pk_mul_f32 v[130:131], v[140:141], v[130:131] op_sel_hi:[0,1]
	v_pk_mul_f32 v[116:117], v[116:117], v[32:33]
	v_pk_mul_f32 v[118:119], v[118:119], v[34:35]
	v_pk_mul_f32 v[120:121], v[120:121], v[36:37]
	v_pk_mul_f32 v[122:123], v[122:123], v[38:39]
	v_pk_mul_f32 v[124:125], v[124:125], v[40:41]
	v_pk_mul_f32 v[126:127], v[126:127], v[42:43]
	v_pk_mul_f32 v[128:129], v[128:129], v[44:45]
	v_pk_mul_f32 v[130:131], v[130:131], v[46:47]
	v_pk_fma_f32 v[116:117], v[116:117], v[84:85], v[100:101]
	v_pk_fma_f32 v[118:119], v[118:119], v[86:87], v[102:103]
	v_pk_fma_f32 v[120:121], v[120:121], v[88:89], v[104:105]
	v_pk_fma_f32 v[122:123], v[122:123], v[90:91], v[106:107]
	v_pk_fma_f32 v[124:125], v[124:125], v[92:93], v[108:109]
	v_pk_fma_f32 v[126:127], v[126:127], v[94:95], v[110:111]
	v_pk_fma_f32 v[128:129], v[128:129], v[96:97], v[112:113]
	v_pk_fma_f32 v[130:131], v[130:131], v[98:99], v[114:115]
	v_cvt_pk_bf16_f32 v164, v116, v117
	v_cvt_pk_bf16_f32 v165, v118, v119
	v_cvt_pk_bf16_f32 v166, v120, v121
	v_cvt_pk_bf16_f32 v167, v122, v123
	v_cvt_pk_bf16_f32 v168, v124, v125
	v_cvt_pk_bf16_f32 v169, v126, v127
	v_cvt_pk_bf16_f32 v170, v128, v129
	v_cvt_pk_bf16_f32 v171, v130, v131
	global_store_dwordx4 v51, v[164:167], s[26:27]
	global_store_dwordx4 v51, v[168:171], s[26:27] offset:1024
	v_lshlrev_b32_e32 v116, 16, v60
	v_and_b32_e32 v117, 0xffff0000, v60
	v_lshlrev_b32_e32 v118, 16, v61
	v_and_b32_e32 v119, 0xffff0000, v61
	v_lshlrev_b32_e32 v120, 16, v62
	v_and_b32_e32 v121, 0xffff0000, v62
	v_lshlrev_b32_e32 v122, 16, v63
	v_and_b32_e32 v123, 0xffff0000, v63
	v_lshlrev_b32_e32 v124, 16, v64
	v_and_b32_e32 v125, 0xffff0000, v64
	v_lshlrev_b32_e32 v126, 16, v65
	v_and_b32_e32 v127, 0xffff0000, v65
	v_lshlrev_b32_e32 v128, 16, v66
	v_and_b32_e32 v129, 0xffff0000, v66
	v_lshlrev_b32_e32 v130, 16, v67
	v_and_b32_e32 v131, 0xffff0000, v67
	v_pk_mul_f32 v[116:117], v[142:143], v[116:117] op_sel_hi:[0,1]
	v_pk_mul_f32 v[118:119], v[142:143], v[118:119] op_sel_hi:[0,1]
	v_pk_mul_f32 v[120:121], v[142:143], v[120:121] op_sel_hi:[0,1]
	v_pk_mul_f32 v[122:123], v[142:143], v[122:123] op_sel_hi:[0,1]
	v_pk_mul_f32 v[124:125], v[142:143], v[124:125] op_sel_hi:[0,1]
	v_pk_mul_f32 v[126:127], v[142:143], v[126:127] op_sel_hi:[0,1]
	v_pk_mul_f32 v[128:129], v[142:143], v[128:129] op_sel_hi:[0,1]
	v_pk_mul_f32 v[130:131], v[142:143], v[130:131] op_sel_hi:[0,1]
	v_pk_mul_f32 v[116:117], v[116:117], v[32:33]
	v_pk_mul_f32 v[118:119], v[118:119], v[34:35]
	v_pk_mul_f32 v[120:121], v[120:121], v[36:37]
	v_pk_mul_f32 v[122:123], v[122:123], v[38:39]
	v_pk_mul_f32 v[124:125], v[124:125], v[40:41]
	v_pk_mul_f32 v[126:127], v[126:127], v[42:43]
	v_pk_mul_f32 v[128:129], v[128:129], v[44:45]
	v_pk_mul_f32 v[130:131], v[130:131], v[46:47]
	v_pk_fma_f32 v[116:117], v[116:117], v[84:85], v[100:101]
	v_pk_fma_f32 v[118:119], v[118:119], v[86:87], v[102:103]
	v_pk_fma_f32 v[120:121], v[120:121], v[88:89], v[104:105]
	v_pk_fma_f32 v[122:123], v[122:123], v[90:91], v[106:107]
	v_pk_fma_f32 v[124:125], v[124:125], v[92:93], v[108:109]
	v_pk_fma_f32 v[126:127], v[126:127], v[94:95], v[110:111]
	v_pk_fma_f32 v[128:129], v[128:129], v[96:97], v[112:113]
	v_pk_fma_f32 v[130:131], v[130:131], v[98:99], v[114:115]
	v_cvt_pk_bf16_f32 v172, v116, v117
	v_cvt_pk_bf16_f32 v173, v118, v119
	v_cvt_pk_bf16_f32 v174, v120, v121
	v_cvt_pk_bf16_f32 v175, v122, v123
	v_cvt_pk_bf16_f32 v176, v124, v125
	v_cvt_pk_bf16_f32 v177, v126, v127
	v_cvt_pk_bf16_f32 v178, v128, v129
	v_cvt_pk_bf16_f32 v179, v130, v131
	global_store_dwordx4 v51, v[172:175], s[26:27] offset:2048
	global_store_dwordx4 v51, v[176:179], s[26:27] offset:3072
	v_lshlrev_b32_e32 v116, 16, v68
	v_and_b32_e32 v117, 0xffff0000, v68
	v_lshlrev_b32_e32 v118, 16, v69
	v_and_b32_e32 v119, 0xffff0000, v69
	v_lshlrev_b32_e32 v120, 16, v70
	v_and_b32_e32 v121, 0xffff0000, v70
	v_lshlrev_b32_e32 v122, 16, v71
	v_and_b32_e32 v123, 0xffff0000, v71
	v_lshlrev_b32_e32 v124, 16, v72
	v_and_b32_e32 v125, 0xffff0000, v72
	v_lshlrev_b32_e32 v126, 16, v73
	v_and_b32_e32 v127, 0xffff0000, v73
	v_lshlrev_b32_e32 v128, 16, v74
	v_and_b32_e32 v129, 0xffff0000, v74
	v_lshlrev_b32_e32 v130, 16, v75
	v_and_b32_e32 v131, 0xffff0000, v75
	v_pk_mul_f32 v[116:117], v[144:145], v[116:117] op_sel_hi:[0,1]
	v_pk_mul_f32 v[118:119], v[144:145], v[118:119] op_sel_hi:[0,1]
	v_pk_mul_f32 v[120:121], v[144:145], v[120:121] op_sel_hi:[0,1]
	v_pk_mul_f32 v[122:123], v[144:145], v[122:123] op_sel_hi:[0,1]
	v_pk_mul_f32 v[124:125], v[144:145], v[124:125] op_sel_hi:[0,1]
	v_pk_mul_f32 v[126:127], v[144:145], v[126:127] op_sel_hi:[0,1]
	v_pk_mul_f32 v[128:129], v[144:145], v[128:129] op_sel_hi:[0,1]
	v_pk_mul_f32 v[130:131], v[144:145], v[130:131] op_sel_hi:[0,1]
	v_pk_mul_f32 v[116:117], v[116:117], v[32:33]
	v_pk_mul_f32 v[118:119], v[118:119], v[34:35]
	v_pk_mul_f32 v[120:121], v[120:121], v[36:37]
	v_pk_mul_f32 v[122:123], v[122:123], v[38:39]
	v_pk_mul_f32 v[124:125], v[124:125], v[40:41]
	v_pk_mul_f32 v[126:127], v[126:127], v[42:43]
	v_pk_mul_f32 v[128:129], v[128:129], v[44:45]
	v_pk_mul_f32 v[130:131], v[130:131], v[46:47]
	v_pk_fma_f32 v[116:117], v[116:117], v[84:85], v[100:101]
	v_pk_fma_f32 v[118:119], v[118:119], v[86:87], v[102:103]
	v_pk_fma_f32 v[120:121], v[120:121], v[88:89], v[104:105]
	v_pk_fma_f32 v[122:123], v[122:123], v[90:91], v[106:107]
	v_pk_fma_f32 v[124:125], v[124:125], v[92:93], v[108:109]
	v_pk_fma_f32 v[126:127], v[126:127], v[94:95], v[110:111]
	v_pk_fma_f32 v[128:129], v[128:129], v[96:97], v[112:113]
	v_pk_fma_f32 v[130:131], v[130:131], v[98:99], v[114:115]
	v_cvt_pk_bf16_f32 v164, v116, v117
	v_cvt_pk_bf16_f32 v165, v118, v119
	v_cvt_pk_bf16_f32 v166, v120, v121
	v_cvt_pk_bf16_f32 v167, v122, v123
	v_cvt_pk_bf16_f32 v168, v124, v125
	v_cvt_pk_bf16_f32 v169, v126, v127
	v_cvt_pk_bf16_f32 v170, v128, v129
	v_cvt_pk_bf16_f32 v171, v130, v131
	global_store_dwordx4 v149, v[164:167], s[26:27]
	global_store_dwordx4 v149, v[168:171], s[26:27] offset:1024
	v_lshlrev_b32_e32 v116, 16, v76
	v_and_b32_e32 v117, 0xffff0000, v76
	v_lshlrev_b32_e32 v118, 16, v77
	v_and_b32_e32 v119, 0xffff0000, v77
	v_lshlrev_b32_e32 v120, 16, v78
	v_and_b32_e32 v121, 0xffff0000, v78
	v_lshlrev_b32_e32 v122, 16, v79
	v_and_b32_e32 v123, 0xffff0000, v79
	v_lshlrev_b32_e32 v124, 16, v80
	v_and_b32_e32 v125, 0xffff0000, v80
	v_lshlrev_b32_e32 v126, 16, v81
	v_and_b32_e32 v127, 0xffff0000, v81
	v_lshlrev_b32_e32 v128, 16, v82
	v_and_b32_e32 v129, 0xffff0000, v82
	v_lshlrev_b32_e32 v130, 16, v83
	v_and_b32_e32 v131, 0xffff0000, v83
	v_pk_mul_f32 v[116:117], v[146:147], v[116:117] op_sel_hi:[0,1]
	v_pk_mul_f32 v[118:119], v[146:147], v[118:119] op_sel_hi:[0,1]
	v_pk_mul_f32 v[120:121], v[146:147], v[120:121] op_sel_hi:[0,1]
	v_pk_mul_f32 v[122:123], v[146:147], v[122:123] op_sel_hi:[0,1]
	v_pk_mul_f32 v[124:125], v[146:147], v[124:125] op_sel_hi:[0,1]
	v_pk_mul_f32 v[126:127], v[146:147], v[126:127] op_sel_hi:[0,1]
	v_pk_mul_f32 v[128:129], v[146:147], v[128:129] op_sel_hi:[0,1]
	v_pk_mul_f32 v[130:131], v[146:147], v[130:131] op_sel_hi:[0,1]
	v_pk_mul_f32 v[116:117], v[116:117], v[32:33]
	v_pk_mul_f32 v[118:119], v[118:119], v[34:35]
	v_pk_mul_f32 v[120:121], v[120:121], v[36:37]
	v_pk_mul_f32 v[122:123], v[122:123], v[38:39]
	v_pk_mul_f32 v[124:125], v[124:125], v[40:41]
	v_pk_mul_f32 v[126:127], v[126:127], v[42:43]
	v_pk_mul_f32 v[128:129], v[128:129], v[44:45]
	v_pk_mul_f32 v[130:131], v[130:131], v[46:47]
	v_pk_fma_f32 v[116:117], v[116:117], v[84:85], v[100:101]
	v_pk_fma_f32 v[118:119], v[118:119], v[86:87], v[102:103]
	v_pk_fma_f32 v[120:121], v[120:121], v[88:89], v[104:105]
	v_pk_fma_f32 v[122:123], v[122:123], v[90:91], v[106:107]
	v_pk_fma_f32 v[124:125], v[124:125], v[92:93], v[108:109]
	v_pk_fma_f32 v[126:127], v[126:127], v[94:95], v[110:111]
	v_pk_fma_f32 v[128:129], v[128:129], v[96:97], v[112:113]
	v_pk_fma_f32 v[130:131], v[130:131], v[98:99], v[114:115]
	v_cvt_pk_bf16_f32 v172, v116, v117
	v_cvt_pk_bf16_f32 v173, v118, v119
	v_cvt_pk_bf16_f32 v174, v120, v121
	v_cvt_pk_bf16_f32 v175, v122, v123
	v_cvt_pk_bf16_f32 v176, v124, v125
	v_cvt_pk_bf16_f32 v177, v126, v127
	v_cvt_pk_bf16_f32 v178, v128, v129
	v_cvt_pk_bf16_f32 v179, v130, v131
	global_store_dwordx4 v149, v[172:175], s[26:27] offset:2048
	global_store_dwordx4 v149, v[176:179], s[26:27] offset:3072
	s_add_u32 s26, s26, 0x2000
	s_addc_u32 s27, s27, 0
	s_add_u32 s24, s24, 0x2000
	s_addc_u32 s25, s25, 0
	global_load_dwordx4 v[52:55], v51, s[24:25]
	global_load_dwordx4 v[56:59], v51, s[24:25] offset:1024
	global_load_dwordx4 v[60:63], v51, s[24:25] offset:2048
	global_load_dwordx4 v[64:67], v51, s[24:25] offset:3072
	global_load_dwordx4 v[68:71], v149, s[24:25]
	global_load_dwordx4 v[72:75], v149, s[24:25] offset:1024
	global_load_dwordx4 v[76:79], v149, s[24:25] offset:2048
	global_load_dwordx4 v[80:83], v149, s[24:25] offset:3072
	s_waitcnt vmcnt(16)
	v_lshlrev_b32_e32 v116, 16, v0
	v_and_b32_e32 v117, 0xffff0000, v0
	v_lshlrev_b32_e32 v118, 16, v1
	v_and_b32_e32 v119, 0xffff0000, v1
	v_lshlrev_b32_e32 v120, 16, v2
	v_and_b32_e32 v121, 0xffff0000, v2
	v_lshlrev_b32_e32 v122, 16, v3
	v_and_b32_e32 v123, 0xffff0000, v3
	v_lshlrev_b32_e32 v124, 16, v4
	v_and_b32_e32 v125, 0xffff0000, v4
	v_lshlrev_b32_e32 v126, 16, v5
	v_and_b32_e32 v127, 0xffff0000, v5
	v_lshlrev_b32_e32 v128, 16, v6
	v_and_b32_e32 v129, 0xffff0000, v6
	v_lshlrev_b32_e32 v130, 16, v7
	v_and_b32_e32 v131, 0xffff0000, v7
	v_pk_mul_f32 v[132:133], v[116:117], v[116:117]
	v_pk_fma_f32 v[132:133], v[118:119], v[118:119], v[132:133]
	v_pk_fma_f32 v[132:133], v[120:121], v[120:121], v[132:133]
	v_pk_fma_f32 v[132:133], v[122:123], v[122:123], v[132:133]
	v_pk_fma_f32 v[132:133], v[124:125], v[124:125], v[132:133]
	v_pk_fma_f32 v[132:133], v[126:127], v[126:127], v[132:133]
	v_pk_fma_f32 v[132:133], v[128:129], v[128:129], v[132:133]
	v_pk_fma_f32 v[132:133], v[130:131], v[130:131], v[132:133]
	v_lshlrev_b32_e32 v116, 16, v8
	v_and_b32_e32 v117, 0xffff0000, v8
	v_lshlrev_b32_e32 v118, 16, v9
	v_and_b32_e32 v119, 0xffff0000, v9
	v_lshlrev_b32_e32 v120, 16, v10
	v_and_b32_e32 v121, 0xffff0000, v10
	v_lshlrev_b32_e32 v122, 16, v11
	v_and_b32_e32 v123, 0xffff0000, v11
	v_lshlrev_b32_e32 v124, 16, v12
	v_and_b32_e32 v125, 0xffff0000, v12
	v_lshlrev_b32_e32 v126, 16, v13
	v_and_b32_e32 v127, 0xffff0000, v13
	v_lshlrev_b32_e32 v128, 16, v14
	v_and_b32_e32 v129, 0xffff0000, v14
	v_lshlrev_b32_e32 v130, 16, v15
	v_and_b32_e32 v131, 0xffff0000, v15
	v_pk_mul_f32 v[134:135], v[116:117], v[116:117]
	v_pk_fma_f32 v[134:135], v[118:119], v[118:119], v[134:135]
	v_pk_fma_f32 v[134:135], v[120:121], v[120:121], v[134:135]
	v_pk_fma_f32 v[134:135], v[122:123], v[122:123], v[134:135]
	v_pk_fma_f32 v[134:135], v[124:125], v[124:125], v[134:135]
	v_pk_fma_f32 v[134:135], v[126:127], v[126:127], v[134:135]
	v_pk_fma_f32 v[134:135], v[128:129], v[128:129], v[134:135]
	v_pk_fma_f32 v[134:135], v[130:131], v[130:131], v[134:135]
	v_lshlrev_b32_e32 v116, 16, v16
	v_and_b32_e32 v117, 0xffff0000, v16
	v_lshlrev_b32_e32 v118, 16, v17
	v_and_b32_e32 v119, 0xffff0000, v17
	v_lshlrev_b32_e32 v120, 16, v18
	v_and_b32_e32 v121, 0xffff0000, v18
	v_lshlrev_b32_e32 v122, 16, v19
	v_and_b32_e32 v123, 0xffff0000, v19
	v_lshlrev_b32_e32 v124, 16, v20
	v_and_b32_e32 v125, 0xffff0000, v20
	v_lshlrev_b32_e32 v126, 16, v21
	v_and_b32_e32 v127, 0xffff0000, v21
	v_lshlrev_b32_e32 v128, 16, v22
	v_and_b32_e32 v129, 0xffff0000, v22
	v_lshlrev_b32_e32 v130, 16, v23
	v_and_b32_e32 v131, 0xffff0000, v23
	v_pk_mul_f32 v[136:137], v[116:117], v[116:117]
	v_pk_fma_f32 v[136:137], v[118:119], v[118:119], v[136:137]
	v_pk_fma_f32 v[136:137], v[120:121], v[120:121], v[136:137]
	v_pk_fma_f32 v[136:137], v[122:123], v[122:123], v[136:137]
	v_pk_fma_f32 v[136:137], v[124:125], v[124:125], v[136:137]
	v_pk_fma_f32 v[136:137], v[126:127], v[126:127], v[136:137]
	v_pk_fma_f32 v[136:137], v[128:129], v[128:129], v[136:137]
	v_pk_fma_f32 v[136:137], v[130:131], v[130:131], v[136:137]
	v_lshlrev_b32_e32 v116, 16, v24
	v_and_b32_e32 v117, 0xffff0000, v24
	v_lshlrev_b32_e32 v118, 16, v25
	v_and_b32_e32 v119, 0xffff0000, v25
	v_lshlrev_b32_e32 v120, 16, v26
	v_and_b32_e32 v121, 0xffff0000, v26
	v_lshlrev_b32_e32 v122, 16, v27
	v_and_b32_e32 v123, 0xffff0000, v27
	v_lshlrev_b32_e32 v124, 16, v28
	v_and_b32_e32 v125, 0xffff0000, v28
	v_lshlrev_b32_e32 v126, 16, v29
	v_and_b32_e32 v127, 0xffff0000, v29
	v_lshlrev_b32_e32 v128, 16, v30
	v_and_b32_e32 v129, 0xffff0000, v30
	v_lshlrev_b32_e32 v130, 16, v31
	v_and_b32_e32 v131, 0xffff0000, v31
	v_pk_mul_f32 v[138:139], v[116:117], v[116:117]
	v_pk_fma_f32 v[138:139], v[118:119], v[118:119], v[138:139]
	v_pk_fma_f32 v[138:139], v[120:121], v[120:121], v[138:139]
	v_pk_fma_f32 v[138:139], v[122:123], v[122:123], v[138:139]
	v_pk_fma_f32 v[138:139], v[124:125], v[124:125], v[138:139]
	v_pk_fma_f32 v[138:139], v[126:127], v[126:127], v[138:139]
	v_pk_fma_f32 v[138:139], v[128:129], v[128:129], v[138:139]
	v_pk_fma_f32 v[138:139], v[130:131], v[130:131], v[138:139]
	v_add_f32_e32 v132, v132, v133
	v_add_f32_e32 v134, v134, v135
	v_add_f32_e32 v136, v136, v137
	v_add_f32_e32 v138, v138, v139
	s_nop 1
	v_add_f32_dpp v132, v132, v132 row_shr:1 row_mask:0xf bank_mask:0xf bound_ctrl:1
	v_add_f32_dpp v134, v134, v134 row_shr:1 row_mask:0xf bank_mask:0xf bound_ctrl:1
	v_add_f32_dpp v136, v136, v136 row_shr:1 row_mask:0xf bank_mask:0xf bound_ctrl:1
	v_add_f32_dpp v138, v138, v138 row_shr:1 row_mask:0xf bank_mask:0xf bound_ctrl:1
	v_add_f32_dpp v132, v132, v132 row_shr:2 row_mask:0xf bank_mask:0xf bound_ctrl:1
	v_add_f32_dpp v134, v134, v134 row_shr:2 row_mask:0xf bank_mask:0xf bound_ctrl:1
	v_add_f32_dpp v136, v136, v136 row_shr:2 row_mask:0xf bank_mask:0xf bound_ctrl:1
	v_add_f32_dpp v138, v138, v138 row_shr:2 row_mask:0xf bank_mask:0xf bound_ctrl:1
	v_add_f32_dpp v132, v132, v132 row_shr:4 row_mask:0xf bank_mask:0xf bound_ctrl:1
	v_add_f32_dpp v134, v134, v134 row_shr:4 row_mask:0xf bank_mask:0xf bound_ctrl:1
	v_add_f32_dpp v136, v136, v136 row_shr:4 row_mask:0xf bank_mask:0xf bound_ctrl:1
	v_add_f32_dpp v138, v138, v138 row_shr:4 row_mask:0xf bank_mask:0xf bound_ctrl:1
	v_add_f32_dpp v132, v132, v132 row_shr:8 row_mask:0xf bank_mask:0xf bound_ctrl:1
	v_add_f32_dpp v134, v134, v134 row_shr:8 row_mask:0xf bank_mask:0xf bound_ctrl:1
	v_add_f32_dpp v136, v136, v136 row_shr:8 row_mask:0xf bank_mask:0xf bound_ctrl:1
	v_add_f32_dpp v138, v138, v138 row_shr:8 row_mask:0xf bank_mask:0xf bound_ctrl:1
	v_add_f32_dpp v132, v132, v132 row_bcast:15 row_mask:0xa bank_mask:0xf
	v_add_f32_dpp v134, v134, v134 row_bcast:15 row_mask:0xa bank_mask:0xf
	v_add_f32_dpp v136, v136, v136 row_bcast:15 row_mask:0xa bank_mask:0xf
	v_add_f32_dpp v138, v138, v138 row_bcast:15 row_mask:0xa bank_mask:0xf
	v_add_f32_dpp v132, v132, v132 row_bcast:31 row_mask:0xc bank_mask:0xf
	v_add_f32_dpp v134, v134, v134 row_bcast:31 row_mask:0xc bank_mask:0xf
	v_add_f32_dpp v136, v136, v136 row_bcast:31 row_mask:0xc bank_mask:0xf
	v_add_f32_dpp v138, v138, v138 row_bcast:31 row_mask:0xc bank_mask:0xf
	s_nop 1
	v_readlane_b32 s32, v132, 63
	v_readlane_b32 s28, v134, 63
	v_readlane_b32 s29, v136, 63
	v_readlane_b32 s30, v138, 63
	s_nop 1
	v_mov_b32_e32 v140, s32
	v_mov_b32_e32 v142, s28
	v_mov_b32_e32 v144, s29
	v_mov_b32_e32 v146, s30
	v_fmaak_f32 v140, v140, v50, 0x358637bd
	v_fmaak_f32 v142, v142, v50, 0x358637bd
	v_fmaak_f32 v144, v144, v50, 0x358637bd
	v_fmaak_f32 v146, v146, v50, 0x358637bd
	v_rsq_f32_e32 v140, v140
	v_rsq_f32_e32 v142, v142
	v_rsq_f32_e32 v144, v144
	v_rsq_f32_e32 v146, v146
	s_nop 0
	v_lshlrev_b32_e32 v116, 16, v0
	v_and_b32_e32 v117, 0xffff0000, v0
	v_lshlrev_b32_e32 v118, 16, v1
	v_and_b32_e32 v119, 0xffff0000, v1
	v_lshlrev_b32_e32 v120, 16, v2
	v_and_b32_e32 v121, 0xffff0000, v2
	v_lshlrev_b32_e32 v122, 16, v3
	v_and_b32_e32 v123, 0xffff0000, v3
	v_lshlrev_b32_e32 v124, 16, v4
	v_and_b32_e32 v125, 0xffff0000, v4
	v_lshlrev_b32_e32 v126, 16, v5
	v_and_b32_e32 v127, 0xffff0000, v5
	v_lshlrev_b32_e32 v128, 16, v6
	v_and_b32_e32 v129, 0xffff0000, v6
	v_lshlrev_b32_e32 v130, 16, v7
	v_and_b32_e32 v131, 0xffff0000, v7
	v_pk_mul_f32 v[116:117], v[140:141], v[116:117] op_sel_hi:[0,1]
	v_pk_mul_f32 v[118:119], v[140:141], v[118:119] op_sel_hi:[0,1]
	v_pk_mul_f32 v[120:121], v[140:141], v[120:121] op_sel_hi:[0,1]
	v_pk_mul_f32 v[122:123], v[140:141], v[122:123] op_sel_hi:[0,1]
	v_pk_mul_f32 v[124:125], v[140:141], v[124:125] op_sel_hi:[0,1]
	v_pk_mul_f32 v[126:127], v[140:141], v[126:127] op_sel_hi:[0,1]
	v_pk_mul_f32 v[128:129], v[140:141], v[128:129] op_sel_hi:[0,1]
	v_pk_mul_f32 v[130:131], v[140:141], v[130:131] op_sel_hi:[0,1]
	v_pk_mul_f32 v[116:117], v[116:117], v[32:33]
	v_pk_mul_f32 v[118:119], v[118:119], v[34:35]
	v_pk_mul_f32 v[120:121], v[120:121], v[36:37]
	v_pk_mul_f32 v[122:123], v[122:123], v[38:39]
	v_pk_mul_f32 v[124:125], v[124:125], v[40:41]
	v_pk_mul_f32 v[126:127], v[126:127], v[42:43]
	v_pk_mul_f32 v[128:129], v[128:129], v[44:45]
	v_pk_mul_f32 v[130:131], v[130:131], v[46:47]
	v_pk_fma_f32 v[116:117], v[116:117], v[84:85], v[100:101]
	v_pk_fma_f32 v[118:119], v[118:119], v[86:87], v[102:103]
	v_pk_fma_f32 v[120:121], v[120:121], v[88:89], v[104:105]
	v_pk_fma_f32 v[122:123], v[122:123], v[90:91], v[106:107]
	v_pk_fma_f32 v[124:125], v[124:125], v[92:93], v[108:109]
	v_pk_fma_f32 v[126:127], v[126:127], v[94:95], v[110:111]
	v_pk_fma_f32 v[128:129], v[128:129], v[96:97], v[112:113]
	v_pk_fma_f32 v[130:131], v[130:131], v[98:99], v[114:115]
	v_cvt_pk_bf16_f32 v172, v116, v117
	v_cvt_pk_bf16_f32 v173, v118, v119
	v_cvt_pk_bf16_f32 v174, v120, v121
	v_cvt_pk_bf16_f32 v175, v122, v123
	v_cvt_pk_bf16_f32 v176, v124, v125
	v_cvt_pk_bf16_f32 v177, v126, v127
	v_cvt_pk_bf16_f32 v178, v128, v129
	v_cvt_pk_bf16_f32 v179, v130, v131
	global_store_dwordx4 v51, v[172:175], s[26:27]
	global_store_dwordx4 v51, v[176:179], s[26:27] offset:1024
	v_lshlrev_b32_e32 v116, 16, v8
	v_and_b32_e32 v117, 0xffff0000, v8
	v_lshlrev_b32_e32 v118, 16, v9
	v_and_b32_e32 v119, 0xffff0000, v9
	v_lshlrev_b32_e32 v120, 16, v10
	v_and_b32_e32 v121, 0xffff0000, v10
	v_lshlrev_b32_e32 v122, 16, v11
	v_and_b32_e32 v123, 0xffff0000, v11
	v_lshlrev_b32_e32 v124, 16, v12
	v_and_b32_e32 v125, 0xffff0000, v12
	v_lshlrev_b32_e32 v126, 16, v13
	v_and_b32_e32 v127, 0xffff0000, v13
	v_lshlrev_b32_e32 v128, 16, v14
	v_and_b32_e32 v129, 0xffff0000, v14
	v_lshlrev_b32_e32 v130, 16, v15
	v_and_b32_e32 v131, 0xffff0000, v15
	v_pk_mul_f32 v[116:117], v[142:143], v[116:117] op_sel_hi:[0,1]
	v_pk_mul_f32 v[118:119], v[142:143], v[118:119] op_sel_hi:[0,1]
	v_pk_mul_f32 v[120:121], v[142:143], v[120:121] op_sel_hi:[0,1]
	v_pk_mul_f32 v[122:123], v[142:143], v[122:123] op_sel_hi:[0,1]
	v_pk_mul_f32 v[124:125], v[142:143], v[124:125] op_sel_hi:[0,1]
	v_pk_mul_f32 v[126:127], v[142:143], v[126:127] op_sel_hi:[0,1]
	v_pk_mul_f32 v[128:129], v[142:143], v[128:129] op_sel_hi:[0,1]
	v_pk_mul_f32 v[130:131], v[142:143], v[130:131] op_sel_hi:[0,1]
	v_pk_mul_f32 v[116:117], v[116:117], v[32:33]
	v_pk_mul_f32 v[118:119], v[118:119], v[34:35]
	v_pk_mul_f32 v[120:121], v[120:121], v[36:37]
	v_pk_mul_f32 v[122:123], v[122:123], v[38:39]
	v_pk_mul_f32 v[124:125], v[124:125], v[40:41]
	v_pk_mul_f32 v[126:127], v[126:127], v[42:43]
	v_pk_mul_f32 v[128:129], v[128:129], v[44:45]
	v_pk_mul_f32 v[130:131], v[130:131], v[46:47]
	v_pk_fma_f32 v[116:117], v[116:117], v[84:85], v[100:101]
	v_pk_fma_f32 v[118:119], v[118:119], v[86:87], v[102:103]
	v_pk_fma_f32 v[120:121], v[120:121], v[88:89], v[104:105]
	v_pk_fma_f32 v[122:123], v[122:123], v[90:91], v[106:107]
	v_pk_fma_f32 v[124:125], v[124:125], v[92:93], v[108:109]
	v_pk_fma_f32 v[126:127], v[126:127], v[94:95], v[110:111]
	v_pk_fma_f32 v[128:129], v[128:129], v[96:97], v[112:113]
	v_pk_fma_f32 v[130:131], v[130:131], v[98:99], v[114:115]
	v_cvt_pk_bf16_f32 v164, v116, v117
	v_cvt_pk_bf16_f32 v165, v118, v119
	v_cvt_pk_bf16_f32 v166, v120, v121
	v_cvt_pk_bf16_f32 v167, v122, v123
	v_cvt_pk_bf16_f32 v168, v124, v125
	v_cvt_pk_bf16_f32 v169, v126, v127
	v_cvt_pk_bf16_f32 v170, v128, v129
	v_cvt_pk_bf16_f32 v171, v130, v131
	global_store_dwordx4 v51, v[164:167], s[26:27] offset:2048
	global_store_dwordx4 v51, v[168:171], s[26:27] offset:3072
	v_lshlrev_b32_e32 v116, 16, v16
	v_and_b32_e32 v117, 0xffff0000, v16
	v_lshlrev_b32_e32 v118, 16, v17
	v_and_b32_e32 v119, 0xffff0000, v17
	v_lshlrev_b32_e32 v120, 16, v18
	v_and_b32_e32 v121, 0xffff0000, v18
	v_lshlrev_b32_e32 v122, 16, v19
	v_and_b32_e32 v123, 0xffff0000, v19
	v_lshlrev_b32_e32 v124, 16, v20
	v_and_b32_e32 v125, 0xffff0000, v20
	v_lshlrev_b32_e32 v126, 16, v21
	v_and_b32_e32 v127, 0xffff0000, v21
	v_lshlrev_b32_e32 v128, 16, v22
	v_and_b32_e32 v129, 0xffff0000, v22
	v_lshlrev_b32_e32 v130, 16, v23
	v_and_b32_e32 v131, 0xffff0000, v23
	v_pk_mul_f32 v[116:117], v[144:145], v[116:117] op_sel_hi:[0,1]
	v_pk_mul_f32 v[118:119], v[144:145], v[118:119] op_sel_hi:[0,1]
	v_pk_mul_f32 v[120:121], v[144:145], v[120:121] op_sel_hi:[0,1]
	v_pk_mul_f32 v[122:123], v[144:145], v[122:123] op_sel_hi:[0,1]
	v_pk_mul_f32 v[124:125], v[144:145], v[124:125] op_sel_hi:[0,1]
	v_pk_mul_f32 v[126:127], v[144:145], v[126:127] op_sel_hi:[0,1]
	v_pk_mul_f32 v[128:129], v[144:145], v[128:129] op_sel_hi:[0,1]
	v_pk_mul_f32 v[130:131], v[144:145], v[130:131] op_sel_hi:[0,1]
	v_pk_mul_f32 v[116:117], v[116:117], v[32:33]
	v_pk_mul_f32 v[118:119], v[118:119], v[34:35]
	v_pk_mul_f32 v[120:121], v[120:121], v[36:37]
	v_pk_mul_f32 v[122:123], v[122:123], v[38:39]
	v_pk_mul_f32 v[124:125], v[124:125], v[40:41]
	v_pk_mul_f32 v[126:127], v[126:127], v[42:43]
	v_pk_mul_f32 v[128:129], v[128:129], v[44:45]
	v_pk_mul_f32 v[130:131], v[130:131], v[46:47]
	v_pk_fma_f32 v[116:117], v[116:117], v[84:85], v[100:101]
	v_pk_fma_f32 v[118:119], v[118:119], v[86:87], v[102:103]
	v_pk_fma_f32 v[120:121], v[120:121], v[88:89], v[104:105]
	v_pk_fma_f32 v[122:123], v[122:123], v[90:91], v[106:107]
	v_pk_fma_f32 v[124:125], v[124:125], v[92:93], v[108:109]
	v_pk_fma_f32 v[126:127], v[126:127], v[94:95], v[110:111]
	v_pk_fma_f32 v[128:129], v[128:129], v[96:97], v[112:113]
	v_pk_fma_f32 v[130:131], v[130:131], v[98:99], v[114:115]
	v_cvt_pk_bf16_f32 v172, v116, v117
	v_cvt_pk_bf16_f32 v173, v118, v119
	v_cvt_pk_bf16_f32 v174, v120, v121
	v_cvt_pk_bf16_f32 v175, v122, v123
	v_cvt_pk_bf16_f32 v176, v124, v125
	v_cvt_pk_bf16_f32 v177, v126, v127
	v_cvt_pk_bf16_f32 v178, v128, v129
	v_cvt_pk_bf16_f32 v179, v130, v131
	global_store_dwordx4 v149, v[172:175], s[26:27]
	global_store_dwordx4 v149, v[176:179], s[26:27] offset:1024
	v_lshlrev_b32_e32 v116, 16, v24
	v_and_b32_e32 v117, 0xffff0000, v24
	v_lshlrev_b32_e32 v118, 16, v25
	v_and_b32_e32 v119, 0xffff0000, v25
	v_lshlrev_b32_e32 v120, 16, v26
	v_and_b32_e32 v121, 0xffff0000, v26
	v_lshlrev_b32_e32 v122, 16, v27
	v_and_b32_e32 v123, 0xffff0000, v27
	v_lshlrev_b32_e32 v124, 16, v28
	v_and_b32_e32 v125, 0xffff0000, v28
	v_lshlrev_b32_e32 v126, 16, v29
	v_and_b32_e32 v127, 0xffff0000, v29
	v_lshlrev_b32_e32 v128, 16, v30
	v_and_b32_e32 v129, 0xffff0000, v30
	v_lshlrev_b32_e32 v130, 16, v31
	v_and_b32_e32 v131, 0xffff0000, v31
	v_pk_mul_f32 v[116:117], v[146:147], v[116:117] op_sel_hi:[0,1]
	v_pk_mul_f32 v[118:119], v[146:147], v[118:119] op_sel_hi:[0,1]
	v_pk_mul_f32 v[120:121], v[146:147], v[120:121] op_sel_hi:[0,1]
	v_pk_mul_f32 v[122:123], v[146:147], v[122:123] op_sel_hi:[0,1]
	v_pk_mul_f32 v[124:125], v[146:147], v[124:125] op_sel_hi:[0,1]
	v_pk_mul_f32 v[126:127], v[146:147], v[126:127] op_sel_hi:[0,1]
	v_pk_mul_f32 v[128:129], v[146:147], v[128:129] op_sel_hi:[0,1]
	v_pk_mul_f32 v[130:131], v[146:147], v[130:131] op_sel_hi:[0,1]
	v_pk_mul_f32 v[116:117], v[116:117], v[32:33]
	v_pk_mul_f32 v[118:119], v[118:119], v[34:35]
	v_pk_mul_f32 v[120:121], v[120:121], v[36:37]
	v_pk_mul_f32 v[122:123], v[122:123], v[38:39]
	v_pk_mul_f32 v[124:125], v[124:125], v[40:41]
	v_pk_mul_f32 v[126:127], v[126:127], v[42:43]
	v_pk_mul_f32 v[128:129], v[128:129], v[44:45]
	v_pk_mul_f32 v[130:131], v[130:131], v[46:47]
	v_pk_fma_f32 v[116:117], v[116:117], v[84:85], v[100:101]
	v_pk_fma_f32 v[118:119], v[118:119], v[86:87], v[102:103]
	v_pk_fma_f32 v[120:121], v[120:121], v[88:89], v[104:105]
	v_pk_fma_f32 v[122:123], v[122:123], v[90:91], v[106:107]
	v_pk_fma_f32 v[124:125], v[124:125], v[92:93], v[108:109]
	v_pk_fma_f32 v[126:127], v[126:127], v[94:95], v[110:111]
	v_pk_fma_f32 v[128:129], v[128:129], v[96:97], v[112:113]
	v_pk_fma_f32 v[130:131], v[130:131], v[98:99], v[114:115]
	v_cvt_pk_bf16_f32 v164, v116, v117
	v_cvt_pk_bf16_f32 v165, v118, v119
	v_cvt_pk_bf16_f32 v166, v120, v121
	v_cvt_pk_bf16_f32 v167, v122, v123
	v_cvt_pk_bf16_f32 v168, v124, v125
	v_cvt_pk_bf16_f32 v169, v126, v127
	v_cvt_pk_bf16_f32 v170, v128, v129
	v_cvt_pk_bf16_f32 v171, v130, v131
	global_store_dwordx4 v149, v[164:167], s[26:27] offset:2048
	global_store_dwordx4 v149, v[168:171], s[26:27] offset:3072
	s_add_u32 s26, s26, 0x2000
	s_addc_u32 s27, s27, 0
	s_add_u32 s24, s24, 0x2000
	s_addc_u32 s25, s25, 0
	global_load_dwordx4 v[0:3], v51, s[24:25]
	global_load_dwordx4 v[4:7], v51, s[24:25] offset:1024
	global_load_dwordx4 v[8:11], v51, s[24:25] offset:2048
	global_load_dwordx4 v[12:15], v51, s[24:25] offset:3072
	global_load_dwordx4 v[16:19], v149, s[24:25]
	global_load_dwordx4 v[20:23], v149, s[24:25] offset:1024
	global_load_dwordx4 v[24:27], v149, s[24:25] offset:2048
	global_load_dwordx4 v[28:31], v149, s[24:25] offset:3072
	s_waitcnt vmcnt(16)
	v_lshlrev_b32_e32 v116, 16, v52
	v_and_b32_e32 v117, 0xffff0000, v52
	v_lshlrev_b32_e32 v118, 16, v53
	v_and_b32_e32 v119, 0xffff0000, v53
	v_lshlrev_b32_e32 v120, 16, v54
	v_and_b32_e32 v121, 0xffff0000, v54
	v_lshlrev_b32_e32 v122, 16, v55
	v_and_b32_e32 v123, 0xffff0000, v55
	v_lshlrev_b32_e32 v124, 16, v56
	v_and_b32_e32 v125, 0xffff0000, v56
	v_lshlrev_b32_e32 v126, 16, v57
	v_and_b32_e32 v127, 0xffff0000, v57
	v_lshlrev_b32_e32 v128, 16, v58
	v_and_b32_e32 v129, 0xffff0000, v58
	v_lshlrev_b32_e32 v130, 16, v59
	v_and_b32_e32 v131, 0xffff0000, v59
	v_pk_mul_f32 v[132:133], v[116:117], v[116:117]
	v_pk_fma_f32 v[132:133], v[118:119], v[118:119], v[132:133]
	v_pk_fma_f32 v[132:133], v[120:121], v[120:121], v[132:133]
	v_pk_fma_f32 v[132:133], v[122:123], v[122:123], v[132:133]
	v_pk_fma_f32 v[132:133], v[124:125], v[124:125], v[132:133]
	v_pk_fma_f32 v[132:133], v[126:127], v[126:127], v[132:133]
	v_pk_fma_f32 v[132:133], v[128:129], v[128:129], v[132:133]
	v_pk_fma_f32 v[132:133], v[130:131], v[130:131], v[132:133]
	v_lshlrev_b32_e32 v116, 16, v60
	v_and_b32_e32 v117, 0xffff0000, v60
	v_lshlrev_b32_e32 v118, 16, v61
	v_and_b32_e32 v119, 0xffff0000, v61
	v_lshlrev_b32_e32 v120, 16, v62
	v_and_b32_e32 v121, 0xffff0000, v62
	v_lshlrev_b32_e32 v122, 16, v63
	v_and_b32_e32 v123, 0xffff0000, v63
	v_lshlrev_b32_e32 v124, 16, v64
	v_and_b32_e32 v125, 0xffff0000, v64
	v_lshlrev_b32_e32 v126, 16, v65
	v_and_b32_e32 v127, 0xffff0000, v65
	v_lshlrev_b32_e32 v128, 16, v66
	v_and_b32_e32 v129, 0xffff0000, v66
	v_lshlrev_b32_e32 v130, 16, v67
	v_and_b32_e32 v131, 0xffff0000, v67
	v_pk_mul_f32 v[134:135], v[116:117], v[116:117]
	v_pk_fma_f32 v[134:135], v[118:119], v[118:119], v[134:135]
	v_pk_fma_f32 v[134:135], v[120:121], v[120:121], v[134:135]
	v_pk_fma_f32 v[134:135], v[122:123], v[122:123], v[134:135]
	v_pk_fma_f32 v[134:135], v[124:125], v[124:125], v[134:135]
	v_pk_fma_f32 v[134:135], v[126:127], v[126:127], v[134:135]
	v_pk_fma_f32 v[134:135], v[128:129], v[128:129], v[134:135]
	v_pk_fma_f32 v[134:135], v[130:131], v[130:131], v[134:135]
	v_lshlrev_b32_e32 v116, 16, v68
	v_and_b32_e32 v117, 0xffff0000, v68
	v_lshlrev_b32_e32 v118, 16, v69
	v_and_b32_e32 v119, 0xffff0000, v69
	v_lshlrev_b32_e32 v120, 16, v70
	v_and_b32_e32 v121, 0xffff0000, v70
	v_lshlrev_b32_e32 v122, 16, v71
	v_and_b32_e32 v123, 0xffff0000, v71
	v_lshlrev_b32_e32 v124, 16, v72
	v_and_b32_e32 v125, 0xffff0000, v72
	v_lshlrev_b32_e32 v126, 16, v73
	v_and_b32_e32 v127, 0xffff0000, v73
	v_lshlrev_b32_e32 v128, 16, v74
	v_and_b32_e32 v129, 0xffff0000, v74
	v_lshlrev_b32_e32 v130, 16, v75
	v_and_b32_e32 v131, 0xffff0000, v75
	v_pk_mul_f32 v[136:137], v[116:117], v[116:117]
	v_pk_fma_f32 v[136:137], v[118:119], v[118:119], v[136:137]
	v_pk_fma_f32 v[136:137], v[120:121], v[120:121], v[136:137]
	v_pk_fma_f32 v[136:137], v[122:123], v[122:123], v[136:137]
	v_pk_fma_f32 v[136:137], v[124:125], v[124:125], v[136:137]
	v_pk_fma_f32 v[136:137], v[126:127], v[126:127], v[136:137]
	v_pk_fma_f32 v[136:137], v[128:129], v[128:129], v[136:137]
	v_pk_fma_f32 v[136:137], v[130:131], v[130:131], v[136:137]
	v_lshlrev_b32_e32 v116, 16, v76
	v_and_b32_e32 v117, 0xffff0000, v76
	v_lshlrev_b32_e32 v118, 16, v77
	v_and_b32_e32 v119, 0xffff0000, v77
	v_lshlrev_b32_e32 v120, 16, v78
	v_and_b32_e32 v121, 0xffff0000, v78
	v_lshlrev_b32_e32 v122, 16, v79
	v_and_b32_e32 v123, 0xffff0000, v79
	v_lshlrev_b32_e32 v124, 16, v80
	v_and_b32_e32 v125, 0xffff0000, v80
	v_lshlrev_b32_e32 v126, 16, v81
	v_and_b32_e32 v127, 0xffff0000, v81
	v_lshlrev_b32_e32 v128, 16, v82
	v_and_b32_e32 v129, 0xffff0000, v82
	v_lshlrev_b32_e32 v130, 16, v83
	v_and_b32_e32 v131, 0xffff0000, v83
	v_pk_mul_f32 v[138:139], v[116:117], v[116:117]
	v_pk_fma_f32 v[138:139], v[118:119], v[118:119], v[138:139]
	v_pk_fma_f32 v[138:139], v[120:121], v[120:121], v[138:139]
	v_pk_fma_f32 v[138:139], v[122:123], v[122:123], v[138:139]
	v_pk_fma_f32 v[138:139], v[124:125], v[124:125], v[138:139]
	v_pk_fma_f32 v[138:139], v[126:127], v[126:127], v[138:139]
	v_pk_fma_f32 v[138:139], v[128:129], v[128:129], v[138:139]
	v_pk_fma_f32 v[138:139], v[130:131], v[130:131], v[138:139]
	v_add_f32_e32 v132, v132, v133
	v_add_f32_e32 v134, v134, v135
	v_add_f32_e32 v136, v136, v137
	v_add_f32_e32 v138, v138, v139
	s_nop 1
	v_add_f32_dpp v132, v132, v132 row_shr:1 row_mask:0xf bank_mask:0xf bound_ctrl:1
	v_add_f32_dpp v134, v134, v134 row_shr:1 row_mask:0xf bank_mask:0xf bound_ctrl:1
	v_add_f32_dpp v136, v136, v136 row_shr:1 row_mask:0xf bank_mask:0xf bound_ctrl:1
	v_add_f32_dpp v138, v138, v138 row_shr:1 row_mask:0xf bank_mask:0xf bound_ctrl:1
	v_add_f32_dpp v132, v132, v132 row_shr:2 row_mask:0xf bank_mask:0xf bound_ctrl:1
	v_add_f32_dpp v134, v134, v134 row_shr:2 row_mask:0xf bank_mask:0xf bound_ctrl:1
	v_add_f32_dpp v136, v136, v136 row_shr:2 row_mask:0xf bank_mask:0xf bound_ctrl:1
	v_add_f32_dpp v138, v138, v138 row_shr:2 row_mask:0xf bank_mask:0xf bound_ctrl:1
	v_add_f32_dpp v132, v132, v132 row_shr:4 row_mask:0xf bank_mask:0xf bound_ctrl:1
	v_add_f32_dpp v134, v134, v134 row_shr:4 row_mask:0xf bank_mask:0xf bound_ctrl:1
	v_add_f32_dpp v136, v136, v136 row_shr:4 row_mask:0xf bank_mask:0xf bound_ctrl:1
	v_add_f32_dpp v138, v138, v138 row_shr:4 row_mask:0xf bank_mask:0xf bound_ctrl:1
	v_add_f32_dpp v132, v132, v132 row_shr:8 row_mask:0xf bank_mask:0xf bound_ctrl:1
	v_add_f32_dpp v134, v134, v134 row_shr:8 row_mask:0xf bank_mask:0xf bound_ctrl:1
	v_add_f32_dpp v136, v136, v136 row_shr:8 row_mask:0xf bank_mask:0xf bound_ctrl:1
	v_add_f32_dpp v138, v138, v138 row_shr:8 row_mask:0xf bank_mask:0xf bound_ctrl:1
	v_add_f32_dpp v132, v132, v132 row_bcast:15 row_mask:0xa bank_mask:0xf
	v_add_f32_dpp v134, v134, v134 row_bcast:15 row_mask:0xa bank_mask:0xf
	v_add_f32_dpp v136, v136, v136 row_bcast:15 row_mask:0xa bank_mask:0xf
	v_add_f32_dpp v138, v138, v138 row_bcast:15 row_mask:0xa bank_mask:0xf
	v_add_f32_dpp v132, v132, v132 row_bcast:31 row_mask:0xc bank_mask:0xf
	v_add_f32_dpp v134, v134, v134 row_bcast:31 row_mask:0xc bank_mask:0xf
	v_add_f32_dpp v136, v136, v136 row_bcast:31 row_mask:0xc bank_mask:0xf
	v_add_f32_dpp v138, v138, v138 row_bcast:31 row_mask:0xc bank_mask:0xf
	s_nop 1
	v_readlane_b32 s32, v132, 63
	v_readlane_b32 s28, v134, 63
	v_readlane_b32 s29, v136, 63
	v_readlane_b32 s30, v138, 63
	s_nop 1
	v_mov_b32_e32 v140, s32
	v_mov_b32_e32 v142, s28
	v_mov_b32_e32 v144, s29
	v_mov_b32_e32 v146, s30
	v_fmaak_f32 v140, v140, v50, 0x358637bd
	v_fmaak_f32 v142, v142, v50, 0x358637bd
	v_fmaak_f32 v144, v144, v50, 0x358637bd
	v_fmaak_f32 v146, v146, v50, 0x358637bd
	v_rsq_f32_e32 v140, v140
	v_rsq_f32_e32 v142, v142
	v_rsq_f32_e32 v144, v144
	v_rsq_f32_e32 v146, v146
	s_nop 0
	v_lshlrev_b32_e32 v116, 16, v52
	v_and_b32_e32 v117, 0xffff0000, v52
	v_lshlrev_b32_e32 v118, 16, v53
	v_and_b32_e32 v119, 0xffff0000, v53
	v_lshlrev_b32_e32 v120, 16, v54
	v_and_b32_e32 v121, 0xffff0000, v54
	v_lshlrev_b32_e32 v122, 16, v55
	v_and_b32_e32 v123, 0xffff0000, v55
	v_lshlrev_b32_e32 v124, 16, v56
	v_and_b32_e32 v125, 0xffff0000, v56
	v_lshlrev_b32_e32 v126, 16, v57
	v_and_b32_e32 v127, 0xffff0000, v57
	v_lshlrev_b32_e32 v128, 16, v58
	v_and_b32_e32 v129, 0xffff0000, v58
	v_lshlrev_b32_e32 v130, 16, v59
	v_and_b32_e32 v131, 0xffff0000, v59
	v_pk_mul_f32 v[116:117], v[140:141], v[116:117] op_sel_hi:[0,1]
	v_pk_mul_f32 v[118:119], v[140:141], v[118:119] op_sel_hi:[0,1]
	v_pk_mul_f32 v[120:121], v[140:141], v[120:121] op_sel_hi:[0,1]
	v_pk_mul_f32 v[122:123], v[140:141], v[122:123] op_sel_hi:[0,1]
	v_pk_mul_f32 v[124:125], v[140:141], v[124:125] op_sel_hi:[0,1]
	v_pk_mul_f32 v[126:127], v[140:141], v[126:127] op_sel_hi:[0,1]
	v_pk_mul_f32 v[128:129], v[140:141], v[128:129] op_sel_hi:[0,1]
	v_pk_mul_f32 v[130:131], v[140:141], v[130:131] op_sel_hi:[0,1]
	v_pk_mul_f32 v[116:117], v[116:117], v[32:33]
	v_pk_mul_f32 v[118:119], v[118:119], v[34:35]
	v_pk_mul_f32 v[120:121], v[120:121], v[36:37]
	v_pk_mul_f32 v[122:123], v[122:123], v[38:39]
	v_pk_mul_f32 v[124:125], v[124:125], v[40:41]
	v_pk_mul_f32 v[126:127], v[126:127], v[42:43]
	v_pk_mul_f32 v[128:129], v[128:129], v[44:45]
	v_pk_mul_f32 v[130:131], v[130:131], v[46:47]
	v_pk_fma_f32 v[116:117], v[116:117], v[84:85], v[100:101]
	v_pk_fma_f32 v[118:119], v[118:119], v[86:87], v[102:103]
	v_pk_fma_f32 v[120:121], v[120:121], v[88:89], v[104:105]
	v_pk_fma_f32 v[122:123], v[122:123], v[90:91], v[106:107]
	v_pk_fma_f32 v[124:125], v[124:125], v[92:93], v[108:109]
	v_pk_fma_f32 v[126:127], v[126:127], v[94:95], v[110:111]
	v_pk_fma_f32 v[128:129], v[128:129], v[96:97], v[112:113]
	v_pk_fma_f32 v[130:131], v[130:131], v[98:99], v[114:115]
	v_cvt_pk_bf16_f32 v164, v116, v117
	v_cvt_pk_bf16_f32 v165, v118, v119
	v_cvt_pk_bf16_f32 v166, v120, v121
	v_cvt_pk_bf16_f32 v167, v122, v123
	v_cvt_pk_bf16_f32 v168, v124, v125
	v_cvt_pk_bf16_f32 v169, v126, v127
	v_cvt_pk_bf16_f32 v170, v128, v129
	v_cvt_pk_bf16_f32 v171, v130, v131
	global_store_dwordx4 v51, v[164:167], s[26:27]
	global_store_dwordx4 v51, v[168:171], s[26:27] offset:1024
	v_lshlrev_b32_e32 v116, 16, v60
	v_and_b32_e32 v117, 0xffff0000, v60
	v_lshlrev_b32_e32 v118, 16, v61
	v_and_b32_e32 v119, 0xffff0000, v61
	v_lshlrev_b32_e32 v120, 16, v62
	v_and_b32_e32 v121, 0xffff0000, v62
	v_lshlrev_b32_e32 v122, 16, v63
	v_and_b32_e32 v123, 0xffff0000, v63
	v_lshlrev_b32_e32 v124, 16, v64
	v_and_b32_e32 v125, 0xffff0000, v64
	v_lshlrev_b32_e32 v126, 16, v65
	v_and_b32_e32 v127, 0xffff0000, v65
	v_lshlrev_b32_e32 v128, 16, v66
	v_and_b32_e32 v129, 0xffff0000, v66
	v_lshlrev_b32_e32 v130, 16, v67
	v_and_b32_e32 v131, 0xffff0000, v67
	v_pk_mul_f32 v[116:117], v[142:143], v[116:117] op_sel_hi:[0,1]
	v_pk_mul_f32 v[118:119], v[142:143], v[118:119] op_sel_hi:[0,1]
	v_pk_mul_f32 v[120:121], v[142:143], v[120:121] op_sel_hi:[0,1]
	v_pk_mul_f32 v[122:123], v[142:143], v[122:123] op_sel_hi:[0,1]
	v_pk_mul_f32 v[124:125], v[142:143], v[124:125] op_sel_hi:[0,1]
	v_pk_mul_f32 v[126:127], v[142:143], v[126:127] op_sel_hi:[0,1]
	v_pk_mul_f32 v[128:129], v[142:143], v[128:129] op_sel_hi:[0,1]
	v_pk_mul_f32 v[130:131], v[142:143], v[130:131] op_sel_hi:[0,1]
	v_pk_mul_f32 v[116:117], v[116:117], v[32:33]
	v_pk_mul_f32 v[118:119], v[118:119], v[34:35]
	v_pk_mul_f32 v[120:121], v[120:121], v[36:37]
	v_pk_mul_f32 v[122:123], v[122:123], v[38:39]
	v_pk_mul_f32 v[124:125], v[124:125], v[40:41]
	v_pk_mul_f32 v[126:127], v[126:127], v[42:43]
	v_pk_mul_f32 v[128:129], v[128:129], v[44:45]
	v_pk_mul_f32 v[130:131], v[130:131], v[46:47]
	v_pk_fma_f32 v[116:117], v[116:117], v[84:85], v[100:101]
	v_pk_fma_f32 v[118:119], v[118:119], v[86:87], v[102:103]
	v_pk_fma_f32 v[120:121], v[120:121], v[88:89], v[104:105]
	v_pk_fma_f32 v[122:123], v[122:123], v[90:91], v[106:107]
	v_pk_fma_f32 v[124:125], v[124:125], v[92:93], v[108:109]
	v_pk_fma_f32 v[126:127], v[126:127], v[94:95], v[110:111]
	v_pk_fma_f32 v[128:129], v[128:129], v[96:97], v[112:113]
	v_pk_fma_f32 v[130:131], v[130:131], v[98:99], v[114:115]
	v_cvt_pk_bf16_f32 v172, v116, v117
	v_cvt_pk_bf16_f32 v173, v118, v119
	v_cvt_pk_bf16_f32 v174, v120, v121
	v_cvt_pk_bf16_f32 v175, v122, v123
	v_cvt_pk_bf16_f32 v176, v124, v125
	v_cvt_pk_bf16_f32 v177, v126, v127
	v_cvt_pk_bf16_f32 v178, v128, v129
	v_cvt_pk_bf16_f32 v179, v130, v131
	global_store_dwordx4 v51, v[172:175], s[26:27] offset:2048
	global_store_dwordx4 v51, v[176:179], s[26:27] offset:3072
	v_lshlrev_b32_e32 v116, 16, v68
	v_and_b32_e32 v117, 0xffff0000, v68
	v_lshlrev_b32_e32 v118, 16, v69
	v_and_b32_e32 v119, 0xffff0000, v69
	v_lshlrev_b32_e32 v120, 16, v70
	v_and_b32_e32 v121, 0xffff0000, v70
	v_lshlrev_b32_e32 v122, 16, v71
	v_and_b32_e32 v123, 0xffff0000, v71
	v_lshlrev_b32_e32 v124, 16, v72
	v_and_b32_e32 v125, 0xffff0000, v72
	v_lshlrev_b32_e32 v126, 16, v73
	v_and_b32_e32 v127, 0xffff0000, v73
	v_lshlrev_b32_e32 v128, 16, v74
	v_and_b32_e32 v129, 0xffff0000, v74
	v_lshlrev_b32_e32 v130, 16, v75
	v_and_b32_e32 v131, 0xffff0000, v75
	v_pk_mul_f32 v[116:117], v[144:145], v[116:117] op_sel_hi:[0,1]
	v_pk_mul_f32 v[118:119], v[144:145], v[118:119] op_sel_hi:[0,1]
	v_pk_mul_f32 v[120:121], v[144:145], v[120:121] op_sel_hi:[0,1]
	v_pk_mul_f32 v[122:123], v[144:145], v[122:123] op_sel_hi:[0,1]
	v_pk_mul_f32 v[124:125], v[144:145], v[124:125] op_sel_hi:[0,1]
	v_pk_mul_f32 v[126:127], v[144:145], v[126:127] op_sel_hi:[0,1]
	v_pk_mul_f32 v[128:129], v[144:145], v[128:129] op_sel_hi:[0,1]
	v_pk_mul_f32 v[130:131], v[144:145], v[130:131] op_sel_hi:[0,1]
	v_pk_mul_f32 v[116:117], v[116:117], v[32:33]
	v_pk_mul_f32 v[118:119], v[118:119], v[34:35]
	v_pk_mul_f32 v[120:121], v[120:121], v[36:37]
	v_pk_mul_f32 v[122:123], v[122:123], v[38:39]
	v_pk_mul_f32 v[124:125], v[124:125], v[40:41]
	v_pk_mul_f32 v[126:127], v[126:127], v[42:43]
	v_pk_mul_f32 v[128:129], v[128:129], v[44:45]
	v_pk_mul_f32 v[130:131], v[130:131], v[46:47]
	v_pk_fma_f32 v[116:117], v[116:117], v[84:85], v[100:101]
	v_pk_fma_f32 v[118:119], v[118:119], v[86:87], v[102:103]
	v_pk_fma_f32 v[120:121], v[120:121], v[88:89], v[104:105]
	v_pk_fma_f32 v[122:123], v[122:123], v[90:91], v[106:107]
	v_pk_fma_f32 v[124:125], v[124:125], v[92:93], v[108:109]
	v_pk_fma_f32 v[126:127], v[126:127], v[94:95], v[110:111]
	v_pk_fma_f32 v[128:129], v[128:129], v[96:97], v[112:113]
	v_pk_fma_f32 v[130:131], v[130:131], v[98:99], v[114:115]
	v_cvt_pk_bf16_f32 v164, v116, v117
	v_cvt_pk_bf16_f32 v165, v118, v119
	v_cvt_pk_bf16_f32 v166, v120, v121
	v_cvt_pk_bf16_f32 v167, v122, v123
	v_cvt_pk_bf16_f32 v168, v124, v125
	v_cvt_pk_bf16_f32 v169, v126, v127
	v_cvt_pk_bf16_f32 v170, v128, v129
	v_cvt_pk_bf16_f32 v171, v130, v131
	global_store_dwordx4 v149, v[164:167], s[26:27]
	global_store_dwordx4 v149, v[168:171], s[26:27] offset:1024
	v_lshlrev_b32_e32 v116, 16, v76
	v_and_b32_e32 v117, 0xffff0000, v76
	v_lshlrev_b32_e32 v118, 16, v77
	v_and_b32_e32 v119, 0xffff0000, v77
	v_lshlrev_b32_e32 v120, 16, v78
	v_and_b32_e32 v121, 0xffff0000, v78
	v_lshlrev_b32_e32 v122, 16, v79
	v_and_b32_e32 v123, 0xffff0000, v79
	v_lshlrev_b32_e32 v124, 16, v80
	v_and_b32_e32 v125, 0xffff0000, v80
	v_lshlrev_b32_e32 v126, 16, v81
	v_and_b32_e32 v127, 0xffff0000, v81
	v_lshlrev_b32_e32 v128, 16, v82
	v_and_b32_e32 v129, 0xffff0000, v82
	v_lshlrev_b32_e32 v130, 16, v83
	v_and_b32_e32 v131, 0xffff0000, v83
	v_pk_mul_f32 v[116:117], v[146:147], v[116:117] op_sel_hi:[0,1]
	v_pk_mul_f32 v[118:119], v[146:147], v[118:119] op_sel_hi:[0,1]
	v_pk_mul_f32 v[120:121], v[146:147], v[120:121] op_sel_hi:[0,1]
	v_pk_mul_f32 v[122:123], v[146:147], v[122:123] op_sel_hi:[0,1]
	v_pk_mul_f32 v[124:125], v[146:147], v[124:125] op_sel_hi:[0,1]
	v_pk_mul_f32 v[126:127], v[146:147], v[126:127] op_sel_hi:[0,1]
	v_pk_mul_f32 v[128:129], v[146:147], v[128:129] op_sel_hi:[0,1]
	v_pk_mul_f32 v[130:131], v[146:147], v[130:131] op_sel_hi:[0,1]
	v_pk_mul_f32 v[116:117], v[116:117], v[32:33]
	v_pk_mul_f32 v[118:119], v[118:119], v[34:35]
	v_pk_mul_f32 v[120:121], v[120:121], v[36:37]
	v_pk_mul_f32 v[122:123], v[122:123], v[38:39]
	v_pk_mul_f32 v[124:125], v[124:125], v[40:41]
	v_pk_mul_f32 v[126:127], v[126:127], v[42:43]
	v_pk_mul_f32 v[128:129], v[128:129], v[44:45]
	v_pk_mul_f32 v[130:131], v[130:131], v[46:47]
	v_pk_fma_f32 v[116:117], v[116:117], v[84:85], v[100:101]
	v_pk_fma_f32 v[118:119], v[118:119], v[86:87], v[102:103]
	v_pk_fma_f32 v[120:121], v[120:121], v[88:89], v[104:105]
	v_pk_fma_f32 v[122:123], v[122:123], v[90:91], v[106:107]
	v_pk_fma_f32 v[124:125], v[124:125], v[92:93], v[108:109]
	v_pk_fma_f32 v[126:127], v[126:127], v[94:95], v[110:111]
	v_pk_fma_f32 v[128:129], v[128:129], v[96:97], v[112:113]
	v_pk_fma_f32 v[130:131], v[130:131], v[98:99], v[114:115]
	v_cvt_pk_bf16_f32 v172, v116, v117
	v_cvt_pk_bf16_f32 v173, v118, v119
	v_cvt_pk_bf16_f32 v174, v120, v121
	v_cvt_pk_bf16_f32 v175, v122, v123
	v_cvt_pk_bf16_f32 v176, v124, v125
	v_cvt_pk_bf16_f32 v177, v126, v127
	v_cvt_pk_bf16_f32 v178, v128, v129
	v_cvt_pk_bf16_f32 v179, v130, v131
	global_store_dwordx4 v149, v[172:175], s[26:27] offset:2048
	global_store_dwordx4 v149, v[176:179], s[26:27] offset:3072
	s_add_u32 s26, s26, 0x2000
	s_addc_u32 s27, s27, 0
	s_waitcnt vmcnt(8)
	v_lshlrev_b32_e32 v116, 16, v0
	v_and_b32_e32 v117, 0xffff0000, v0
	v_lshlrev_b32_e32 v118, 16, v1
	v_and_b32_e32 v119, 0xffff0000, v1
	v_lshlrev_b32_e32 v120, 16, v2
	v_and_b32_e32 v121, 0xffff0000, v2
	v_lshlrev_b32_e32 v122, 16, v3
	v_and_b32_e32 v123, 0xffff0000, v3
	v_lshlrev_b32_e32 v124, 16, v4
	v_and_b32_e32 v125, 0xffff0000, v4
	v_lshlrev_b32_e32 v126, 16, v5
	v_and_b32_e32 v127, 0xffff0000, v5
	v_lshlrev_b32_e32 v128, 16, v6
	v_and_b32_e32 v129, 0xffff0000, v6
	v_lshlrev_b32_e32 v130, 16, v7
	v_and_b32_e32 v131, 0xffff0000, v7
	v_pk_mul_f32 v[132:133], v[116:117], v[116:117]
	v_pk_fma_f32 v[132:133], v[118:119], v[118:119], v[132:133]
	v_pk_fma_f32 v[132:133], v[120:121], v[120:121], v[132:133]
	v_pk_fma_f32 v[132:133], v[122:123], v[122:123], v[132:133]
	v_pk_fma_f32 v[132:133], v[124:125], v[124:125], v[132:133]
	v_pk_fma_f32 v[132:133], v[126:127], v[126:127], v[132:133]
	v_pk_fma_f32 v[132:133], v[128:129], v[128:129], v[132:133]
	v_pk_fma_f32 v[132:133], v[130:131], v[130:131], v[132:133]
	v_lshlrev_b32_e32 v116, 16, v8
	v_and_b32_e32 v117, 0xffff0000, v8
	v_lshlrev_b32_e32 v118, 16, v9
	v_and_b32_e32 v119, 0xffff0000, v9
	v_lshlrev_b32_e32 v120, 16, v10
	v_and_b32_e32 v121, 0xffff0000, v10
	v_lshlrev_b32_e32 v122, 16, v11
	v_and_b32_e32 v123, 0xffff0000, v11
	v_lshlrev_b32_e32 v124, 16, v12
	v_and_b32_e32 v125, 0xffff0000, v12
	v_lshlrev_b32_e32 v126, 16, v13
	v_and_b32_e32 v127, 0xffff0000, v13
	v_lshlrev_b32_e32 v128, 16, v14
	v_and_b32_e32 v129, 0xffff0000, v14
	v_lshlrev_b32_e32 v130, 16, v15
	v_and_b32_e32 v131, 0xffff0000, v15
	v_pk_mul_f32 v[134:135], v[116:117], v[116:117]
	v_pk_fma_f32 v[134:135], v[118:119], v[118:119], v[134:135]
	v_pk_fma_f32 v[134:135], v[120:121], v[120:121], v[134:135]
	v_pk_fma_f32 v[134:135], v[122:123], v[122:123], v[134:135]
	v_pk_fma_f32 v[134:135], v[124:125], v[124:125], v[134:135]
	v_pk_fma_f32 v[134:135], v[126:127], v[126:127], v[134:135]
	v_pk_fma_f32 v[134:135], v[128:129], v[128:129], v[134:135]
	v_pk_fma_f32 v[134:135], v[130:131], v[130:131], v[134:135]
	v_lshlrev_b32_e32 v116, 16, v16
	v_and_b32_e32 v117, 0xffff0000, v16
	v_lshlrev_b32_e32 v118, 16, v17
	v_and_b32_e32 v119, 0xffff0000, v17
	v_lshlrev_b32_e32 v120, 16, v18
	v_and_b32_e32 v121, 0xffff0000, v18
	v_lshlrev_b32_e32 v122, 16, v19
	v_and_b32_e32 v123, 0xffff0000, v19
	v_lshlrev_b32_e32 v124, 16, v20
	v_and_b32_e32 v125, 0xffff0000, v20
	v_lshlrev_b32_e32 v126, 16, v21
	v_and_b32_e32 v127, 0xffff0000, v21
	v_lshlrev_b32_e32 v128, 16, v22
	v_and_b32_e32 v129, 0xffff0000, v22
	v_lshlrev_b32_e32 v130, 16, v23
	v_and_b32_e32 v131, 0xffff0000, v23
	v_pk_mul_f32 v[136:137], v[116:117], v[116:117]
	v_pk_fma_f32 v[136:137], v[118:119], v[118:119], v[136:137]
	v_pk_fma_f32 v[136:137], v[120:121], v[120:121], v[136:137]
	v_pk_fma_f32 v[136:137], v[122:123], v[122:123], v[136:137]
	v_pk_fma_f32 v[136:137], v[124:125], v[124:125], v[136:137]
	v_pk_fma_f32 v[136:137], v[126:127], v[126:127], v[136:137]
	v_pk_fma_f32 v[136:137], v[128:129], v[128:129], v[136:137]
	v_pk_fma_f32 v[136:137], v[130:131], v[130:131], v[136:137]
	v_lshlrev_b32_e32 v116, 16, v24
	v_and_b32_e32 v117, 0xffff0000, v24
	v_lshlrev_b32_e32 v118, 16, v25
	v_and_b32_e32 v119, 0xffff0000, v25
	v_lshlrev_b32_e32 v120, 16, v26
	v_and_b32_e32 v121, 0xffff0000, v26
	v_lshlrev_b32_e32 v122, 16, v27
	v_and_b32_e32 v123, 0xffff0000, v27
	v_lshlrev_b32_e32 v124, 16, v28
	v_and_b32_e32 v125, 0xffff0000, v28
	v_lshlrev_b32_e32 v126, 16, v29
	v_and_b32_e32 v127, 0xffff0000, v29
	v_lshlrev_b32_e32 v128, 16, v30
	v_and_b32_e32 v129, 0xffff0000, v30
	v_lshlrev_b32_e32 v130, 16, v31
	v_and_b32_e32 v131, 0xffff0000, v31
	v_pk_mul_f32 v[138:139], v[116:117], v[116:117]
	v_pk_fma_f32 v[138:139], v[118:119], v[118:119], v[138:139]
	v_pk_fma_f32 v[138:139], v[120:121], v[120:121], v[138:139]
	v_pk_fma_f32 v[138:139], v[122:123], v[122:123], v[138:139]
	v_pk_fma_f32 v[138:139], v[124:125], v[124:125], v[138:139]
	v_pk_fma_f32 v[138:139], v[126:127], v[126:127], v[138:139]
	v_pk_fma_f32 v[138:139], v[128:129], v[128:129], v[138:139]
	v_pk_fma_f32 v[138:139], v[130:131], v[130:131], v[138:139]
	v_add_f32_e32 v132, v132, v133
	v_add_f32_e32 v134, v134, v135
	v_add_f32_e32 v136, v136, v137
	v_add_f32_e32 v138, v138, v139
	s_nop 1
	v_add_f32_dpp v132, v132, v132 row_shr:1 row_mask:0xf bank_mask:0xf bound_ctrl:1
	v_add_f32_dpp v134, v134, v134 row_shr:1 row_mask:0xf bank_mask:0xf bound_ctrl:1
	v_add_f32_dpp v136, v136, v136 row_shr:1 row_mask:0xf bank_mask:0xf bound_ctrl:1
	v_add_f32_dpp v138, v138, v138 row_shr:1 row_mask:0xf bank_mask:0xf bound_ctrl:1
	v_add_f32_dpp v132, v132, v132 row_shr:2 row_mask:0xf bank_mask:0xf bound_ctrl:1
	v_add_f32_dpp v134, v134, v134 row_shr:2 row_mask:0xf bank_mask:0xf bound_ctrl:1
	v_add_f32_dpp v136, v136, v136 row_shr:2 row_mask:0xf bank_mask:0xf bound_ctrl:1
	v_add_f32_dpp v138, v138, v138 row_shr:2 row_mask:0xf bank_mask:0xf bound_ctrl:1
	v_add_f32_dpp v132, v132, v132 row_shr:4 row_mask:0xf bank_mask:0xf bound_ctrl:1
	v_add_f32_dpp v134, v134, v134 row_shr:4 row_mask:0xf bank_mask:0xf bound_ctrl:1
	v_add_f32_dpp v136, v136, v136 row_shr:4 row_mask:0xf bank_mask:0xf bound_ctrl:1
	v_add_f32_dpp v138, v138, v138 row_shr:4 row_mask:0xf bank_mask:0xf bound_ctrl:1
	v_add_f32_dpp v132, v132, v132 row_shr:8 row_mask:0xf bank_mask:0xf bound_ctrl:1
	v_add_f32_dpp v134, v134, v134 row_shr:8 row_mask:0xf bank_mask:0xf bound_ctrl:1
	v_add_f32_dpp v136, v136, v136 row_shr:8 row_mask:0xf bank_mask:0xf bound_ctrl:1
	v_add_f32_dpp v138, v138, v138 row_shr:8 row_mask:0xf bank_mask:0xf bound_ctrl:1
	v_add_f32_dpp v132, v132, v132 row_bcast:15 row_mask:0xa bank_mask:0xf
	v_add_f32_dpp v134, v134, v134 row_bcast:15 row_mask:0xa bank_mask:0xf
	v_add_f32_dpp v136, v136, v136 row_bcast:15 row_mask:0xa bank_mask:0xf
	v_add_f32_dpp v138, v138, v138 row_bcast:15 row_mask:0xa bank_mask:0xf
	v_add_f32_dpp v132, v132, v132 row_bcast:31 row_mask:0xc bank_mask:0xf
	v_add_f32_dpp v134, v134, v134 row_bcast:31 row_mask:0xc bank_mask:0xf
	v_add_f32_dpp v136, v136, v136 row_bcast:31 row_mask:0xc bank_mask:0xf
	v_add_f32_dpp v138, v138, v138 row_bcast:31 row_mask:0xc bank_mask:0xf
	s_nop 1
	v_readlane_b32 s32, v132, 63
	v_readlane_b32 s28, v134, 63
	v_readlane_b32 s29, v136, 63
	v_readlane_b32 s30, v138, 63
	s_nop 1
	v_mov_b32_e32 v140, s32
	v_mov_b32_e32 v142, s28
	v_mov_b32_e32 v144, s29
	v_mov_b32_e32 v146, s30
	v_fmaak_f32 v140, v140, v50, 0x358637bd
	v_fmaak_f32 v142, v142, v50, 0x358637bd
	v_fmaak_f32 v144, v144, v50, 0x358637bd
	v_fmaak_f32 v146, v146, v50, 0x358637bd
	v_rsq_f32_e32 v140, v140
	v_rsq_f32_e32 v142, v142
	v_rsq_f32_e32 v144, v144
	v_rsq_f32_e32 v146, v146
	s_nop 0
	v_lshlrev_b32_e32 v116, 16, v0
	v_and_b32_e32 v117, 0xffff0000, v0
	v_lshlrev_b32_e32 v118, 16, v1
	v_and_b32_e32 v119, 0xffff0000, v1
	v_lshlrev_b32_e32 v120, 16, v2
	v_and_b32_e32 v121, 0xffff0000, v2
	v_lshlrev_b32_e32 v122, 16, v3
	v_and_b32_e32 v123, 0xffff0000, v3
	v_lshlrev_b32_e32 v124, 16, v4
	v_and_b32_e32 v125, 0xffff0000, v4
	v_lshlrev_b32_e32 v126, 16, v5
	v_and_b32_e32 v127, 0xffff0000, v5
	v_lshlrev_b32_e32 v128, 16, v6
	v_and_b32_e32 v129, 0xffff0000, v6
	v_lshlrev_b32_e32 v130, 16, v7
	v_and_b32_e32 v131, 0xffff0000, v7
	v_pk_mul_f32 v[116:117], v[140:141], v[116:117] op_sel_hi:[0,1]
	v_pk_mul_f32 v[118:119], v[140:141], v[118:119] op_sel_hi:[0,1]
	v_pk_mul_f32 v[120:121], v[140:141], v[120:121] op_sel_hi:[0,1]
	v_pk_mul_f32 v[122:123], v[140:141], v[122:123] op_sel_hi:[0,1]
	v_pk_mul_f32 v[124:125], v[140:141], v[124:125] op_sel_hi:[0,1]
	v_pk_mul_f32 v[126:127], v[140:141], v[126:127] op_sel_hi:[0,1]
	v_pk_mul_f32 v[128:129], v[140:141], v[128:129] op_sel_hi:[0,1]
	v_pk_mul_f32 v[130:131], v[140:141], v[130:131] op_sel_hi:[0,1]
	v_pk_mul_f32 v[116:117], v[116:117], v[32:33]
	v_pk_mul_f32 v[118:119], v[118:119], v[34:35]
	v_pk_mul_f32 v[120:121], v[120:121], v[36:37]
	v_pk_mul_f32 v[122:123], v[122:123], v[38:39]
	v_pk_mul_f32 v[124:125], v[124:125], v[40:41]
	v_pk_mul_f32 v[126:127], v[126:127], v[42:43]
	v_pk_mul_f32 v[128:129], v[128:129], v[44:45]
	v_pk_mul_f32 v[130:131], v[130:131], v[46:47]
	v_pk_fma_f32 v[116:117], v[116:117], v[84:85], v[100:101]
	v_pk_fma_f32 v[118:119], v[118:119], v[86:87], v[102:103]
	v_pk_fma_f32 v[120:121], v[120:121], v[88:89], v[104:105]
	v_pk_fma_f32 v[122:123], v[122:123], v[90:91], v[106:107]
	v_pk_fma_f32 v[124:125], v[124:125], v[92:93], v[108:109]
	v_pk_fma_f32 v[126:127], v[126:127], v[94:95], v[110:111]
	v_pk_fma_f32 v[128:129], v[128:129], v[96:97], v[112:113]
	v_pk_fma_f32 v[130:131], v[130:131], v[98:99], v[114:115]
	v_cvt_pk_bf16_f32 v172, v116, v117
	v_cvt_pk_bf16_f32 v173, v118, v119
	v_cvt_pk_bf16_f32 v174, v120, v121
	v_cvt_pk_bf16_f32 v175, v122, v123
	v_cvt_pk_bf16_f32 v176, v124, v125
	v_cvt_pk_bf16_f32 v177, v126, v127
	v_cvt_pk_bf16_f32 v178, v128, v129
	v_cvt_pk_bf16_f32 v179, v130, v131
	global_store_dwordx4 v51, v[172:175], s[26:27]
	global_store_dwordx4 v51, v[176:179], s[26:27] offset:1024
	v_lshlrev_b32_e32 v116, 16, v8
	v_and_b32_e32 v117, 0xffff0000, v8
	v_lshlrev_b32_e32 v118, 16, v9
	v_and_b32_e32 v119, 0xffff0000, v9
	v_lshlrev_b32_e32 v120, 16, v10
	v_and_b32_e32 v121, 0xffff0000, v10
	v_lshlrev_b32_e32 v122, 16, v11
	v_and_b32_e32 v123, 0xffff0000, v11
	v_lshlrev_b32_e32 v124, 16, v12
	v_and_b32_e32 v125, 0xffff0000, v12
	v_lshlrev_b32_e32 v126, 16, v13
	v_and_b32_e32 v127, 0xffff0000, v13
	v_lshlrev_b32_e32 v128, 16, v14
	v_and_b32_e32 v129, 0xffff0000, v14
	v_lshlrev_b32_e32 v130, 16, v15
	v_and_b32_e32 v131, 0xffff0000, v15
	v_pk_mul_f32 v[116:117], v[142:143], v[116:117] op_sel_hi:[0,1]
	v_pk_mul_f32 v[118:119], v[142:143], v[118:119] op_sel_hi:[0,1]
	v_pk_mul_f32 v[120:121], v[142:143], v[120:121] op_sel_hi:[0,1]
	v_pk_mul_f32 v[122:123], v[142:143], v[122:123] op_sel_hi:[0,1]
	v_pk_mul_f32 v[124:125], v[142:143], v[124:125] op_sel_hi:[0,1]
	v_pk_mul_f32 v[126:127], v[142:143], v[126:127] op_sel_hi:[0,1]
	v_pk_mul_f32 v[128:129], v[142:143], v[128:129] op_sel_hi:[0,1]
	v_pk_mul_f32 v[130:131], v[142:143], v[130:131] op_sel_hi:[0,1]
	v_pk_mul_f32 v[116:117], v[116:117], v[32:33]
	v_pk_mul_f32 v[118:119], v[118:119], v[34:35]
	v_pk_mul_f32 v[120:121], v[120:121], v[36:37]
	v_pk_mul_f32 v[122:123], v[122:123], v[38:39]
	v_pk_mul_f32 v[124:125], v[124:125], v[40:41]
	v_pk_mul_f32 v[126:127], v[126:127], v[42:43]
	v_pk_mul_f32 v[128:129], v[128:129], v[44:45]
	v_pk_mul_f32 v[130:131], v[130:131], v[46:47]
	v_pk_fma_f32 v[116:117], v[116:117], v[84:85], v[100:101]
	v_pk_fma_f32 v[118:119], v[118:119], v[86:87], v[102:103]
	v_pk_fma_f32 v[120:121], v[120:121], v[88:89], v[104:105]
	v_pk_fma_f32 v[122:123], v[122:123], v[90:91], v[106:107]
	v_pk_fma_f32 v[124:125], v[124:125], v[92:93], v[108:109]
	v_pk_fma_f32 v[126:127], v[126:127], v[94:95], v[110:111]
	v_pk_fma_f32 v[128:129], v[128:129], v[96:97], v[112:113]
	v_pk_fma_f32 v[130:131], v[130:131], v[98:99], v[114:115]
	v_cvt_pk_bf16_f32 v164, v116, v117
	v_cvt_pk_bf16_f32 v165, v118, v119
	v_cvt_pk_bf16_f32 v166, v120, v121
	v_cvt_pk_bf16_f32 v167, v122, v123
	v_cvt_pk_bf16_f32 v168, v124, v125
	v_cvt_pk_bf16_f32 v169, v126, v127
	v_cvt_pk_bf16_f32 v170, v128, v129
	v_cvt_pk_bf16_f32 v171, v130, v131
	global_store_dwordx4 v51, v[164:167], s[26:27] offset:2048
	global_store_dwordx4 v51, v[168:171], s[26:27] offset:3072
	v_lshlrev_b32_e32 v116, 16, v16
	v_and_b32_e32 v117, 0xffff0000, v16
	v_lshlrev_b32_e32 v118, 16, v17
	v_and_b32_e32 v119, 0xffff0000, v17
	v_lshlrev_b32_e32 v120, 16, v18
	v_and_b32_e32 v121, 0xffff0000, v18
	v_lshlrev_b32_e32 v122, 16, v19
	v_and_b32_e32 v123, 0xffff0000, v19
	v_lshlrev_b32_e32 v124, 16, v20
	v_and_b32_e32 v125, 0xffff0000, v20
	v_lshlrev_b32_e32 v126, 16, v21
	v_and_b32_e32 v127, 0xffff0000, v21
	v_lshlrev_b32_e32 v128, 16, v22
	v_and_b32_e32 v129, 0xffff0000, v22
	v_lshlrev_b32_e32 v130, 16, v23
	v_and_b32_e32 v131, 0xffff0000, v23
	v_pk_mul_f32 v[116:117], v[144:145], v[116:117] op_sel_hi:[0,1]
	v_pk_mul_f32 v[118:119], v[144:145], v[118:119] op_sel_hi:[0,1]
	v_pk_mul_f32 v[120:121], v[144:145], v[120:121] op_sel_hi:[0,1]
	v_pk_mul_f32 v[122:123], v[144:145], v[122:123] op_sel_hi:[0,1]
	v_pk_mul_f32 v[124:125], v[144:145], v[124:125] op_sel_hi:[0,1]
	v_pk_mul_f32 v[126:127], v[144:145], v[126:127] op_sel_hi:[0,1]
	v_pk_mul_f32 v[128:129], v[144:145], v[128:129] op_sel_hi:[0,1]
	v_pk_mul_f32 v[130:131], v[144:145], v[130:131] op_sel_hi:[0,1]
	v_pk_mul_f32 v[116:117], v[116:117], v[32:33]
	v_pk_mul_f32 v[118:119], v[118:119], v[34:35]
	v_pk_mul_f32 v[120:121], v[120:121], v[36:37]
	v_pk_mul_f32 v[122:123], v[122:123], v[38:39]
	v_pk_mul_f32 v[124:125], v[124:125], v[40:41]
	v_pk_mul_f32 v[126:127], v[126:127], v[42:43]
	v_pk_mul_f32 v[128:129], v[128:129], v[44:45]
	v_pk_mul_f32 v[130:131], v[130:131], v[46:47]
	v_pk_fma_f32 v[116:117], v[116:117], v[84:85], v[100:101]
	v_pk_fma_f32 v[118:119], v[118:119], v[86:87], v[102:103]
	v_pk_fma_f32 v[120:121], v[120:121], v[88:89], v[104:105]
	v_pk_fma_f32 v[122:123], v[122:123], v[90:91], v[106:107]
	v_pk_fma_f32 v[124:125], v[124:125], v[92:93], v[108:109]
	v_pk_fma_f32 v[126:127], v[126:127], v[94:95], v[110:111]
	v_pk_fma_f32 v[128:129], v[128:129], v[96:97], v[112:113]
	v_pk_fma_f32 v[130:131], v[130:131], v[98:99], v[114:115]
	v_cvt_pk_bf16_f32 v172, v116, v117
	v_cvt_pk_bf16_f32 v173, v118, v119
	v_cvt_pk_bf16_f32 v174, v120, v121
	v_cvt_pk_bf16_f32 v175, v122, v123
	v_cvt_pk_bf16_f32 v176, v124, v125
	v_cvt_pk_bf16_f32 v177, v126, v127
	v_cvt_pk_bf16_f32 v178, v128, v129
	v_cvt_pk_bf16_f32 v179, v130, v131
	global_store_dwordx4 v149, v[172:175], s[26:27]
	global_store_dwordx4 v149, v[176:179], s[26:27] offset:1024
	v_lshlrev_b32_e32 v116, 16, v24
	v_and_b32_e32 v117, 0xffff0000, v24
	v_lshlrev_b32_e32 v118, 16, v25
	v_and_b32_e32 v119, 0xffff0000, v25
	v_lshlrev_b32_e32 v120, 16, v26
	v_and_b32_e32 v121, 0xffff0000, v26
	v_lshlrev_b32_e32 v122, 16, v27
	v_and_b32_e32 v123, 0xffff0000, v27
	v_lshlrev_b32_e32 v124, 16, v28
	v_and_b32_e32 v125, 0xffff0000, v28
	v_lshlrev_b32_e32 v126, 16, v29
	v_and_b32_e32 v127, 0xffff0000, v29
	v_lshlrev_b32_e32 v128, 16, v30
	v_and_b32_e32 v129, 0xffff0000, v30
	v_lshlrev_b32_e32 v130, 16, v31
	v_and_b32_e32 v131, 0xffff0000, v31
	v_pk_mul_f32 v[116:117], v[146:147], v[116:117] op_sel_hi:[0,1]
	v_pk_mul_f32 v[118:119], v[146:147], v[118:119] op_sel_hi:[0,1]
	v_pk_mul_f32 v[120:121], v[146:147], v[120:121] op_sel_hi:[0,1]
	v_pk_mul_f32 v[122:123], v[146:147], v[122:123] op_sel_hi:[0,1]
	v_pk_mul_f32 v[124:125], v[146:147], v[124:125] op_sel_hi:[0,1]
	v_pk_mul_f32 v[126:127], v[146:147], v[126:127] op_sel_hi:[0,1]
	v_pk_mul_f32 v[128:129], v[146:147], v[128:129] op_sel_hi:[0,1]
	v_pk_mul_f32 v[130:131], v[146:147], v[130:131] op_sel_hi:[0,1]
	v_pk_mul_f32 v[116:117], v[116:117], v[32:33]
	v_pk_mul_f32 v[118:119], v[118:119], v[34:35]
	v_pk_mul_f32 v[120:121], v[120:121], v[36:37]
	v_pk_mul_f32 v[122:123], v[122:123], v[38:39]
	v_pk_mul_f32 v[124:125], v[124:125], v[40:41]
	v_pk_mul_f32 v[126:127], v[126:127], v[42:43]
	v_pk_mul_f32 v[128:129], v[128:129], v[44:45]
	v_pk_mul_f32 v[130:131], v[130:131], v[46:47]
	v_pk_fma_f32 v[116:117], v[116:117], v[84:85], v[100:101]
	v_pk_fma_f32 v[118:119], v[118:119], v[86:87], v[102:103]
	v_pk_fma_f32 v[120:121], v[120:121], v[88:89], v[104:105]
	v_pk_fma_f32 v[122:123], v[122:123], v[90:91], v[106:107]
	v_pk_fma_f32 v[124:125], v[124:125], v[92:93], v[108:109]
	v_pk_fma_f32 v[126:127], v[126:127], v[94:95], v[110:111]
	v_pk_fma_f32 v[128:129], v[128:129], v[96:97], v[112:113]
	v_pk_fma_f32 v[130:131], v[130:131], v[98:99], v[114:115]
	v_cvt_pk_bf16_f32 v164, v116, v117
	v_cvt_pk_bf16_f32 v165, v118, v119
	v_cvt_pk_bf16_f32 v166, v120, v121
	v_cvt_pk_bf16_f32 v167, v122, v123
	v_cvt_pk_bf16_f32 v168, v124, v125
	v_cvt_pk_bf16_f32 v169, v126, v127
	v_cvt_pk_bf16_f32 v170, v128, v129
	v_cvt_pk_bf16_f32 v171, v130, v131
	global_store_dwordx4 v149, v[164:167], s[26:27] offset:2048
	global_store_dwordx4 v149, v[168:171], s[26:27] offset:3072
	s_add_u32 s26, s26, 0x2000
	s_addc_u32 s27, s27, 0
	s_branch .LBB0_238

.LBB0_290:
	s_or_b64 exec, exec, s[0:1]
	s_mov_b64 s[0:1], s[78:79]
	s_waitcnt lgkmcnt(0)
	s_barrier
	s_load_dwordx2 s[0:1], s[0:1], 0x100
	s_mov_b64 s[4:5], s[78:79]
	s_load_dwordx2 s[4:5], s[4:5], 0x100
	v_mov_b32_e32 v8, v224
	s_waitcnt lgkmcnt(0)
	s_add_u32 s36, s0, 0x85b4000
	s_addc_u32 s37, s1, 0
	s_mov_b64 s[0:1], s[78:79]
	s_load_dwordx2 s[18:19], s[0:1], 0x100
	s_mov_b64 s[0:1], s[78:79]
	s_load_dwordx2 s[0:1], s[0:1], 0x100
	s_add_u32 s38, s4, s60
	s_addc_u32 s39, s5, 0
	v_readlane_b32 s4, v252, 4
	v_readlane_b32 s5, v252, 5
	s_and_b64 vcc, exec, s[4:5]
	v_readfirstlane_b32 s40, v8
	s_cbranch_vccz .LBB0_292
	v_readlane_b32 s4, v252, 49
	v_readlane_b32 s5, v252, 50
	s_mov_b32 s20, s4
	s_cmp_lt_u32 s20, 0x7000000
	s_cbranch_scc0 .Lxnr_a_hi
	s_load_dwordx2 s[4:5], s[78:79], 0xf8
	s_waitcnt lgkmcnt(0)
	s_add_u32 s4, s4, 0x9000000
	s_addc_u32 s5, s5, 0
	s_branch .Lxnr_a_join
.Lxnr_a_hi:
	s_load_dwordx2 s[4:5], s[78:79], 0x100
	s_waitcnt lgkmcnt(0)
	s_sub_u32 s4, s4, 0xa4c000
	s_subb_u32 s5, s5, 0
.Lxnr_a_join:
	s_add_u32 s4, s4, s20
	s_addc_u32 s5, s5, 0
	v_readlane_b32 s20, v252, 53
	v_readlane_b32 s21, v252, 54
	s_add_u32 s30, s38, s20
	s_addc_u32 s31, s39, s21
	v_readlane_b32 s20, v252, 51
	v_readlane_b32 s21, v252, 52
	s_mov_b32 s49, s20
	v_readlane_b32 s20, v252, 47
	s_mov_b32 s50, s20
	v_readlane_b32 s21, v252, 48

.LBB0_303:
	s_ashr_i32 s25, s24, 31
	s_lshl_b64 s[26:27], s[24:25], 19
	s_mov_b32 s25, s26
	s_cmp_lt_u32 s24, 0xe0
	s_cbranch_scc0 .Lxnr_b_hi
	s_load_dwordx2 s[26:27], s[78:79], 0xf8
	s_waitcnt lgkmcnt(0)
	s_add_u32 s26, s26, 0x9000000
	s_addc_u32 s27, s27, 0
	s_branch .Lxnr_b_join
.Lxnr_b_hi:
	s_load_dwordx2 s[26:27], s[78:79], 0x100
	s_waitcnt lgkmcnt(0)
	s_sub_u32 s26, s26, 0xa4c000
	s_subb_u32 s27, s27, 0
.Lxnr_b_join:
	s_add_u32 s26, s26, s25
	s_addc_u32 s27, s27, 0
	s_ashr_i32 s23, s22, 31
	s_lshl_b64 s[28:29], s[22:23], 19
	s_add_u32 s28, s38, s28
	s_addc_u32 s29, s39, s29

.LBB0_987:
.LBB0_991:
	s_mov_b64 s[6:7], s[78:79]
	s_getreg_b32 s5, hwreg(HW_REG_XCC_ID, 0, 4)
	s_waitcnt vmcnt(0)
	s_waitcnt lgkmcnt(0)
	s_barrier
	s_mov_b64 s[0:1], exec
	v_readlane_b32 s8, v252, 0
	v_readlane_b32 s9, v252, 1
	s_and_b64 s[8:9], s[0:1], s[8:9]
	s_mov_b64 exec, s[8:9]
	s_cbranch_execz .LBB0_1043
	v_mov_b32_e32 v0, s87
	s_load_dwordx2 s[6:7], s[6:7], 0x100
	s_waitcnt vmcnt(0) expcnt(0) lgkmcnt(0)
	ds_read_b32 v2, v0
	v_mov_b32_e32 v0, s88
	ds_read_b32 v0, v0
	s_and_b32 s5, s5, 15
	s_waitcnt lgkmcnt(1)
	v_cmp_ne_u32_e32 vcc, 0, v2
	s_cbranch_vccnz .LBB0_1007
	s_add_u32 s8, s6, 0x3b314200
	s_addc_u32 s9, s7, 0
	s_add_u32 s10, s6, 0x3b314400
	s_addc_u32 s11, s7, 0
	s_add_u32 s12, s6, 0x3b314500
	s_addc_u32 s13, s7, 0
	s_add_u32 s14, s6, 0x3b314600
	s_addc_u32 s15, s7, 0
	s_add_u32 s16, s6, 0x3b314700
	s_addc_u32 s17, s7, 0
	s_add_u32 s18, s6, 0x3b314800
	s_addc_u32 s19, s7, 0
	s_add_u32 s20, s6, 0x3b314900
	s_addc_u32 s21, s7, 0
	s_add_u32 s22, s6, 0x3b314a00
	s_addc_u32 s23, s7, 0
	s_add_u32 s24, s6, 0x3b314b00
	s_addc_u32 s25, s7, 0
	s_add_u32 s26, s6, 0x3b314c00
	s_addc_u32 s27, s7, 0
	s_add_u32 s28, s6, 0x3b314d00
	s_addc_u32 s29, s7, 0
	s_add_u32 s30, s6, 0x3b314e00
	s_addc_u32 s31, s7, 0
	s_add_u32 s34, s6, 0x3b314f00
	s_addc_u32 s35, s7, 0
	s_add_u32 s36, s6, 0x3b315000
	s_addc_u32 s37, s7, 0
	s_add_u32 s38, s6, 0x3b315100
	s_addc_u32 s39, s7, 0
	s_add_u32 s40, s6, 0x3b315200
	s_addc_u32 s41, s7, 0
	s_add_u32 s42, s6, 0x3b315300
	s_addc_u32 s43, s7, 0
	s_mov_b32 s50, 1
	s_branch .LBB0_995

.LBB0_1053:
	s_andn2_b64 vcc, exec, s[30:31]
	s_cbranch_vccnz .LBB0_1055
	s_ashr_i32 s19, s18, 31
	s_lshl_b64 s[20:21], s[18:19], 19
	s_cmp_eq_u32 s80, 0
	s_cbranch_scc1 .Lxnr_c_l0
	s_mov_b32 s19, s20
	s_cmp_lt_u32 s18, 0xe0
	s_cbranch_scc0 .Lxnr_c_hi
	s_load_dwordx2 s[20:21], s[78:79], 0xf8
	s_waitcnt lgkmcnt(0)
	s_add_u32 s20, s20, 0x9000000
	s_addc_u32 s21, s21, 0
	s_branch .Lxnr_c_join
.Lxnr_c_hi:
	s_load_dwordx2 s[20:21], s[78:79], 0x100
	s_waitcnt lgkmcnt(0)
	s_sub_u32 s20, s20, 0xa4c000
	s_subb_u32 s21, s21, 0
.Lxnr_c_join:
	s_add_u32 s20, s20, s19
	s_addc_u32 s21, s21, 0
	s_branch .Lxnr_c_done
.Lxnr_c_l0:
	s_add_u32 s20, s43, s20
	s_addc_u32 s21, s44, s21
.Lxnr_c_done:
	s_lshl_b32 s17, s27, 2
	s_add_i32 s22, s16, s17
	s_ashr_i32 s23, s22, 31
	s_lshl_b64 s[22:23], s[22:23], 19
	s_add_u32 s22, s45, s22
	s_addc_u32 s23, s46, s23
	s_mov_b32 s54, 16
